# GEMM K-loop: s_setprio/waitcnt trimmed around MMA blocks; attention: per-lane LDS-DMA source offsets hoisted out of tile steps
# speedup vs baseline: 1.0076x; 1.0076x over previous
.LBB0_196:
	s_cmp_lg_u32 s22, 0
	s_mov_b32 s22, 0
	s_cbranch_scc0 .LBB0_198
	ds_read_b128 v[2:5], v161
	ds_read_b128 v[6:9], v161 offset:1024
	ds_read_b128 v[10:13], v161 offset:2048
	ds_read_b128 v[14:17], v161 offset:3072
	ds_read_b128 v[18:21], v162
	ds_read_b128 v[22:25], v162 offset:1024
	ds_read_b128 v[26:29], v162 offset:2048
	ds_read_b128 v[30:33], v162 offset:3072
	s_add_u32 s0, s4, 0x10000
	s_addc_u32 s1, s5, 0
	ds_read_b128 v[34:37], v163
	ds_read_b128 v[38:41], v163 offset:1024
	ds_read_b128 v[42:45], v163 offset:2048
	ds_read_b128 v[46:49], v163 offset:3072
	ds_read_b128 v[50:53], v163 offset:4096
	ds_read_b128 v[54:57], v163 offset:5120
	ds_read_b128 v[58:61], v163 offset:6144
	ds_read_b128 v[62:65], v163 offset:7168
	s_waitcnt vmcnt(24)
	s_waitcnt lgkmcnt(0)
	s_setprio 1
	s_barrier
	v_mfma_f32_16x16x32_bf16 v[90:93], v[2:5], v[58:61], 0
	v_mfma_f32_16x16x32_bf16 v[66:69], v[2:5], v[34:37], 0
	v_mfma_f32_16x16x32_bf16 v[70:73], v[10:13], v[34:37], 0
	v_mfma_f32_16x16x32_bf16 v[74:77], v[2:5], v[42:45], 0
	v_mfma_f32_16x16x32_bf16 v[78:81], v[10:13], v[42:45], 0
	v_mfma_f32_16x16x32_bf16 v[82:85], v[2:5], v[50:53], 0
	v_mfma_f32_16x16x32_bf16 v[86:89], v[10:13], v[50:53], 0
	v_mfma_f32_16x16x32_bf16 v[100:103], v[6:9], v[62:65], v[90:93]
	v_mfma_f32_16x16x32_bf16 v[90:93], v[10:13], v[58:61], 0
	v_mfma_f32_16x16x32_bf16 v[66:69], v[6:9], v[38:41], v[66:69]
	v_mfma_f32_16x16x32_bf16 v[70:73], v[14:17], v[38:41], v[70:73]
	v_mfma_f32_16x16x32_bf16 v[74:77], v[6:9], v[46:49], v[74:77]
	v_mfma_f32_16x16x32_bf16 v[78:81], v[14:17], v[46:49], v[78:81]
	v_mfma_f32_16x16x32_bf16 v[82:85], v[6:9], v[54:57], v[82:85]
	v_mfma_f32_16x16x32_bf16 v[86:89], v[14:17], v[54:57], v[86:89]
	v_mfma_f32_16x16x32_bf16 v[104:107], v[14:17], v[62:65], v[90:93]
	v_mfma_f32_16x16x32_bf16 v[90:93], v[18:21], v[34:37], 0
	v_mfma_f32_16x16x32_bf16 v[34:37], v[26:29], v[34:37], 0
	v_mfma_f32_16x16x32_bf16 v[116:119], v[22:25], v[38:41], v[90:93]
	v_mfma_f32_16x16x32_bf16 v[34:37], v[30:33], v[38:41], v[34:37]
	v_mfma_f32_16x16x32_bf16 v[38:41], v[18:21], v[42:45], 0
	v_mfma_f32_16x16x32_bf16 v[42:45], v[26:29], v[42:45], 0
	v_mfma_f32_16x16x32_bf16 v[38:41], v[22:25], v[46:49], v[38:41]
	v_mfma_f32_16x16x32_bf16 v[42:45], v[30:33], v[46:49], v[42:45]
	v_mfma_f32_16x16x32_bf16 v[46:49], v[18:21], v[50:53], 0
	v_mfma_f32_16x16x32_bf16 v[50:53], v[26:29], v[50:53], 0
	v_mfma_f32_16x16x32_bf16 v[46:49], v[22:25], v[54:57], v[46:49]
	v_mfma_f32_16x16x32_bf16 v[50:53], v[30:33], v[54:57], v[50:53]
	v_mfma_f32_16x16x32_bf16 v[54:57], v[18:21], v[58:61], 0
	v_mfma_f32_16x16x32_bf16 v[58:61], v[26:29], v[58:61], 0
	v_mfma_f32_16x16x32_bf16 v[54:57], v[22:25], v[62:65], v[54:57]
	v_mfma_f32_16x16x32_bf16 v[58:61], v[30:33], v[62:65], v[58:61]
	s_barrier
	s_setprio 0
	s_add_i32 s12, s60, s17
	v_lshl_add_u64 v[98:99], s[0:1], 0, v[134:135]
	s_mov_b32 m0, s12
	ds_read_b128 v[62:65], v163 offset:16384
	ds_read_b128 v[90:93], v163 offset:17408
	ds_read_b128 v[94:97], v163 offset:18432
	ds_read_b128 v[108:111], v163 offset:19456
	ds_read_b128 v[112:115], v163 offset:20480
	ds_read_b128 v[120:123], v163 offset:21504
	ds_read_b128 v[124:127], v163 offset:22528
	ds_read_b128 v[128:131], v163 offset:23552
	global_load_lds_dwordx4 v[98:99], off
	s_add_i32 m0, s12, 0x2000
	v_lshl_add_u64 v[98:99], s[0:1], 0, v[138:139]
	s_add_u32 s0, s4, 0x14000
	s_addc_u32 s1, s5, 0
	s_add_i32 s12, s61, s17
	global_load_lds_dwordx4 v[98:99], off
	v_lshl_add_u64 v[98:99], s[0:1], 0, v[134:135]
	s_mov_b32 m0, s12
	v_lshl_add_u64 v[156:157], s[8:9], 0, v[132:133]
	global_load_lds_dwordx4 v[98:99], off
	v_lshl_add_u64 v[98:99], s[0:1], 0, v[138:139]
	s_add_i32 m0, s12, 0x2000
	v_lshl_add_u64 v[144:145], s[8:9], 0, v[136:137]
	global_load_lds_dwordx4 v[98:99], off
	v_lshl_add_u64 v[98:99], v[156:157], 0, s[36:37]
	s_mov_b32 m0, s18
	s_nop 0
	global_load_lds_dwordx4 v[98:99], off
	v_lshl_add_u64 v[98:99], v[144:145], 0, s[36:37]
	s_mov_b32 m0, s19
	s_nop 0
	global_load_lds_dwordx4 v[98:99], off
	s_waitcnt vmcnt(24)
	s_waitcnt lgkmcnt(0)
	s_setprio 1
	s_barrier
	v_mfma_f32_16x16x32_bf16 v[148:151], v[2:5], v[62:65], 0
	v_mfma_f32_16x16x32_bf16 v[166:169], v[2:5], v[94:97], 0
	v_mfma_f32_16x16x32_bf16 v[174:177], v[2:5], v[112:115], 0
	v_mfma_f32_16x16x32_bf16 v[2:5], v[2:5], v[124:127], 0
	v_mfma_f32_16x16x32_bf16 v[148:151], v[6:9], v[90:93], v[148:151]
	v_mfma_f32_16x16x32_bf16 v[166:169], v[6:9], v[108:111], v[166:169]
	v_mfma_f32_16x16x32_bf16 v[174:177], v[6:9], v[120:123], v[174:177]
	v_mfma_f32_16x16x32_bf16 v[2:5], v[6:9], v[128:131], v[2:5]
	v_mfma_f32_16x16x32_bf16 v[6:9], v[10:13], v[124:127], 0
	v_mfma_f32_16x16x32_bf16 v[152:155], v[10:13], v[62:65], 0
	v_mfma_f32_16x16x32_bf16 v[170:173], v[10:13], v[94:97], 0
	v_mfma_f32_16x16x32_bf16 v[178:181], v[10:13], v[112:115], 0
	v_mfma_f32_16x16x32_bf16 v[6:9], v[14:17], v[128:131], v[6:9]
	v_mfma_f32_16x16x32_bf16 v[152:155], v[14:17], v[90:93], v[152:155]
	v_mfma_f32_16x16x32_bf16 v[170:173], v[14:17], v[108:111], v[170:173]
	v_mfma_f32_16x16x32_bf16 v[178:181], v[14:17], v[120:123], v[178:181]
	v_mfma_f32_16x16x32_bf16 v[10:13], v[18:21], v[62:65], 0
	v_mfma_f32_16x16x32_bf16 v[182:185], v[22:25], v[90:93], v[10:13]
	v_mfma_f32_16x16x32_bf16 v[10:13], v[26:29], v[62:65], 0
	v_mfma_f32_16x16x32_bf16 v[186:189], v[30:33], v[90:93], v[10:13]
	v_mfma_f32_16x16x32_bf16 v[10:13], v[18:21], v[94:97], 0
	v_mfma_f32_16x16x32_bf16 v[190:193], v[22:25], v[108:111], v[10:13]
	v_mfma_f32_16x16x32_bf16 v[10:13], v[26:29], v[94:97], 0
	v_mfma_f32_16x16x32_bf16 v[194:197], v[30:33], v[108:111], v[10:13]
	v_mfma_f32_16x16x32_bf16 v[10:13], v[18:21], v[112:115], 0
	v_mfma_f32_16x16x32_bf16 v[198:201], v[22:25], v[120:123], v[10:13]
	v_mfma_f32_16x16x32_bf16 v[10:13], v[26:29], v[112:115], 0
	v_mfma_f32_16x16x32_bf16 v[202:205], v[30:33], v[120:123], v[10:13]
	v_mfma_f32_16x16x32_bf16 v[10:13], v[18:21], v[124:127], 0
	v_mfma_f32_16x16x32_bf16 v[206:209], v[22:25], v[128:131], v[10:13]
	v_mfma_f32_16x16x32_bf16 v[10:13], v[26:29], v[124:127], 0
	v_mfma_f32_16x16x32_bf16 v[210:213], v[30:33], v[128:131], v[10:13]
	s_barrier
	s_setprio 0
	s_add_i32 s12, 0, 0x18000
	v_add_u32_e32 v1, s12, v160
	s_add_i32 s13, 0, 0x1c000
	s_nop 1
	ds_read_b128 v[10:13], v1
	ds_read_b128 v[14:17], v1 offset:1024
	ds_read_b128 v[20:23], v1 offset:2048
	ds_read_b128 v[24:27], v1 offset:3072
	v_add_u32_e32 v1, s13, v160
	ds_read_b128 v[214:217], v1
	ds_read_b128 v[218:221], v1 offset:1024
	ds_read_b128 v[222:225], v1 offset:2048
	ds_read_b128 v[226:229], v1 offset:3072
	s_add_u32 s0, s8, 0x100100
	s_addc_u32 s1, s9, 0
	s_mov_b32 m0, s20
	v_lshl_add_u64 v[18:19], s[0:1], 0, v[132:133]
	ds_read_b128 v[28:31], v163 offset:32768
	ds_read_b128 v[62:65], v163 offset:33792
	ds_read_b128 v[230:233], v163 offset:34816
	ds_read_b128 v[234:237], v163 offset:35840
	ds_read_b128 v[238:241], v163 offset:36864
	ds_read_b128 v[242:245], v163 offset:37888
	ds_read_b128 v[246:249], v163 offset:38912
	ds_read_b128 v[250:253], v163 offset:39936
	global_load_lds_dwordx4 v[18:19], off
	v_lshl_add_u64 v[18:19], s[0:1], 0, v[136:137]
	s_mov_b32 m0, s21
	s_nop 0
	global_load_lds_dwordx4 v[18:19], off
	s_waitcnt vmcnt(24)
	s_waitcnt lgkmcnt(0)
	s_setprio 1
	s_barrier
	v_mfma_f32_16x16x32_bf16 v[66:69], v[10:13], v[28:31], v[66:69]
	v_mfma_f32_16x16x32_bf16 v[128:131], v[14:17], v[62:65], v[66:69]
	v_mfma_f32_16x16x32_bf16 v[66:69], v[20:23], v[28:31], v[70:73]
	v_mfma_f32_16x16x32_bf16 v[124:127], v[24:27], v[62:65], v[66:69]
	v_mfma_f32_16x16x32_bf16 v[66:69], v[10:13], v[230:233], v[74:77]
	v_mfma_f32_16x16x32_bf16 v[112:115], v[14:17], v[234:237], v[66:69]
	v_mfma_f32_16x16x32_bf16 v[66:69], v[20:23], v[230:233], v[78:81]
	v_mfma_f32_16x16x32_bf16 v[108:111], v[24:27], v[234:237], v[66:69]
	v_mfma_f32_16x16x32_bf16 v[66:69], v[10:13], v[238:241], v[82:85]
	v_mfma_f32_16x16x32_bf16 v[96:99], v[14:17], v[242:245], v[66:69]
	v_mfma_f32_16x16x32_bf16 v[66:69], v[20:23], v[238:241], v[86:89]
	v_mfma_f32_16x16x32_bf16 v[92:95], v[24:27], v[242:245], v[66:69]
	v_mfma_f32_16x16x32_bf16 v[66:69], v[10:13], v[246:249], v[100:103]
	v_mfma_f32_16x16x32_bf16 v[80:83], v[14:17], v[250:253], v[66:69]
	v_mfma_f32_16x16x32_bf16 v[66:69], v[20:23], v[246:249], v[104:107]
	v_mfma_f32_16x16x32_bf16 v[76:79], v[24:27], v[250:253], v[66:69]
	v_mfma_f32_16x16x32_bf16 v[66:69], v[214:217], v[28:31], v[116:119]
	v_mfma_f32_16x16x32_bf16 v[28:31], v[222:225], v[28:31], v[34:37]
	v_mfma_f32_16x16x32_bf16 v[116:119], v[226:229], v[62:65], v[28:31]
	v_mfma_f32_16x16x32_bf16 v[28:31], v[214:217], v[230:233], v[38:41]
	v_mfma_f32_16x16x32_bf16 v[104:107], v[218:221], v[234:237], v[28:31]
	v_mfma_f32_16x16x32_bf16 v[28:31], v[222:225], v[230:233], v[42:45]
	v_mfma_f32_16x16x32_bf16 v[100:103], v[226:229], v[234:237], v[28:31]
	v_mfma_f32_16x16x32_bf16 v[28:31], v[214:217], v[238:241], v[46:49]
	v_mfma_f32_16x16x32_bf16 v[88:91], v[218:221], v[242:245], v[28:31]
	v_mfma_f32_16x16x32_bf16 v[28:31], v[222:225], v[238:241], v[50:53]
	v_mfma_f32_16x16x32_bf16 v[84:87], v[226:229], v[242:245], v[28:31]
	v_mfma_f32_16x16x32_bf16 v[28:31], v[214:217], v[246:249], v[54:57]
	v_mfma_f32_16x16x32_bf16 v[72:75], v[218:221], v[250:253], v[28:31]
	v_mfma_f32_16x16x32_bf16 v[28:31], v[222:225], v[246:249], v[58:61]
	v_mfma_f32_16x16x32_bf16 v[120:123], v[218:221], v[62:65], v[66:69]
	v_mfma_f32_16x16x32_bf16 v[68:71], v[226:229], v[250:253], v[28:31]
	s_barrier
	s_setprio 0
	s_add_u32 s0, s4, 0x18000
	s_addc_u32 s1, s5, 0
	s_add_i32 s12, s12, s17
	v_lshl_add_u64 v[18:19], s[0:1], 0, v[134:135]
	s_mov_b32 m0, s12
	ds_read_b128 v[36:39], v163 offset:49152
	ds_read_b128 v[40:43], v163 offset:50176
	ds_read_b128 v[230:233], v163 offset:51200
	ds_read_b128 v[234:237], v163 offset:52224
	ds_read_b128 v[238:241], v163 offset:53248
	ds_read_b128 v[242:245], v163 offset:54272
	ds_read_b128 v[246:249], v163 offset:55296
	ds_read_b128 v[250:253], v163 offset:56320
	global_load_lds_dwordx4 v[18:19], off
	s_add_i32 m0, s12, 0x2000
	v_lshl_add_u64 v[18:19], s[0:1], 0, v[138:139]
	s_add_u32 s0, s4, 0x1c000
	s_addc_u32 s1, s5, 0
	s_add_i32 s12, s13, s17
	global_load_lds_dwordx4 v[18:19], off
	v_lshl_add_u64 v[18:19], s[0:1], 0, v[134:135]
	s_mov_b32 m0, s12
	s_nop 0
	global_load_lds_dwordx4 v[18:19], off
	v_lshl_add_u64 v[18:19], s[0:1], 0, v[138:139]
	s_add_i32 m0, s12, 0x2000
	s_nop 0
	global_load_lds_dwordx4 v[18:19], off
	v_lshl_add_u64 v[18:19], v[156:157], 0, s[38:39]
	s_mov_b32 m0, s51
	s_nop 0
	global_load_lds_dwordx4 v[18:19], off
	v_lshl_add_u64 v[18:19], v[144:145], 0, s[38:39]
	s_mov_b32 m0, s56
	s_nop 0
	global_load_lds_dwordx4 v[18:19], off
	s_waitcnt vmcnt(8)
	s_waitcnt lgkmcnt(0)
	s_setprio 1
	s_barrier
	v_mfma_f32_16x16x32_bf16 v[28:31], v[10:13], v[36:39], v[148:151]
	v_mfma_f32_16x16x32_bf16 v[64:67], v[14:17], v[40:43], v[28:31]
	v_mfma_f32_16x16x32_bf16 v[28:31], v[20:23], v[36:39], v[152:155]
	v_mfma_f32_16x16x32_bf16 v[60:63], v[24:27], v[40:43], v[28:31]
	v_mfma_f32_16x16x32_bf16 v[28:31], v[10:13], v[230:233], v[166:169]
	v_mfma_f32_16x16x32_bf16 v[48:51], v[14:17], v[234:237], v[28:31]
	v_mfma_f32_16x16x32_bf16 v[28:31], v[20:23], v[230:233], v[170:173]
	v_mfma_f32_16x16x32_bf16 v[44:47], v[24:27], v[234:237], v[28:31]
	v_mfma_f32_16x16x32_bf16 v[28:31], v[10:13], v[238:241], v[174:177]
	v_mfma_f32_16x16x32_bf16 v[2:5], v[10:13], v[246:249], v[2:5]
	v_mfma_f32_16x16x32_bf16 v[32:35], v[14:17], v[242:245], v[28:31]
	v_mfma_f32_16x16x32_bf16 v[28:31], v[20:23], v[238:241], v[178:181]
	v_mfma_f32_16x16x32_bf16 v[16:19], v[14:17], v[250:253], v[2:5]
	v_mfma_f32_16x16x32_bf16 v[2:5], v[20:23], v[246:249], v[6:9]
	v_mfma_f32_16x16x32_bf16 v[28:31], v[24:27], v[242:245], v[28:31]
	v_mfma_f32_16x16x32_bf16 v[12:15], v[24:27], v[250:253], v[2:5]
	v_mfma_f32_16x16x32_bf16 v[2:5], v[214:217], v[36:39], v[182:185]
	v_mfma_f32_16x16x32_bf16 v[56:59], v[218:221], v[40:43], v[2:5]
	v_mfma_f32_16x16x32_bf16 v[2:5], v[222:225], v[36:39], v[186:189]
	v_mfma_f32_16x16x32_bf16 v[52:55], v[226:229], v[40:43], v[2:5]
	v_mfma_f32_16x16x32_bf16 v[2:5], v[214:217], v[230:233], v[190:193]
	v_mfma_f32_16x16x32_bf16 v[40:43], v[218:221], v[234:237], v[2:5]
	v_mfma_f32_16x16x32_bf16 v[2:5], v[222:225], v[230:233], v[194:197]
	v_mfma_f32_16x16x32_bf16 v[36:39], v[226:229], v[234:237], v[2:5]
	v_mfma_f32_16x16x32_bf16 v[2:5], v[214:217], v[238:241], v[198:201]
	v_mfma_f32_16x16x32_bf16 v[24:27], v[218:221], v[242:245], v[2:5]
	v_mfma_f32_16x16x32_bf16 v[2:5], v[222:225], v[238:241], v[202:205]
	v_mfma_f32_16x16x32_bf16 v[20:23], v[226:229], v[242:245], v[2:5]
	v_mfma_f32_16x16x32_bf16 v[2:5], v[214:217], v[246:249], v[206:209]
	v_mfma_f32_16x16x32_bf16 v[8:11], v[218:221], v[250:253], v[2:5]
	v_mfma_f32_16x16x32_bf16 v[2:5], v[222:225], v[246:249], v[210:213]
	v_mfma_f32_16x16x32_bf16 v[4:7], v[226:229], v[250:253], v[2:5]
	s_barrier
	s_setprio 0
	s_mov_b32 s22, 2
	s_branch .LBB0_199

.LBB0_200:
	ds_read_b128 v[150:153], v161
	ds_read_b128 v[154:157], v161 offset:1024
	ds_read_b128 v[166:169], v161 offset:2048
	ds_read_b128 v[170:173], v161 offset:3072
	ds_read_b128 v[174:177], v162
	ds_read_b128 v[178:181], v162 offset:1024
	ds_read_b128 v[182:185], v162 offset:2048
	ds_read_b128 v[186:189], v162 offset:3072
	s_add_u32 s8, s55, s26
	s_addc_u32 s9, s63, 0
	s_cmp_eq_u32 s26, s4
	s_cselect_b32 s23, s0, s9
	s_cselect_b32 s22, s1, s8
	s_cselect_b32 s9, s41, s54
	s_cselect_b32 s8, s43, s53
	s_add_i32 s65, s18, 0xc000
	v_lshl_add_u64 v[144:145], v[2:3], 0, s[26:27]
	s_mov_b32 m0, s65
	s_add_i32 s64, s18, 0xe000
	ds_read_b128 v[190:193], v163
	ds_read_b128 v[194:197], v163 offset:1024
	ds_read_b128 v[198:201], v163 offset:2048
	ds_read_b128 v[202:205], v163 offset:3072
	ds_read_b128 v[206:209], v163 offset:4096
	ds_read_b128 v[210:213], v163 offset:5120
	ds_read_b128 v[214:217], v163 offset:6144
	ds_read_b128 v[218:221], v163 offset:7168
	global_load_lds_dwordx4 v[144:145], off
	v_lshl_add_u64 v[144:145], v[148:149], 0, s[26:27]
	s_mov_b32 m0, s64
	s_nop 0
	global_load_lds_dwordx4 v[144:145], off
	s_waitcnt vmcnt(8)
	s_waitcnt lgkmcnt(0)
	s_setprio 1
	s_barrier
	v_mfma_f32_16x16x32_bf16 v[128:131], v[150:153], v[190:193], v[128:131]
	v_mfma_f32_16x16x32_bf16 v[124:127], v[166:169], v[190:193], v[124:127]
	v_mfma_f32_16x16x32_bf16 v[112:115], v[150:153], v[198:201], v[112:115]
	v_mfma_f32_16x16x32_bf16 v[108:111], v[166:169], v[198:201], v[108:111]
	v_mfma_f32_16x16x32_bf16 v[96:99], v[150:153], v[206:209], v[96:99]
	v_mfma_f32_16x16x32_bf16 v[92:95], v[166:169], v[206:209], v[92:95]
	v_mfma_f32_16x16x32_bf16 v[80:83], v[150:153], v[214:217], v[80:83]
	v_mfma_f32_16x16x32_bf16 v[76:79], v[166:169], v[214:217], v[76:79]
	v_mfma_f32_16x16x32_bf16 v[128:131], v[154:157], v[194:197], v[128:131]
	v_mfma_f32_16x16x32_bf16 v[124:127], v[170:173], v[194:197], v[124:127]
	v_mfma_f32_16x16x32_bf16 v[112:115], v[154:157], v[202:205], v[112:115]
	v_mfma_f32_16x16x32_bf16 v[108:111], v[170:173], v[202:205], v[108:111]
	v_mfma_f32_16x16x32_bf16 v[96:99], v[154:157], v[210:213], v[96:99]
	v_mfma_f32_16x16x32_bf16 v[92:95], v[170:173], v[210:213], v[92:95]
	v_mfma_f32_16x16x32_bf16 v[80:83], v[154:157], v[218:221], v[80:83]
	v_mfma_f32_16x16x32_bf16 v[76:79], v[170:173], v[218:221], v[76:79]
	v_mfma_f32_16x16x32_bf16 v[120:123], v[174:177], v[190:193], v[120:123]
	v_mfma_f32_16x16x32_bf16 v[116:119], v[182:185], v[190:193], v[116:119]
	v_mfma_f32_16x16x32_bf16 v[104:107], v[174:177], v[198:201], v[104:107]
	v_mfma_f32_16x16x32_bf16 v[100:103], v[182:185], v[198:201], v[100:103]
	v_mfma_f32_16x16x32_bf16 v[88:91], v[174:177], v[206:209], v[88:91]
	v_mfma_f32_16x16x32_bf16 v[84:87], v[182:185], v[206:209], v[84:87]
	v_mfma_f32_16x16x32_bf16 v[72:75], v[174:177], v[214:217], v[72:75]
	v_mfma_f32_16x16x32_bf16 v[68:71], v[182:185], v[214:217], v[68:71]
	v_mfma_f32_16x16x32_bf16 v[120:123], v[178:181], v[194:197], v[120:123]
	v_mfma_f32_16x16x32_bf16 v[116:119], v[186:189], v[194:197], v[116:119]
	v_mfma_f32_16x16x32_bf16 v[104:107], v[178:181], v[202:205], v[104:107]
	v_mfma_f32_16x16x32_bf16 v[100:103], v[186:189], v[202:205], v[100:103]
	v_mfma_f32_16x16x32_bf16 v[88:91], v[178:181], v[210:213], v[88:91]
	v_mfma_f32_16x16x32_bf16 v[84:87], v[186:189], v[210:213], v[84:87]
	v_mfma_f32_16x16x32_bf16 v[72:75], v[178:181], v[218:221], v[72:75]
	v_mfma_f32_16x16x32_bf16 v[68:71], v[186:189], v[218:221], v[68:71]
	s_barrier
	s_setprio 0
	s_add_i32 s12, s60, s17
	v_lshl_add_u64 v[144:145], s[8:9], 0, v[134:135]
	s_mov_b32 m0, s12
	ds_read_b128 v[190:193], v163 offset:16384
	ds_read_b128 v[194:197], v163 offset:17408
	ds_read_b128 v[198:201], v163 offset:18432
	ds_read_b128 v[202:205], v163 offset:19456
	ds_read_b128 v[206:209], v163 offset:20480
	ds_read_b128 v[210:213], v163 offset:21504
	ds_read_b128 v[214:217], v163 offset:22528
	ds_read_b128 v[218:221], v163 offset:23552
	global_load_lds_dwordx4 v[144:145], off
	s_add_i32 m0, s12, 0x2000
	s_add_u32 s12, s8, 0x4000
	v_lshl_add_u64 v[144:145], s[8:9], 0, v[138:139]
	s_addc_u32 s13, s9, 0
	s_add_i32 s14, s61, s17
	global_load_lds_dwordx4 v[144:145], off
	v_lshl_add_u64 v[144:145], s[12:13], 0, v[134:135]
	s_mov_b32 m0, s14
	v_lshl_add_u64 v[222:223], s[22:23], 0, v[136:137]
	global_load_lds_dwordx4 v[144:145], off
	v_lshl_add_u64 v[144:145], s[12:13], 0, v[138:139]
	s_add_i32 m0, s14, 0x2000
	s_nop 0
	global_load_lds_dwordx4 v[144:145], off
	v_lshl_add_u64 v[144:145], s[22:23], 0, v[132:133]
	s_mov_b32 m0, s18
	s_nop 0
	global_load_lds_dwordx4 v[144:145], off
	s_mov_b32 m0, s19
	s_nop 0
	global_load_lds_dwordx4 v[222:223], off
	s_waitcnt vmcnt(8)
	s_waitcnt lgkmcnt(0)
	s_setprio 1
	s_barrier
	v_mfma_f32_16x16x32_bf16 v[64:67], v[150:153], v[190:193], v[64:67]
	v_mfma_f32_16x16x32_bf16 v[60:63], v[166:169], v[190:193], v[60:63]
	v_mfma_f32_16x16x32_bf16 v[48:51], v[150:153], v[198:201], v[48:51]
	v_mfma_f32_16x16x32_bf16 v[44:47], v[166:169], v[198:201], v[44:47]
	v_mfma_f32_16x16x32_bf16 v[32:35], v[150:153], v[206:209], v[32:35]
	v_mfma_f32_16x16x32_bf16 v[28:31], v[166:169], v[206:209], v[28:31]
	v_mfma_f32_16x16x32_bf16 v[16:19], v[150:153], v[214:217], v[16:19]
	v_mfma_f32_16x16x32_bf16 v[12:15], v[166:169], v[214:217], v[12:15]
	v_mfma_f32_16x16x32_bf16 v[64:67], v[154:157], v[194:197], v[64:67]
	v_mfma_f32_16x16x32_bf16 v[60:63], v[170:173], v[194:197], v[60:63]
	v_mfma_f32_16x16x32_bf16 v[48:51], v[154:157], v[202:205], v[48:51]
	v_mfma_f32_16x16x32_bf16 v[44:47], v[170:173], v[202:205], v[44:47]
	v_mfma_f32_16x16x32_bf16 v[32:35], v[154:157], v[210:213], v[32:35]
	v_mfma_f32_16x16x32_bf16 v[28:31], v[170:173], v[210:213], v[28:31]
	v_mfma_f32_16x16x32_bf16 v[16:19], v[154:157], v[218:221], v[16:19]
	v_mfma_f32_16x16x32_bf16 v[12:15], v[170:173], v[218:221], v[12:15]
	v_mfma_f32_16x16x32_bf16 v[56:59], v[174:177], v[190:193], v[56:59]
	v_mfma_f32_16x16x32_bf16 v[52:55], v[182:185], v[190:193], v[52:55]
	v_mfma_f32_16x16x32_bf16 v[40:43], v[174:177], v[198:201], v[40:43]
	v_mfma_f32_16x16x32_bf16 v[36:39], v[182:185], v[198:201], v[36:39]
	v_mfma_f32_16x16x32_bf16 v[24:27], v[174:177], v[206:209], v[24:27]
	v_mfma_f32_16x16x32_bf16 v[20:23], v[182:185], v[206:209], v[20:23]
	v_mfma_f32_16x16x32_bf16 v[8:11], v[174:177], v[214:217], v[8:11]
	v_mfma_f32_16x16x32_bf16 v[4:7], v[182:185], v[214:217], v[4:7]
	v_mfma_f32_16x16x32_bf16 v[56:59], v[178:181], v[194:197], v[56:59]
	v_mfma_f32_16x16x32_bf16 v[52:55], v[186:189], v[194:197], v[52:55]
	v_mfma_f32_16x16x32_bf16 v[40:43], v[178:181], v[202:205], v[40:43]
	v_mfma_f32_16x16x32_bf16 v[36:39], v[186:189], v[202:205], v[36:39]
	v_mfma_f32_16x16x32_bf16 v[24:27], v[178:181], v[210:213], v[24:27]
	v_mfma_f32_16x16x32_bf16 v[20:23], v[186:189], v[210:213], v[20:23]
	v_mfma_f32_16x16x32_bf16 v[8:11], v[178:181], v[218:221], v[8:11]
	v_mfma_f32_16x16x32_bf16 v[4:7], v[186:189], v[218:221], v[4:7]
	s_barrier
	s_setprio 0
	s_add_i32 s14, 0, 0x18000
	v_add_u32_e32 v1, s14, v160
	s_add_i32 s66, 0, 0x1c000
	ds_read_b128 v[150:153], v1
	ds_read_b128 v[154:157], v1 offset:1024
	ds_read_b128 v[166:169], v1 offset:2048
	ds_read_b128 v[170:173], v1 offset:3072
	v_add_u32_e32 v1, s66, v160
	ds_read_b128 v[174:177], v1
	ds_read_b128 v[178:181], v1 offset:1024
	ds_read_b128 v[182:185], v1 offset:2048
	ds_read_b128 v[186:189], v1 offset:3072
	s_add_u32 s12, s22, 0x100000
	s_addc_u32 s13, s23, 0
	s_mov_b32 m0, s20
	v_lshl_add_u64 v[224:225], s[12:13], 0, v[132:133]
	ds_read_b128 v[190:193], v163 offset:32768
	ds_read_b128 v[194:197], v163 offset:33792
	ds_read_b128 v[198:201], v163 offset:34816
	ds_read_b128 v[202:205], v163 offset:35840
	ds_read_b128 v[206:209], v163 offset:36864
	ds_read_b128 v[210:213], v163 offset:37888
	ds_read_b128 v[214:217], v163 offset:38912
	ds_read_b128 v[218:221], v163 offset:39936
	global_load_lds_dwordx4 v[224:225], off
	v_lshl_add_u64 v[224:225], s[12:13], 0, v[136:137]
	s_mov_b32 m0, s21
	s_nop 0
	global_load_lds_dwordx4 v[224:225], off
	s_waitcnt vmcnt(8)
	s_waitcnt lgkmcnt(0)
	s_setprio 1
	s_barrier
	v_mfma_f32_16x16x32_bf16 v[128:131], v[150:153], v[190:193], v[128:131]
	v_mfma_f32_16x16x32_bf16 v[124:127], v[166:169], v[190:193], v[124:127]
	v_mfma_f32_16x16x32_bf16 v[112:115], v[150:153], v[198:201], v[112:115]
	v_mfma_f32_16x16x32_bf16 v[108:111], v[166:169], v[198:201], v[108:111]
	v_mfma_f32_16x16x32_bf16 v[96:99], v[150:153], v[206:209], v[96:99]
	v_mfma_f32_16x16x32_bf16 v[92:95], v[166:169], v[206:209], v[92:95]
	v_mfma_f32_16x16x32_bf16 v[80:83], v[150:153], v[214:217], v[80:83]
	v_mfma_f32_16x16x32_bf16 v[76:79], v[166:169], v[214:217], v[76:79]
	v_mfma_f32_16x16x32_bf16 v[128:131], v[154:157], v[194:197], v[128:131]
	v_mfma_f32_16x16x32_bf16 v[124:127], v[170:173], v[194:197], v[124:127]
	v_mfma_f32_16x16x32_bf16 v[112:115], v[154:157], v[202:205], v[112:115]
	v_mfma_f32_16x16x32_bf16 v[108:111], v[170:173], v[202:205], v[108:111]
	v_mfma_f32_16x16x32_bf16 v[96:99], v[154:157], v[210:213], v[96:99]
	v_mfma_f32_16x16x32_bf16 v[92:95], v[170:173], v[210:213], v[92:95]
	v_mfma_f32_16x16x32_bf16 v[80:83], v[154:157], v[218:221], v[80:83]
	v_mfma_f32_16x16x32_bf16 v[76:79], v[170:173], v[218:221], v[76:79]
	v_mfma_f32_16x16x32_bf16 v[120:123], v[174:177], v[190:193], v[120:123]
	v_mfma_f32_16x16x32_bf16 v[116:119], v[182:185], v[190:193], v[116:119]
	v_mfma_f32_16x16x32_bf16 v[104:107], v[174:177], v[198:201], v[104:107]
	v_mfma_f32_16x16x32_bf16 v[100:103], v[182:185], v[198:201], v[100:103]
	v_mfma_f32_16x16x32_bf16 v[88:91], v[174:177], v[206:209], v[88:91]
	v_mfma_f32_16x16x32_bf16 v[84:87], v[182:185], v[206:209], v[84:87]
	v_mfma_f32_16x16x32_bf16 v[72:75], v[174:177], v[214:217], v[72:75]
	v_mfma_f32_16x16x32_bf16 v[68:71], v[182:185], v[214:217], v[68:71]
	v_mfma_f32_16x16x32_bf16 v[120:123], v[178:181], v[194:197], v[120:123]
	v_mfma_f32_16x16x32_bf16 v[116:119], v[186:189], v[194:197], v[116:119]
	v_mfma_f32_16x16x32_bf16 v[104:107], v[178:181], v[202:205], v[104:107]
	v_mfma_f32_16x16x32_bf16 v[100:103], v[186:189], v[202:205], v[100:103]
	v_mfma_f32_16x16x32_bf16 v[88:91], v[178:181], v[210:213], v[88:91]
	v_mfma_f32_16x16x32_bf16 v[84:87], v[186:189], v[210:213], v[84:87]
	v_mfma_f32_16x16x32_bf16 v[72:75], v[178:181], v[218:221], v[72:75]
	v_mfma_f32_16x16x32_bf16 v[68:71], v[186:189], v[218:221], v[68:71]
	s_barrier
	s_setprio 0
	s_add_u32 s12, s8, 0x8000
	s_addc_u32 s13, s9, 0
	s_add_i32 s14, s14, s17
	v_lshl_add_u64 v[224:225], s[12:13], 0, v[134:135]
	s_mov_b32 m0, s14
	ds_read_b128 v[190:193], v163 offset:49152
	ds_read_b128 v[194:197], v163 offset:50176
	ds_read_b128 v[198:201], v163 offset:51200
	ds_read_b128 v[202:205], v163 offset:52224
	ds_read_b128 v[206:209], v163 offset:53248
	ds_read_b128 v[210:213], v163 offset:54272
	ds_read_b128 v[214:217], v163 offset:55296
	ds_read_b128 v[218:221], v163 offset:56320
	global_load_lds_dwordx4 v[224:225], off
	s_add_i32 m0, s14, 0x2000
	s_add_u32 s8, s8, 0xc000
	v_lshl_add_u64 v[224:225], s[12:13], 0, v[138:139]
	s_addc_u32 s9, s9, 0
	s_add_i32 s12, s66, s17
	global_load_lds_dwordx4 v[224:225], off
	v_lshl_add_u64 v[224:225], s[8:9], 0, v[134:135]
	s_mov_b32 m0, s12
	v_lshl_add_u64 v[144:145], v[144:145], 0, s[30:31]
	global_load_lds_dwordx4 v[224:225], off
	v_lshl_add_u64 v[224:225], s[8:9], 0, v[138:139]
	s_add_i32 m0, s12, 0x2000
	s_nop 0
	global_load_lds_dwordx4 v[224:225], off
	s_mov_b32 m0, s51
	s_nop 0
	global_load_lds_dwordx4 v[144:145], off
	v_lshl_add_u64 v[144:145], v[222:223], 0, s[30:31]
	s_mov_b32 m0, s56
	s_nop 0
	global_load_lds_dwordx4 v[144:145], off
	s_waitcnt vmcnt(8)
	s_waitcnt lgkmcnt(0)
	s_setprio 1
	s_barrier
	v_mfma_f32_16x16x32_bf16 v[64:67], v[150:153], v[190:193], v[64:67]
	v_mfma_f32_16x16x32_bf16 v[60:63], v[166:169], v[190:193], v[60:63]
	v_mfma_f32_16x16x32_bf16 v[48:51], v[150:153], v[198:201], v[48:51]
	v_mfma_f32_16x16x32_bf16 v[44:47], v[166:169], v[198:201], v[44:47]
	v_mfma_f32_16x16x32_bf16 v[32:35], v[150:153], v[206:209], v[32:35]
	v_mfma_f32_16x16x32_bf16 v[28:31], v[166:169], v[206:209], v[28:31]
	v_mfma_f32_16x16x32_bf16 v[16:19], v[150:153], v[214:217], v[16:19]
	v_mfma_f32_16x16x32_bf16 v[12:15], v[166:169], v[214:217], v[12:15]
	v_mfma_f32_16x16x32_bf16 v[64:67], v[154:157], v[194:197], v[64:67]
	v_mfma_f32_16x16x32_bf16 v[60:63], v[170:173], v[194:197], v[60:63]
	v_mfma_f32_16x16x32_bf16 v[48:51], v[154:157], v[202:205], v[48:51]
	v_mfma_f32_16x16x32_bf16 v[44:47], v[170:173], v[202:205], v[44:47]
	v_mfma_f32_16x16x32_bf16 v[32:35], v[154:157], v[210:213], v[32:35]
	v_mfma_f32_16x16x32_bf16 v[28:31], v[170:173], v[210:213], v[28:31]
	v_mfma_f32_16x16x32_bf16 v[16:19], v[154:157], v[218:221], v[16:19]
	v_mfma_f32_16x16x32_bf16 v[12:15], v[170:173], v[218:221], v[12:15]
	v_mfma_f32_16x16x32_bf16 v[56:59], v[174:177], v[190:193], v[56:59]
	v_mfma_f32_16x16x32_bf16 v[52:55], v[182:185], v[190:193], v[52:55]
	v_mfma_f32_16x16x32_bf16 v[40:43], v[174:177], v[198:201], v[40:43]
	v_mfma_f32_16x16x32_bf16 v[36:39], v[182:185], v[198:201], v[36:39]
	v_mfma_f32_16x16x32_bf16 v[24:27], v[174:177], v[206:209], v[24:27]
	v_mfma_f32_16x16x32_bf16 v[20:23], v[182:185], v[206:209], v[20:23]
	v_mfma_f32_16x16x32_bf16 v[8:11], v[174:177], v[214:217], v[8:11]
	v_mfma_f32_16x16x32_bf16 v[4:7], v[182:185], v[214:217], v[4:7]
	v_mfma_f32_16x16x32_bf16 v[56:59], v[178:181], v[194:197], v[56:59]
	v_mfma_f32_16x16x32_bf16 v[52:55], v[186:189], v[194:197], v[52:55]
	v_mfma_f32_16x16x32_bf16 v[40:43], v[178:181], v[202:205], v[40:43]
	v_mfma_f32_16x16x32_bf16 v[36:39], v[186:189], v[202:205], v[36:39]
	v_mfma_f32_16x16x32_bf16 v[24:27], v[178:181], v[210:213], v[24:27]
	v_mfma_f32_16x16x32_bf16 v[20:23], v[186:189], v[210:213], v[20:23]
	v_mfma_f32_16x16x32_bf16 v[8:11], v[178:181], v[218:221], v[8:11]
	v_mfma_f32_16x16x32_bf16 v[4:7], v[186:189], v[218:221], v[4:7]
	s_barrier
	s_setprio 0
	s_add_i32 s52, s52, 2
	s_add_u32 s53, s53, 0x10000
	s_addc_u32 s54, s54, 0
	s_add_u32 s55, s55, 0x100
	s_addc_u32 s63, s63, 0
	s_add_u32 s4, s4, 0xffffff00
	s_addc_u32 s5, s5, -1
	v_lshl_add_u64 v[2:3], v[2:3], 0, s[36:37]
	s_cmp_gt_u32 s52, 61
	v_lshl_add_u64 v[148:149], v[148:149], 0, s[36:37]
	s_cbranch_scc0 .LBB0_200
	s_and_b64 vcc, exec, s[34:35]
	s_cbranch_vccz .LBB0_203
	s_barrier

.LBB0_506:
	s_cmp_eq_u32 s22, 0
	s_mov_b32 s22, 0
	s_cbranch_scc1 .LBB0_508
	ds_read_b128 v[2:5], v153
	ds_read_b128 v[6:9], v153 offset:1024
	ds_read_b128 v[10:13], v153 offset:2048
	ds_read_b128 v[14:17], v153 offset:3072
	ds_read_b128 v[18:21], v154
	ds_read_b128 v[22:25], v154 offset:1024
	ds_read_b128 v[26:29], v154 offset:2048
	ds_read_b128 v[30:33], v154 offset:3072
	s_add_u32 s0, s8, 0x10000
	s_addc_u32 s1, s9, 0
	ds_read_b128 v[34:37], v155
	ds_read_b128 v[38:41], v155 offset:1024
	ds_read_b128 v[42:45], v155 offset:2048
	ds_read_b128 v[46:49], v155 offset:3072
	ds_read_b128 v[50:53], v155 offset:4096
	ds_read_b128 v[54:57], v155 offset:5120
	ds_read_b128 v[58:61], v155 offset:6144
	ds_read_b128 v[62:65], v155 offset:7168
	s_waitcnt vmcnt(24)
	s_waitcnt lgkmcnt(0)
	s_setprio 1
	s_barrier
	v_mfma_f32_16x16x32_bf16 v[66:69], v[2:5], v[34:37], 0
	v_mfma_f32_16x16x32_bf16 v[70:73], v[10:13], v[34:37], 0
	v_mfma_f32_16x16x32_bf16 v[74:77], v[2:5], v[42:45], 0
	v_mfma_f32_16x16x32_bf16 v[78:81], v[10:13], v[42:45], 0
	v_mfma_f32_16x16x32_bf16 v[82:85], v[2:5], v[50:53], 0
	v_mfma_f32_16x16x32_bf16 v[86:89], v[10:13], v[50:53], 0
	v_mfma_f32_16x16x32_bf16 v[90:93], v[2:5], v[58:61], 0
	v_mfma_f32_16x16x32_bf16 v[94:97], v[10:13], v[58:61], 0
	v_mfma_f32_16x16x32_bf16 v[66:69], v[6:9], v[38:41], v[66:69]
	v_mfma_f32_16x16x32_bf16 v[70:73], v[14:17], v[38:41], v[70:73]
	v_mfma_f32_16x16x32_bf16 v[74:77], v[6:9], v[46:49], v[74:77]
	v_mfma_f32_16x16x32_bf16 v[78:81], v[14:17], v[46:49], v[78:81]
	v_mfma_f32_16x16x32_bf16 v[82:85], v[6:9], v[54:57], v[82:85]
	v_mfma_f32_16x16x32_bf16 v[86:89], v[14:17], v[54:57], v[86:89]
	v_mfma_f32_16x16x32_bf16 v[90:93], v[6:9], v[62:65], v[90:93]
	v_mfma_f32_16x16x32_bf16 v[104:107], v[14:17], v[62:65], v[94:97]
	v_mfma_f32_16x16x32_bf16 v[94:97], v[18:21], v[34:37], 0
	v_mfma_f32_16x16x32_bf16 v[34:37], v[26:29], v[34:37], 0
	v_mfma_f32_16x16x32_bf16 v[108:111], v[22:25], v[38:41], v[94:97]
	v_mfma_f32_16x16x32_bf16 v[34:37], v[30:33], v[38:41], v[34:37]
	v_mfma_f32_16x16x32_bf16 v[38:41], v[18:21], v[42:45], 0
	v_mfma_f32_16x16x32_bf16 v[42:45], v[26:29], v[42:45], 0
	v_mfma_f32_16x16x32_bf16 v[38:41], v[22:25], v[46:49], v[38:41]
	v_mfma_f32_16x16x32_bf16 v[42:45], v[30:33], v[46:49], v[42:45]
	v_mfma_f32_16x16x32_bf16 v[46:49], v[18:21], v[50:53], 0
	v_mfma_f32_16x16x32_bf16 v[50:53], v[26:29], v[50:53], 0
	v_mfma_f32_16x16x32_bf16 v[46:49], v[22:25], v[54:57], v[46:49]
	v_mfma_f32_16x16x32_bf16 v[50:53], v[30:33], v[54:57], v[50:53]
	v_mfma_f32_16x16x32_bf16 v[54:57], v[18:21], v[58:61], 0
	v_mfma_f32_16x16x32_bf16 v[58:61], v[26:29], v[58:61], 0
	v_mfma_f32_16x16x32_bf16 v[54:57], v[22:25], v[62:65], v[54:57]
	v_mfma_f32_16x16x32_bf16 v[58:61], v[30:33], v[62:65], v[58:61]
	s_barrier
	s_setprio 0
	s_add_i32 s12, s58, s17
	v_lshl_add_u64 v[102:103], s[0:1], 0, v[134:135]
	s_mov_b32 m0, s12
	ds_read_b128 v[62:65], v155 offset:16384
	ds_read_b128 v[94:97], v155 offset:17408
	ds_read_b128 v[98:101], v155 offset:18432
	ds_read_b128 v[112:115], v155 offset:19456
	ds_read_b128 v[116:119], v155 offset:20480
	ds_read_b128 v[120:123], v155 offset:21504
	ds_read_b128 v[124:127], v155 offset:22528
	ds_read_b128 v[128:131], v155 offset:23552
	global_load_lds_dwordx4 v[102:103], off
	s_add_i32 m0, s12, 0x2000
	v_lshl_add_u64 v[102:103], s[0:1], 0, v[138:139]
	s_add_u32 s0, s8, 0x14000
	s_addc_u32 s1, s9, 0
	s_add_i32 s12, s59, s17
	global_load_lds_dwordx4 v[102:103], off
	v_lshl_add_u64 v[102:103], s[0:1], 0, v[134:135]
	s_mov_b32 m0, s12
	v_lshl_add_u64 v[148:149], s[56:57], 0, v[132:133]
	global_load_lds_dwordx4 v[102:103], off
	v_lshl_add_u64 v[102:103], s[0:1], 0, v[138:139]
	s_add_i32 m0, s12, 0x2000
	v_lshl_add_u64 v[144:145], s[56:57], 0, v[136:137]
	global_load_lds_dwordx4 v[102:103], off
	v_lshl_add_u64 v[102:103], v[148:149], 0, s[40:41]
	s_mov_b32 m0, s18
	s_nop 0
	global_load_lds_dwordx4 v[102:103], off
	v_lshl_add_u64 v[102:103], v[144:145], 0, s[40:41]
	s_mov_b32 m0, s19
	s_nop 0
	global_load_lds_dwordx4 v[102:103], off
	s_waitcnt vmcnt(24)
	s_waitcnt lgkmcnt(0)
	s_setprio 1
	s_barrier
	v_mfma_f32_16x16x32_bf16 v[158:161], v[2:5], v[62:65], 0
	v_mfma_f32_16x16x32_bf16 v[166:169], v[2:5], v[98:101], 0
	v_mfma_f32_16x16x32_bf16 v[174:177], v[2:5], v[116:119], 0
	v_mfma_f32_16x16x32_bf16 v[2:5], v[2:5], v[124:127], 0
	v_mfma_f32_16x16x32_bf16 v[158:161], v[6:9], v[94:97], v[158:161]
	v_mfma_f32_16x16x32_bf16 v[166:169], v[6:9], v[112:115], v[166:169]
	v_mfma_f32_16x16x32_bf16 v[174:177], v[6:9], v[120:123], v[174:177]
	v_mfma_f32_16x16x32_bf16 v[2:5], v[6:9], v[128:131], v[2:5]
	v_mfma_f32_16x16x32_bf16 v[6:9], v[10:13], v[124:127], 0
	v_mfma_f32_16x16x32_bf16 v[162:165], v[10:13], v[62:65], 0
	v_mfma_f32_16x16x32_bf16 v[170:173], v[10:13], v[98:101], 0
	v_mfma_f32_16x16x32_bf16 v[178:181], v[10:13], v[116:119], 0
	v_mfma_f32_16x16x32_bf16 v[6:9], v[14:17], v[128:131], v[6:9]
	v_mfma_f32_16x16x32_bf16 v[162:165], v[14:17], v[94:97], v[162:165]
	v_mfma_f32_16x16x32_bf16 v[170:173], v[14:17], v[112:115], v[170:173]
	v_mfma_f32_16x16x32_bf16 v[178:181], v[14:17], v[120:123], v[178:181]
	v_mfma_f32_16x16x32_bf16 v[14:17], v[26:29], v[62:65], 0
	v_mfma_f32_16x16x32_bf16 v[182:185], v[30:33], v[94:97], v[14:17]
	v_mfma_f32_16x16x32_bf16 v[14:17], v[18:21], v[98:101], 0
	v_mfma_f32_16x16x32_bf16 v[186:189], v[22:25], v[112:115], v[14:17]
	v_mfma_f32_16x16x32_bf16 v[14:17], v[26:29], v[98:101], 0
	v_mfma_f32_16x16x32_bf16 v[190:193], v[30:33], v[112:115], v[14:17]
	v_mfma_f32_16x16x32_bf16 v[14:17], v[18:21], v[116:119], 0
	v_mfma_f32_16x16x32_bf16 v[194:197], v[22:25], v[120:123], v[14:17]
	v_mfma_f32_16x16x32_bf16 v[14:17], v[26:29], v[116:119], 0
	v_mfma_f32_16x16x32_bf16 v[10:13], v[18:21], v[62:65], 0
	v_mfma_f32_16x16x32_bf16 v[198:201], v[30:33], v[120:123], v[14:17]
	v_mfma_f32_16x16x32_bf16 v[14:17], v[18:21], v[124:127], 0
	v_mfma_f32_16x16x32_bf16 v[10:13], v[22:25], v[94:97], v[10:13]
	v_mfma_f32_16x16x32_bf16 v[202:205], v[22:25], v[128:131], v[14:17]
	v_mfma_f32_16x16x32_bf16 v[14:17], v[26:29], v[124:127], 0
	v_mfma_f32_16x16x32_bf16 v[206:209], v[30:33], v[128:131], v[14:17]
	s_barrier
	s_setprio 0
	s_add_i32 s12, 0, 0x18000
	v_add_u32_e32 v1, s12, v151
	s_add_i32 s13, 0, 0x1c000
	s_nop 1
	ds_read_b128 v[14:17], v1
	ds_read_b128 v[24:27], v1 offset:1024
	ds_read_b128 v[28:31], v1 offset:2048
	ds_read_b128 v[210:213], v1 offset:3072
	v_add_u32_e32 v1, s13, v151
	ds_read_b128 v[214:217], v1
	ds_read_b128 v[218:221], v1 offset:1024
	ds_read_b128 v[222:225], v1 offset:2048
	ds_read_b128 v[226:229], v1 offset:3072
	s_add_u32 s0, s56, 0x100100
	s_addc_u32 s1, s57, 0
	s_mov_b32 m0, s20
	v_lshl_add_u64 v[22:23], s[0:1], 0, v[132:133]
	ds_read_b128 v[18:21], v155 offset:32768
	ds_read_b128 v[120:123], v155 offset:33792
	ds_read_b128 v[230:233], v155 offset:34816
	ds_read_b128 v[234:237], v155 offset:35840
	ds_read_b128 v[238:241], v155 offset:36864
	ds_read_b128 v[242:245], v155 offset:37888
	ds_read_b128 v[246:249], v155 offset:38912
	ds_read_b128 v[250:253], v155 offset:39936
	global_load_lds_dwordx4 v[22:23], off
	v_lshl_add_u64 v[22:23], s[0:1], 0, v[136:137]
	s_mov_b32 m0, s21
	s_nop 0
	global_load_lds_dwordx4 v[22:23], off
	s_waitcnt vmcnt(24)
	s_waitcnt lgkmcnt(0)
	s_setprio 1
	s_barrier
	v_mfma_f32_16x16x32_bf16 v[62:65], v[14:17], v[18:21], v[66:69]
	v_mfma_f32_16x16x32_bf16 v[128:131], v[24:27], v[120:123], v[62:65]
	v_mfma_f32_16x16x32_bf16 v[62:65], v[28:31], v[18:21], v[70:73]
	v_mfma_f32_16x16x32_bf16 v[116:119], v[210:213], v[120:123], v[62:65]
	v_mfma_f32_16x16x32_bf16 v[62:65], v[14:17], v[230:233], v[74:77]
	v_mfma_f32_16x16x32_bf16 v[112:115], v[24:27], v[234:237], v[62:65]
	v_mfma_f32_16x16x32_bf16 v[62:65], v[28:31], v[230:233], v[78:81]
	v_mfma_f32_16x16x32_bf16 v[100:103], v[210:213], v[234:237], v[62:65]
	v_mfma_f32_16x16x32_bf16 v[62:65], v[14:17], v[238:241], v[82:85]
	v_mfma_f32_16x16x32_bf16 v[96:99], v[24:27], v[242:245], v[62:65]
	v_mfma_f32_16x16x32_bf16 v[62:65], v[28:31], v[238:241], v[86:89]
	v_mfma_f32_16x16x32_bf16 v[84:87], v[210:213], v[242:245], v[62:65]
	v_mfma_f32_16x16x32_bf16 v[62:65], v[14:17], v[246:249], v[90:93]
	v_mfma_f32_16x16x32_bf16 v[80:83], v[24:27], v[250:253], v[62:65]
	v_mfma_f32_16x16x32_bf16 v[62:65], v[28:31], v[246:249], v[104:107]
	v_mfma_f32_16x16x32_bf16 v[64:67], v[210:213], v[250:253], v[62:65]
	v_mfma_f32_16x16x32_bf16 v[68:71], v[214:217], v[18:21], v[108:111]
	v_mfma_f32_16x16x32_bf16 v[18:21], v[222:225], v[18:21], v[34:37]
	v_mfma_f32_16x16x32_bf16 v[124:127], v[218:221], v[120:123], v[68:71]
	v_mfma_f32_16x16x32_bf16 v[120:123], v[226:229], v[120:123], v[18:21]
	v_mfma_f32_16x16x32_bf16 v[18:21], v[214:217], v[230:233], v[38:41]
	v_mfma_f32_16x16x32_bf16 v[108:111], v[218:221], v[234:237], v[18:21]
	v_mfma_f32_16x16x32_bf16 v[18:21], v[222:225], v[230:233], v[42:45]
	v_mfma_f32_16x16x32_bf16 v[104:107], v[226:229], v[234:237], v[18:21]
	v_mfma_f32_16x16x32_bf16 v[18:21], v[214:217], v[238:241], v[46:49]
	v_mfma_f32_16x16x32_bf16 v[92:95], v[218:221], v[242:245], v[18:21]
	v_mfma_f32_16x16x32_bf16 v[18:21], v[222:225], v[238:241], v[50:53]
	v_mfma_f32_16x16x32_bf16 v[88:91], v[226:229], v[242:245], v[18:21]
	v_mfma_f32_16x16x32_bf16 v[18:21], v[214:217], v[246:249], v[54:57]
	v_mfma_f32_16x16x32_bf16 v[72:75], v[218:221], v[250:253], v[18:21]
	v_mfma_f32_16x16x32_bf16 v[18:21], v[222:225], v[246:249], v[58:61]
	v_mfma_f32_16x16x32_bf16 v[68:71], v[226:229], v[250:253], v[18:21]
	s_barrier
	s_setprio 0
	s_add_u32 s0, s8, 0x18000
	s_addc_u32 s1, s9, 0
	s_add_i32 s12, s12, s17
	s_nop 1
	v_lshl_add_u64 v[18:19], s[0:1], 0, v[134:135]
	s_mov_b32 m0, s12
	ds_read_b128 v[40:43], v155 offset:49152
	ds_read_b128 v[44:47], v155 offset:50176
	ds_read_b128 v[230:233], v155 offset:51200
	ds_read_b128 v[234:237], v155 offset:52224
	ds_read_b128 v[238:241], v155 offset:53248
	ds_read_b128 v[242:245], v155 offset:54272
	ds_read_b128 v[246:249], v155 offset:55296
	ds_read_b128 v[250:253], v155 offset:56320
	global_load_lds_dwordx4 v[18:19], off
	s_add_i32 m0, s12, 0x2000
	v_lshl_add_u64 v[18:19], s[0:1], 0, v[138:139]
	s_add_u32 s0, s8, 0x1c000
	s_addc_u32 s1, s9, 0
	s_add_i32 s12, s13, s17
	global_load_lds_dwordx4 v[18:19], off
	v_lshl_add_u64 v[18:19], s[0:1], 0, v[134:135]
	s_mov_b32 m0, s12
	s_nop 0
	global_load_lds_dwordx4 v[18:19], off
	v_lshl_add_u64 v[18:19], s[0:1], 0, v[138:139]
	s_add_i32 m0, s12, 0x2000
	s_nop 0
	global_load_lds_dwordx4 v[18:19], off
	v_lshl_add_u64 v[18:19], v[148:149], 0, s[42:43]
	s_mov_b32 m0, s25
	s_nop 0
	global_load_lds_dwordx4 v[18:19], off
	v_lshl_add_u64 v[18:19], v[144:145], 0, s[42:43]
	s_mov_b32 m0, s33
	s_nop 0
	global_load_lds_dwordx4 v[18:19], off
	s_waitcnt vmcnt(8)
	s_waitcnt lgkmcnt(0)
	s_setprio 1
	s_barrier
	v_mfma_f32_16x16x32_bf16 v[18:21], v[14:17], v[40:43], v[158:161]
	v_mfma_f32_16x16x32_bf16 v[76:79], v[24:27], v[44:47], v[18:21]
	v_mfma_f32_16x16x32_bf16 v[18:21], v[28:31], v[40:43], v[162:165]
	v_mfma_f32_16x16x32_bf16 v[52:55], v[210:213], v[44:47], v[18:21]
	v_mfma_f32_16x16x32_bf16 v[18:21], v[14:17], v[230:233], v[166:169]
	v_mfma_f32_16x16x32_bf16 v[48:51], v[24:27], v[234:237], v[18:21]
	v_mfma_f32_16x16x32_bf16 v[18:21], v[28:31], v[230:233], v[170:173]
	v_mfma_f32_16x16x32_bf16 v[36:39], v[210:213], v[234:237], v[18:21]
	v_mfma_f32_16x16x32_bf16 v[18:21], v[14:17], v[238:241], v[174:177]
	v_mfma_f32_16x16x32_bf16 v[32:35], v[24:27], v[242:245], v[18:21]
	v_mfma_f32_16x16x32_bf16 v[18:21], v[28:31], v[238:241], v[178:181]
	v_mfma_f32_16x16x32_bf16 v[2:5], v[14:17], v[246:249], v[2:5]
	v_mfma_f32_16x16x32_bf16 v[20:23], v[210:213], v[242:245], v[18:21]
	v_mfma_f32_16x16x32_bf16 v[16:19], v[24:27], v[250:253], v[2:5]
	v_mfma_f32_16x16x32_bf16 v[2:5], v[28:31], v[246:249], v[6:9]
	v_mfma_f32_16x16x32_bf16 v[4:7], v[210:213], v[250:253], v[2:5]
	v_mfma_f32_16x16x32_bf16 v[8:11], v[214:217], v[40:43], v[10:13]
	v_mfma_f32_16x16x32_bf16 v[60:63], v[218:221], v[44:47], v[8:11]
	v_mfma_f32_16x16x32_bf16 v[8:11], v[222:225], v[40:43], v[182:185]
	v_mfma_f32_16x16x32_bf16 v[56:59], v[226:229], v[44:47], v[8:11]
	v_mfma_f32_16x16x32_bf16 v[8:11], v[214:217], v[230:233], v[186:189]
	v_mfma_f32_16x16x32_bf16 v[44:47], v[218:221], v[234:237], v[8:11]
	v_mfma_f32_16x16x32_bf16 v[8:11], v[222:225], v[230:233], v[190:193]
	v_mfma_f32_16x16x32_bf16 v[40:43], v[226:229], v[234:237], v[8:11]
	v_mfma_f32_16x16x32_bf16 v[8:11], v[214:217], v[238:241], v[194:197]
	v_mfma_f32_16x16x32_bf16 v[28:31], v[218:221], v[242:245], v[8:11]
	v_mfma_f32_16x16x32_bf16 v[8:11], v[222:225], v[238:241], v[198:201]
	v_mfma_f32_16x16x32_bf16 v[24:27], v[226:229], v[242:245], v[8:11]
	v_mfma_f32_16x16x32_bf16 v[8:11], v[214:217], v[246:249], v[202:205]
	v_mfma_f32_16x16x32_bf16 v[12:15], v[218:221], v[250:253], v[8:11]
	v_mfma_f32_16x16x32_bf16 v[8:11], v[222:225], v[246:249], v[206:209]
	v_mfma_f32_16x16x32_bf16 v[8:11], v[226:229], v[250:253], v[8:11]
	s_barrier
	s_setprio 0
	s_mov_b32 s22, 2
	s_branch .LBB0_509

.LBB0_510:
	ds_read_b128 v[158:161], v153
	ds_read_b128 v[162:165], v153 offset:1024
	ds_read_b128 v[166:169], v153 offset:2048
	ds_read_b128 v[170:173], v153 offset:3072
	ds_read_b128 v[174:177], v154
	ds_read_b128 v[178:181], v154 offset:1024
	ds_read_b128 v[182:185], v154 offset:2048
	ds_read_b128 v[186:189], v154 offset:3072
	s_add_u32 s12, s64, s26
	s_addc_u32 s13, s65, 0
	s_cmp_eq_u32 s26, s8
	s_cselect_b32 s23, s0, s13
	s_cselect_b32 s22, s1, s12
	s_cselect_b32 s57, s45, s63
	s_cselect_b32 s56, s47, s62
	s_add_i32 s67, s18, 0xc000
	v_lshl_add_u64 v[144:145], v[2:3], 0, s[26:27]
	s_mov_b32 m0, s67
	s_add_i32 s66, s18, 0xe000
	ds_read_b128 v[190:193], v155
	ds_read_b128 v[194:197], v155 offset:1024
	ds_read_b128 v[198:201], v155 offset:2048
	ds_read_b128 v[202:205], v155 offset:3072
	ds_read_b128 v[206:209], v155 offset:4096
	ds_read_b128 v[210:213], v155 offset:5120
	ds_read_b128 v[214:217], v155 offset:6144
	ds_read_b128 v[218:221], v155 offset:7168
	global_load_lds_dwordx4 v[144:145], off
	v_lshl_add_u64 v[144:145], v[148:149], 0, s[26:27]
	s_mov_b32 m0, s66
	s_nop 0
	global_load_lds_dwordx4 v[144:145], off
	s_waitcnt vmcnt(8)
	s_waitcnt lgkmcnt(0)
	s_setprio 1
	s_barrier
	v_mfma_f32_16x16x32_bf16 v[128:131], v[158:161], v[190:193], v[128:131]
	v_mfma_f32_16x16x32_bf16 v[116:119], v[166:169], v[190:193], v[116:119]
	v_mfma_f32_16x16x32_bf16 v[112:115], v[158:161], v[198:201], v[112:115]
	v_mfma_f32_16x16x32_bf16 v[100:103], v[166:169], v[198:201], v[100:103]
	v_mfma_f32_16x16x32_bf16 v[96:99], v[158:161], v[206:209], v[96:99]
	v_mfma_f32_16x16x32_bf16 v[84:87], v[166:169], v[206:209], v[84:87]
	v_mfma_f32_16x16x32_bf16 v[80:83], v[158:161], v[214:217], v[80:83]
	v_mfma_f32_16x16x32_bf16 v[64:67], v[166:169], v[214:217], v[64:67]
	v_mfma_f32_16x16x32_bf16 v[128:131], v[162:165], v[194:197], v[128:131]
	v_mfma_f32_16x16x32_bf16 v[116:119], v[170:173], v[194:197], v[116:119]
	v_mfma_f32_16x16x32_bf16 v[112:115], v[162:165], v[202:205], v[112:115]
	v_mfma_f32_16x16x32_bf16 v[100:103], v[170:173], v[202:205], v[100:103]
	v_mfma_f32_16x16x32_bf16 v[96:99], v[162:165], v[210:213], v[96:99]
	v_mfma_f32_16x16x32_bf16 v[84:87], v[170:173], v[210:213], v[84:87]
	v_mfma_f32_16x16x32_bf16 v[80:83], v[162:165], v[218:221], v[80:83]
	v_mfma_f32_16x16x32_bf16 v[64:67], v[170:173], v[218:221], v[64:67]
	v_mfma_f32_16x16x32_bf16 v[124:127], v[174:177], v[190:193], v[124:127]
	v_mfma_f32_16x16x32_bf16 v[120:123], v[182:185], v[190:193], v[120:123]
	v_mfma_f32_16x16x32_bf16 v[108:111], v[174:177], v[198:201], v[108:111]
	v_mfma_f32_16x16x32_bf16 v[104:107], v[182:185], v[198:201], v[104:107]
	v_mfma_f32_16x16x32_bf16 v[92:95], v[174:177], v[206:209], v[92:95]
	v_mfma_f32_16x16x32_bf16 v[88:91], v[182:185], v[206:209], v[88:91]
	v_mfma_f32_16x16x32_bf16 v[72:75], v[174:177], v[214:217], v[72:75]
	v_mfma_f32_16x16x32_bf16 v[68:71], v[182:185], v[214:217], v[68:71]
	v_mfma_f32_16x16x32_bf16 v[124:127], v[178:181], v[194:197], v[124:127]
	v_mfma_f32_16x16x32_bf16 v[120:123], v[186:189], v[194:197], v[120:123]
	v_mfma_f32_16x16x32_bf16 v[108:111], v[178:181], v[202:205], v[108:111]
	v_mfma_f32_16x16x32_bf16 v[104:107], v[186:189], v[202:205], v[104:107]
	v_mfma_f32_16x16x32_bf16 v[92:95], v[178:181], v[210:213], v[92:95]
	v_mfma_f32_16x16x32_bf16 v[88:91], v[186:189], v[210:213], v[88:91]
	v_mfma_f32_16x16x32_bf16 v[72:75], v[178:181], v[218:221], v[72:75]
	v_mfma_f32_16x16x32_bf16 v[68:71], v[186:189], v[218:221], v[68:71]
	s_barrier
	s_setprio 0
	s_add_i32 s12, s58, s17
	v_lshl_add_u64 v[144:145], s[56:57], 0, v[134:135]
	s_mov_b32 m0, s12
	ds_read_b128 v[190:193], v155 offset:16384
	ds_read_b128 v[194:197], v155 offset:17408
	ds_read_b128 v[198:201], v155 offset:18432
	ds_read_b128 v[202:205], v155 offset:19456
	ds_read_b128 v[206:209], v155 offset:20480
	ds_read_b128 v[210:213], v155 offset:21504
	ds_read_b128 v[214:217], v155 offset:22528
	ds_read_b128 v[218:221], v155 offset:23552
	global_load_lds_dwordx4 v[144:145], off
	s_add_i32 m0, s12, 0x2000
	s_add_u32 s12, s56, 0x4000
	v_lshl_add_u64 v[144:145], s[56:57], 0, v[138:139]
	s_addc_u32 s13, s57, 0
	s_add_i32 s14, s59, s17
	global_load_lds_dwordx4 v[144:145], off
	v_lshl_add_u64 v[144:145], s[12:13], 0, v[134:135]
	s_mov_b32 m0, s14
	v_lshl_add_u64 v[222:223], s[22:23], 0, v[136:137]
	global_load_lds_dwordx4 v[144:145], off
	v_lshl_add_u64 v[144:145], s[12:13], 0, v[138:139]
	s_add_i32 m0, s14, 0x2000
	s_nop 0
	global_load_lds_dwordx4 v[144:145], off
	v_lshl_add_u64 v[144:145], s[22:23], 0, v[132:133]
	s_mov_b32 m0, s18
	s_nop 0
	global_load_lds_dwordx4 v[144:145], off
	s_mov_b32 m0, s19
	s_nop 0
	global_load_lds_dwordx4 v[222:223], off
	s_waitcnt vmcnt(8)
	s_waitcnt lgkmcnt(0)
	s_setprio 1
	s_barrier
	v_mfma_f32_16x16x32_bf16 v[76:79], v[158:161], v[190:193], v[76:79]
	v_mfma_f32_16x16x32_bf16 v[52:55], v[166:169], v[190:193], v[52:55]
	v_mfma_f32_16x16x32_bf16 v[48:51], v[158:161], v[198:201], v[48:51]
	v_mfma_f32_16x16x32_bf16 v[36:39], v[166:169], v[198:201], v[36:39]
	v_mfma_f32_16x16x32_bf16 v[32:35], v[158:161], v[206:209], v[32:35]
	v_mfma_f32_16x16x32_bf16 v[20:23], v[166:169], v[206:209], v[20:23]
	v_mfma_f32_16x16x32_bf16 v[16:19], v[158:161], v[214:217], v[16:19]
	v_mfma_f32_16x16x32_bf16 v[4:7], v[166:169], v[214:217], v[4:7]
	v_mfma_f32_16x16x32_bf16 v[76:79], v[162:165], v[194:197], v[76:79]
	v_mfma_f32_16x16x32_bf16 v[52:55], v[170:173], v[194:197], v[52:55]
	v_mfma_f32_16x16x32_bf16 v[48:51], v[162:165], v[202:205], v[48:51]
	v_mfma_f32_16x16x32_bf16 v[36:39], v[170:173], v[202:205], v[36:39]
	v_mfma_f32_16x16x32_bf16 v[32:35], v[162:165], v[210:213], v[32:35]
	v_mfma_f32_16x16x32_bf16 v[20:23], v[170:173], v[210:213], v[20:23]
	v_mfma_f32_16x16x32_bf16 v[16:19], v[162:165], v[218:221], v[16:19]
	v_mfma_f32_16x16x32_bf16 v[4:7], v[170:173], v[218:221], v[4:7]
	v_mfma_f32_16x16x32_bf16 v[60:63], v[174:177], v[190:193], v[60:63]
	v_mfma_f32_16x16x32_bf16 v[56:59], v[182:185], v[190:193], v[56:59]
	v_mfma_f32_16x16x32_bf16 v[44:47], v[174:177], v[198:201], v[44:47]
	v_mfma_f32_16x16x32_bf16 v[40:43], v[182:185], v[198:201], v[40:43]
	v_mfma_f32_16x16x32_bf16 v[28:31], v[174:177], v[206:209], v[28:31]
	v_mfma_f32_16x16x32_bf16 v[24:27], v[182:185], v[206:209], v[24:27]
	v_mfma_f32_16x16x32_bf16 v[12:15], v[174:177], v[214:217], v[12:15]
	v_mfma_f32_16x16x32_bf16 v[8:11], v[182:185], v[214:217], v[8:11]
	v_mfma_f32_16x16x32_bf16 v[60:63], v[178:181], v[194:197], v[60:63]
	v_mfma_f32_16x16x32_bf16 v[56:59], v[186:189], v[194:197], v[56:59]
	v_mfma_f32_16x16x32_bf16 v[44:47], v[178:181], v[202:205], v[44:47]
	v_mfma_f32_16x16x32_bf16 v[40:43], v[186:189], v[202:205], v[40:43]
	v_mfma_f32_16x16x32_bf16 v[28:31], v[178:181], v[210:213], v[28:31]
	v_mfma_f32_16x16x32_bf16 v[24:27], v[186:189], v[210:213], v[24:27]
	v_mfma_f32_16x16x32_bf16 v[12:15], v[178:181], v[218:221], v[12:15]
	v_mfma_f32_16x16x32_bf16 v[8:11], v[186:189], v[218:221], v[8:11]
	s_barrier
	s_setprio 0
	s_add_i32 s14, 0, 0x18000
	v_add_u32_e32 v1, s14, v151
	s_add_i32 s68, 0, 0x1c000
	ds_read_b128 v[158:161], v1
	ds_read_b128 v[162:165], v1 offset:1024
	ds_read_b128 v[166:169], v1 offset:2048
	ds_read_b128 v[170:173], v1 offset:3072
	v_add_u32_e32 v1, s68, v151
	ds_read_b128 v[174:177], v1
	ds_read_b128 v[178:181], v1 offset:1024
	ds_read_b128 v[182:185], v1 offset:2048
	ds_read_b128 v[186:189], v1 offset:3072
	s_add_u32 s12, s22, 0x100000
	s_addc_u32 s13, s23, 0
	s_mov_b32 m0, s20
	v_lshl_add_u64 v[224:225], s[12:13], 0, v[132:133]
	ds_read_b128 v[190:193], v155 offset:32768
	ds_read_b128 v[194:197], v155 offset:33792
	ds_read_b128 v[198:201], v155 offset:34816
	ds_read_b128 v[202:205], v155 offset:35840
	ds_read_b128 v[206:209], v155 offset:36864
	ds_read_b128 v[210:213], v155 offset:37888
	ds_read_b128 v[214:217], v155 offset:38912
	ds_read_b128 v[218:221], v155 offset:39936
	global_load_lds_dwordx4 v[224:225], off
	v_lshl_add_u64 v[224:225], s[12:13], 0, v[136:137]
	s_mov_b32 m0, s21
	s_nop 0
	global_load_lds_dwordx4 v[224:225], off
	s_waitcnt vmcnt(8)
	s_waitcnt lgkmcnt(0)
	s_setprio 1
	s_barrier
	v_mfma_f32_16x16x32_bf16 v[128:131], v[158:161], v[190:193], v[128:131]
	v_mfma_f32_16x16x32_bf16 v[116:119], v[166:169], v[190:193], v[116:119]
	v_mfma_f32_16x16x32_bf16 v[112:115], v[158:161], v[198:201], v[112:115]
	v_mfma_f32_16x16x32_bf16 v[100:103], v[166:169], v[198:201], v[100:103]
	v_mfma_f32_16x16x32_bf16 v[96:99], v[158:161], v[206:209], v[96:99]
	v_mfma_f32_16x16x32_bf16 v[84:87], v[166:169], v[206:209], v[84:87]
	v_mfma_f32_16x16x32_bf16 v[80:83], v[158:161], v[214:217], v[80:83]
	v_mfma_f32_16x16x32_bf16 v[64:67], v[166:169], v[214:217], v[64:67]
	v_mfma_f32_16x16x32_bf16 v[128:131], v[162:165], v[194:197], v[128:131]
	v_mfma_f32_16x16x32_bf16 v[116:119], v[170:173], v[194:197], v[116:119]
	v_mfma_f32_16x16x32_bf16 v[112:115], v[162:165], v[202:205], v[112:115]
	v_mfma_f32_16x16x32_bf16 v[100:103], v[170:173], v[202:205], v[100:103]
	v_mfma_f32_16x16x32_bf16 v[96:99], v[162:165], v[210:213], v[96:99]
	v_mfma_f32_16x16x32_bf16 v[84:87], v[170:173], v[210:213], v[84:87]
	v_mfma_f32_16x16x32_bf16 v[80:83], v[162:165], v[218:221], v[80:83]
	v_mfma_f32_16x16x32_bf16 v[64:67], v[170:173], v[218:221], v[64:67]
	v_mfma_f32_16x16x32_bf16 v[124:127], v[174:177], v[190:193], v[124:127]
	v_mfma_f32_16x16x32_bf16 v[120:123], v[182:185], v[190:193], v[120:123]
	v_mfma_f32_16x16x32_bf16 v[108:111], v[174:177], v[198:201], v[108:111]
	v_mfma_f32_16x16x32_bf16 v[104:107], v[182:185], v[198:201], v[104:107]
	v_mfma_f32_16x16x32_bf16 v[92:95], v[174:177], v[206:209], v[92:95]
	v_mfma_f32_16x16x32_bf16 v[88:91], v[182:185], v[206:209], v[88:91]
	v_mfma_f32_16x16x32_bf16 v[72:75], v[174:177], v[214:217], v[72:75]
	v_mfma_f32_16x16x32_bf16 v[68:71], v[182:185], v[214:217], v[68:71]
	v_mfma_f32_16x16x32_bf16 v[124:127], v[178:181], v[194:197], v[124:127]
	v_mfma_f32_16x16x32_bf16 v[120:123], v[186:189], v[194:197], v[120:123]
	v_mfma_f32_16x16x32_bf16 v[108:111], v[178:181], v[202:205], v[108:111]
	v_mfma_f32_16x16x32_bf16 v[104:107], v[186:189], v[202:205], v[104:107]
	v_mfma_f32_16x16x32_bf16 v[92:95], v[178:181], v[210:213], v[92:95]
	v_mfma_f32_16x16x32_bf16 v[88:91], v[186:189], v[210:213], v[88:91]
	v_mfma_f32_16x16x32_bf16 v[72:75], v[178:181], v[218:221], v[72:75]
	v_mfma_f32_16x16x32_bf16 v[68:71], v[186:189], v[218:221], v[68:71]
	s_barrier
	s_setprio 0
	s_add_u32 s12, s56, 0x8000
	s_addc_u32 s13, s57, 0
	s_add_i32 s14, s14, s17
	v_lshl_add_u64 v[224:225], s[12:13], 0, v[134:135]
	s_mov_b32 m0, s14
	ds_read_b128 v[190:193], v155 offset:49152
	ds_read_b128 v[194:197], v155 offset:50176
	ds_read_b128 v[198:201], v155 offset:51200
	ds_read_b128 v[202:205], v155 offset:52224
	ds_read_b128 v[206:209], v155 offset:53248
	ds_read_b128 v[210:213], v155 offset:54272
	ds_read_b128 v[214:217], v155 offset:55296
	ds_read_b128 v[218:221], v155 offset:56320
	global_load_lds_dwordx4 v[224:225], off
	s_add_i32 m0, s14, 0x2000
	v_lshl_add_u64 v[224:225], s[12:13], 0, v[138:139]
	s_add_u32 s12, s56, 0xc000
	s_addc_u32 s13, s57, 0
	s_add_i32 s14, s68, s17
	global_load_lds_dwordx4 v[224:225], off
	v_lshl_add_u64 v[224:225], s[12:13], 0, v[134:135]
	s_mov_b32 m0, s14
	v_lshl_add_u64 v[144:145], v[144:145], 0, s[36:37]
	global_load_lds_dwordx4 v[224:225], off
	v_lshl_add_u64 v[224:225], s[12:13], 0, v[138:139]
	s_add_i32 m0, s14, 0x2000
	s_nop 0
	global_load_lds_dwordx4 v[224:225], off
	s_mov_b32 m0, s25
	s_nop 0
	global_load_lds_dwordx4 v[144:145], off
	v_lshl_add_u64 v[144:145], v[222:223], 0, s[36:37]
	s_mov_b32 m0, s33
	s_nop 0
	global_load_lds_dwordx4 v[144:145], off
	s_waitcnt vmcnt(8)
	s_waitcnt lgkmcnt(0)
	s_setprio 1
	s_barrier
	v_mfma_f32_16x16x32_bf16 v[76:79], v[158:161], v[190:193], v[76:79]
	v_mfma_f32_16x16x32_bf16 v[52:55], v[166:169], v[190:193], v[52:55]
	v_mfma_f32_16x16x32_bf16 v[48:51], v[158:161], v[198:201], v[48:51]
	v_mfma_f32_16x16x32_bf16 v[36:39], v[166:169], v[198:201], v[36:39]
	v_mfma_f32_16x16x32_bf16 v[32:35], v[158:161], v[206:209], v[32:35]
	v_mfma_f32_16x16x32_bf16 v[20:23], v[166:169], v[206:209], v[20:23]
	v_mfma_f32_16x16x32_bf16 v[16:19], v[158:161], v[214:217], v[16:19]
	v_mfma_f32_16x16x32_bf16 v[4:7], v[166:169], v[214:217], v[4:7]
	v_mfma_f32_16x16x32_bf16 v[76:79], v[162:165], v[194:197], v[76:79]
	v_mfma_f32_16x16x32_bf16 v[52:55], v[170:173], v[194:197], v[52:55]
	v_mfma_f32_16x16x32_bf16 v[48:51], v[162:165], v[202:205], v[48:51]
	v_mfma_f32_16x16x32_bf16 v[36:39], v[170:173], v[202:205], v[36:39]
	v_mfma_f32_16x16x32_bf16 v[32:35], v[162:165], v[210:213], v[32:35]
	v_mfma_f32_16x16x32_bf16 v[20:23], v[170:173], v[210:213], v[20:23]
	v_mfma_f32_16x16x32_bf16 v[16:19], v[162:165], v[218:221], v[16:19]
	v_mfma_f32_16x16x32_bf16 v[4:7], v[170:173], v[218:221], v[4:7]
	v_mfma_f32_16x16x32_bf16 v[60:63], v[174:177], v[190:193], v[60:63]
	v_mfma_f32_16x16x32_bf16 v[56:59], v[182:185], v[190:193], v[56:59]
	v_mfma_f32_16x16x32_bf16 v[44:47], v[174:177], v[198:201], v[44:47]
	v_mfma_f32_16x16x32_bf16 v[40:43], v[182:185], v[198:201], v[40:43]
	v_mfma_f32_16x16x32_bf16 v[28:31], v[174:177], v[206:209], v[28:31]
	v_mfma_f32_16x16x32_bf16 v[24:27], v[182:185], v[206:209], v[24:27]
	v_mfma_f32_16x16x32_bf16 v[12:15], v[174:177], v[214:217], v[12:15]
	v_mfma_f32_16x16x32_bf16 v[8:11], v[182:185], v[214:217], v[8:11]
	v_mfma_f32_16x16x32_bf16 v[60:63], v[178:181], v[194:197], v[60:63]
	v_mfma_f32_16x16x32_bf16 v[56:59], v[186:189], v[194:197], v[56:59]
	v_mfma_f32_16x16x32_bf16 v[44:47], v[178:181], v[202:205], v[44:47]
	v_mfma_f32_16x16x32_bf16 v[40:43], v[186:189], v[202:205], v[40:43]
	v_mfma_f32_16x16x32_bf16 v[28:31], v[178:181], v[210:213], v[28:31]
	v_mfma_f32_16x16x32_bf16 v[24:27], v[186:189], v[210:213], v[24:27]
	v_mfma_f32_16x16x32_bf16 v[12:15], v[178:181], v[218:221], v[12:15]
	v_mfma_f32_16x16x32_bf16 v[8:11], v[186:189], v[218:221], v[8:11]
	s_barrier
	s_setprio 0
	s_add_i32 s61, s61, 2
	s_add_u32 s62, s62, 0x10000
	s_addc_u32 s63, s63, 0
	s_add_u32 s64, s64, 0x100
	s_addc_u32 s65, s65, 0
	s_add_u32 s8, s8, 0xffffff00
	s_addc_u32 s9, s9, -1
	v_lshl_add_u64 v[2:3], v[2:3], 0, s[40:41]
	s_cmp_gt_u32 s61, 61
	v_lshl_add_u64 v[148:149], v[148:149], 0, s[40:41]
	s_cbranch_scc0 .LBB0_510
	s_and_b64 vcc, exec, s[38:39]
	s_cbranch_vccz .LBB0_513
	s_barrier

.LBB0_664:
	s_cmp_lg_u32 s65, 0
	s_mov_b32 s22, 0
	s_cbranch_scc0 .LBB0_666
	ds_read_b128 v[2:5], v155
	ds_read_b128 v[6:9], v155 offset:1024
	ds_read_b128 v[10:13], v155 offset:2048
	ds_read_b128 v[14:17], v155 offset:3072
	ds_read_b128 v[18:21], v156
	ds_read_b128 v[22:25], v156 offset:1024
	ds_read_b128 v[26:29], v156 offset:2048
	ds_read_b128 v[30:33], v156 offset:3072
	s_add_u32 s0, s54, 0x10000
	s_addc_u32 s1, s55, 0
	ds_read_b128 v[34:37], v157
	ds_read_b128 v[38:41], v157 offset:1024
	ds_read_b128 v[42:45], v157 offset:2048
	ds_read_b128 v[46:49], v157 offset:3072
	ds_read_b128 v[50:53], v157 offset:4096
	ds_read_b128 v[54:57], v157 offset:5120
	ds_read_b128 v[58:61], v157 offset:6144
	ds_read_b128 v[62:65], v157 offset:7168
	s_waitcnt vmcnt(16)
	s_waitcnt lgkmcnt(0)
	s_setprio 1
	s_barrier
	v_mfma_f32_16x16x32_bf16 v[86:89], v[10:13], v[50:53], 0
	v_mfma_f32_16x16x32_bf16 v[92:95], v[14:17], v[54:57], v[86:89]
	v_mfma_f32_16x16x32_bf16 v[86:89], v[2:5], v[58:61], 0
	v_mfma_f32_16x16x32_bf16 v[66:69], v[2:5], v[34:37], 0
	v_mfma_f32_16x16x32_bf16 v[70:73], v[10:13], v[34:37], 0
	v_mfma_f32_16x16x32_bf16 v[74:77], v[2:5], v[42:45], 0
	v_mfma_f32_16x16x32_bf16 v[78:81], v[10:13], v[42:45], 0
	v_mfma_f32_16x16x32_bf16 v[82:85], v[2:5], v[50:53], 0
	v_mfma_f32_16x16x32_bf16 v[96:99], v[6:9], v[62:65], v[86:89]
	v_mfma_f32_16x16x32_bf16 v[86:89], v[10:13], v[58:61], 0
	v_mfma_f32_16x16x32_bf16 v[66:69], v[6:9], v[38:41], v[66:69]
	v_mfma_f32_16x16x32_bf16 v[70:73], v[14:17], v[38:41], v[70:73]
	v_mfma_f32_16x16x32_bf16 v[74:77], v[6:9], v[46:49], v[74:77]
	v_mfma_f32_16x16x32_bf16 v[78:81], v[14:17], v[46:49], v[78:81]
	v_mfma_f32_16x16x32_bf16 v[82:85], v[6:9], v[54:57], v[82:85]
	v_mfma_f32_16x16x32_bf16 v[108:111], v[14:17], v[62:65], v[86:89]
	v_mfma_f32_16x16x32_bf16 v[86:89], v[18:21], v[34:37], 0
	v_mfma_f32_16x16x32_bf16 v[34:37], v[26:29], v[34:37], 0
	v_mfma_f32_16x16x32_bf16 v[112:115], v[22:25], v[38:41], v[86:89]
	v_mfma_f32_16x16x32_bf16 v[34:37], v[30:33], v[38:41], v[34:37]
	v_mfma_f32_16x16x32_bf16 v[38:41], v[18:21], v[42:45], 0
	v_mfma_f32_16x16x32_bf16 v[42:45], v[26:29], v[42:45], 0
	v_mfma_f32_16x16x32_bf16 v[38:41], v[22:25], v[46:49], v[38:41]
	v_mfma_f32_16x16x32_bf16 v[42:45], v[30:33], v[46:49], v[42:45]
	v_mfma_f32_16x16x32_bf16 v[46:49], v[18:21], v[50:53], 0
	v_mfma_f32_16x16x32_bf16 v[50:53], v[26:29], v[50:53], 0
	v_mfma_f32_16x16x32_bf16 v[46:49], v[22:25], v[54:57], v[46:49]
	v_mfma_f32_16x16x32_bf16 v[50:53], v[30:33], v[54:57], v[50:53]
	v_mfma_f32_16x16x32_bf16 v[54:57], v[18:21], v[58:61], 0
	v_mfma_f32_16x16x32_bf16 v[58:61], v[26:29], v[58:61], 0
	v_mfma_f32_16x16x32_bf16 v[54:57], v[22:25], v[62:65], v[54:57]
	v_mfma_f32_16x16x32_bf16 v[58:61], v[30:33], v[62:65], v[58:61]
	s_barrier
	s_setprio 0
	s_add_i32 s12, s58, s20
	v_lshl_add_u64 v[90:91], s[0:1], 0, v[134:135]
	s_mov_b32 m0, s12
	ds_read_b128 v[62:65], v157 offset:16384
	ds_read_b128 v[86:89], v157 offset:17408
	ds_read_b128 v[100:103], v157 offset:18432
	ds_read_b128 v[104:107], v157 offset:19456
	ds_read_b128 v[116:119], v157 offset:20480
	ds_read_b128 v[120:123], v157 offset:21504
	ds_read_b128 v[124:127], v157 offset:22528
	ds_read_b128 v[128:131], v157 offset:23552
	global_load_lds_dwordx4 v[90:91], off
	s_add_i32 m0, s12, 0x2000
	v_lshl_add_u64 v[90:91], s[0:1], 0, v[138:139]
	s_add_u32 s0, s54, 0x14000
	s_addc_u32 s1, s55, 0
	s_add_i32 s12, s59, s20
	global_load_lds_dwordx4 v[90:91], off
	v_lshl_add_u64 v[90:91], s[0:1], 0, v[134:135]
	s_mov_b32 m0, s12
	v_lshl_add_u64 v[148:149], s[6:7], 0, v[132:133]
	global_load_lds_dwordx4 v[90:91], off
	v_lshl_add_u64 v[90:91], s[0:1], 0, v[138:139]
	s_add_i32 m0, s12, 0x2000
	v_lshl_add_u64 v[144:145], s[6:7], 0, v[136:137]
	global_load_lds_dwordx4 v[90:91], off
	v_lshl_add_u64 v[90:91], v[148:149], 0, s[38:39]
	s_mov_b32 m0, s21
	s_nop 0
	global_load_lds_dwordx4 v[90:91], off
	v_lshl_add_u64 v[90:91], v[144:145], 0, s[38:39]
	s_mov_b32 m0, s24
	s_nop 0
	global_load_lds_dwordx4 v[90:91], off
	s_waitcnt vmcnt(16)
	s_waitcnt lgkmcnt(0)
	s_setprio 1
	s_barrier
	v_mfma_f32_16x16x32_bf16 v[158:161], v[2:5], v[62:65], 0
	v_mfma_f32_16x16x32_bf16 v[166:169], v[2:5], v[100:103], 0
	v_mfma_f32_16x16x32_bf16 v[174:177], v[2:5], v[116:119], 0
	v_mfma_f32_16x16x32_bf16 v[2:5], v[2:5], v[124:127], 0
	v_mfma_f32_16x16x32_bf16 v[158:161], v[6:9], v[86:89], v[158:161]
	v_mfma_f32_16x16x32_bf16 v[162:165], v[10:13], v[62:65], 0
	v_mfma_f32_16x16x32_bf16 v[166:169], v[6:9], v[104:107], v[166:169]
	v_mfma_f32_16x16x32_bf16 v[170:173], v[10:13], v[100:103], 0
	v_mfma_f32_16x16x32_bf16 v[174:177], v[6:9], v[120:123], v[174:177]
	v_mfma_f32_16x16x32_bf16 v[178:181], v[10:13], v[116:119], 0
	v_mfma_f32_16x16x32_bf16 v[2:5], v[6:9], v[128:131], v[2:5]
	v_mfma_f32_16x16x32_bf16 v[6:9], v[10:13], v[124:127], 0
	v_mfma_f32_16x16x32_bf16 v[162:165], v[14:17], v[86:89], v[162:165]
	v_mfma_f32_16x16x32_bf16 v[170:173], v[14:17], v[104:107], v[170:173]
	v_mfma_f32_16x16x32_bf16 v[178:181], v[14:17], v[120:123], v[178:181]
	v_mfma_f32_16x16x32_bf16 v[12:15], v[14:17], v[128:131], v[6:9]
	v_mfma_f32_16x16x32_bf16 v[6:9], v[18:21], v[62:65], 0
	v_mfma_f32_16x16x32_bf16 v[182:185], v[22:25], v[86:89], v[6:9]
	v_mfma_f32_16x16x32_bf16 v[6:9], v[26:29], v[62:65], 0
	v_mfma_f32_16x16x32_bf16 v[186:189], v[30:33], v[86:89], v[6:9]
	v_mfma_f32_16x16x32_bf16 v[6:9], v[18:21], v[100:103], 0
	v_mfma_f32_16x16x32_bf16 v[190:193], v[22:25], v[104:107], v[6:9]
	v_mfma_f32_16x16x32_bf16 v[6:9], v[26:29], v[100:103], 0
	v_mfma_f32_16x16x32_bf16 v[194:197], v[30:33], v[104:107], v[6:9]
	v_mfma_f32_16x16x32_bf16 v[6:9], v[18:21], v[116:119], 0
	v_mfma_f32_16x16x32_bf16 v[198:201], v[22:25], v[120:123], v[6:9]
	v_mfma_f32_16x16x32_bf16 v[6:9], v[26:29], v[116:119], 0
	v_mfma_f32_16x16x32_bf16 v[202:205], v[30:33], v[120:123], v[6:9]
	v_mfma_f32_16x16x32_bf16 v[6:9], v[18:21], v[124:127], 0
	v_mfma_f32_16x16x32_bf16 v[16:19], v[22:25], v[128:131], v[6:9]
	v_mfma_f32_16x16x32_bf16 v[6:9], v[26:29], v[124:127], 0
	v_mfma_f32_16x16x32_bf16 v[206:209], v[30:33], v[128:131], v[6:9]
	s_barrier
	s_setprio 0
	s_add_i32 s12, 0, 0x18000
	v_add_u32_e32 v1, s12, v152
	s_add_i32 s13, 0, 0x1c000
	s_nop 1
	ds_read_b128 v[6:9], v1
	ds_read_b128 v[28:31], v1 offset:1024
	ds_read_b128 v[62:65], v1 offset:2048
	ds_read_b128 v[210:213], v1 offset:3072
	v_add_u32_e32 v1, s13, v152
	ds_read_b128 v[214:217], v1
	ds_read_b128 v[218:221], v1 offset:1024
	ds_read_b128 v[222:225], v1 offset:2048
	ds_read_b128 v[226:229], v1 offset:3072
	s_add_u32 s0, s6, 0x100100
	s_addc_u32 s1, s7, 0
	s_mov_b32 m0, s25
	v_lshl_add_u64 v[10:11], s[0:1], 0, v[132:133]
	ds_read_b128 v[20:23], v157 offset:32768
	ds_read_b128 v[24:27], v157 offset:33792
	ds_read_b128 v[230:233], v157 offset:34816
	ds_read_b128 v[234:237], v157 offset:35840
	ds_read_b128 v[238:241], v157 offset:36864
	ds_read_b128 v[242:245], v157 offset:37888
	ds_read_b128 v[246:249], v157 offset:38912
	ds_read_b128 v[250:253], v157 offset:39936
	global_load_lds_dwordx4 v[10:11], off
	v_lshl_add_u64 v[10:11], s[0:1], 0, v[136:137]
	s_mov_b32 m0, s33
	s_nop 0
	global_load_lds_dwordx4 v[10:11], off
	s_waitcnt vmcnt(16)
	s_waitcnt lgkmcnt(0)
	s_setprio 1
	s_barrier
	v_mfma_f32_16x16x32_bf16 v[66:69], v[6:9], v[20:23], v[66:69]
	v_mfma_f32_16x16x32_bf16 v[120:123], v[28:31], v[24:27], v[66:69]
	v_mfma_f32_16x16x32_bf16 v[66:69], v[62:65], v[20:23], v[70:73]
	v_mfma_f32_16x16x32_bf16 v[116:119], v[210:213], v[24:27], v[66:69]
	v_mfma_f32_16x16x32_bf16 v[66:69], v[6:9], v[230:233], v[74:77]
	v_mfma_f32_16x16x32_bf16 v[104:107], v[28:31], v[234:237], v[66:69]
	v_mfma_f32_16x16x32_bf16 v[66:69], v[62:65], v[230:233], v[78:81]
	v_mfma_f32_16x16x32_bf16 v[100:103], v[210:213], v[234:237], v[66:69]
	v_mfma_f32_16x16x32_bf16 v[66:69], v[6:9], v[238:241], v[82:85]
	v_mfma_f32_16x16x32_bf16 v[88:91], v[28:31], v[242:245], v[66:69]
	v_mfma_f32_16x16x32_bf16 v[66:69], v[62:65], v[238:241], v[92:95]
	v_mfma_f32_16x16x32_bf16 v[84:87], v[210:213], v[242:245], v[66:69]
	v_mfma_f32_16x16x32_bf16 v[66:69], v[6:9], v[246:249], v[96:99]
	v_mfma_f32_16x16x32_bf16 v[72:75], v[28:31], v[250:253], v[66:69]
	v_mfma_f32_16x16x32_bf16 v[66:69], v[62:65], v[246:249], v[108:111]
	v_mfma_f32_16x16x32_bf16 v[68:71], v[210:213], v[250:253], v[66:69]
	v_mfma_f32_16x16x32_bf16 v[76:79], v[214:217], v[20:23], v[112:115]
	v_mfma_f32_16x16x32_bf16 v[20:23], v[222:225], v[20:23], v[34:37]
	v_mfma_f32_16x16x32_bf16 v[124:127], v[226:229], v[24:27], v[20:23]
	v_mfma_f32_16x16x32_bf16 v[20:23], v[214:217], v[230:233], v[38:41]
	v_mfma_f32_16x16x32_bf16 v[112:115], v[218:221], v[234:237], v[20:23]
	v_mfma_f32_16x16x32_bf16 v[20:23], v[222:225], v[230:233], v[42:45]
	v_mfma_f32_16x16x32_bf16 v[108:111], v[226:229], v[234:237], v[20:23]
	v_mfma_f32_16x16x32_bf16 v[20:23], v[214:217], v[238:241], v[46:49]
	v_mfma_f32_16x16x32_bf16 v[96:99], v[218:221], v[242:245], v[20:23]
	v_mfma_f32_16x16x32_bf16 v[20:23], v[222:225], v[238:241], v[50:53]
	v_mfma_f32_16x16x32_bf16 v[92:95], v[226:229], v[242:245], v[20:23]
	v_mfma_f32_16x16x32_bf16 v[20:23], v[214:217], v[246:249], v[54:57]
	v_mfma_f32_16x16x32_bf16 v[80:83], v[218:221], v[250:253], v[20:23]
	v_mfma_f32_16x16x32_bf16 v[20:23], v[222:225], v[246:249], v[58:61]
	v_mfma_f32_16x16x32_bf16 v[128:131], v[218:221], v[24:27], v[76:79]
	v_mfma_f32_16x16x32_bf16 v[76:79], v[226:229], v[250:253], v[20:23]
	s_barrier
	s_setprio 0
	s_add_u32 s0, s54, 0x18000
	s_addc_u32 s1, s55, 0
	s_add_i32 s12, s12, s20
	v_lshl_add_u64 v[10:11], s[0:1], 0, v[134:135]
	s_mov_b32 m0, s12
	ds_read_b128 v[32:35], v157 offset:49152
	ds_read_b128 v[44:47], v157 offset:50176
	ds_read_b128 v[230:233], v157 offset:51200
	ds_read_b128 v[234:237], v157 offset:52224
	ds_read_b128 v[238:241], v157 offset:53248
	ds_read_b128 v[242:245], v157 offset:54272
	ds_read_b128 v[246:249], v157 offset:55296
	ds_read_b128 v[250:253], v157 offset:56320
	global_load_lds_dwordx4 v[10:11], off
	s_add_i32 m0, s12, 0x2000
	v_lshl_add_u64 v[10:11], s[0:1], 0, v[138:139]
	s_add_u32 s0, s54, 0x1c000
	s_addc_u32 s1, s55, 0
	s_add_i32 s12, s13, s20
	global_load_lds_dwordx4 v[10:11], off
	v_lshl_add_u64 v[10:11], s[0:1], 0, v[134:135]
	s_mov_b32 m0, s12
	s_nop 0
	global_load_lds_dwordx4 v[10:11], off
	v_lshl_add_u64 v[10:11], s[0:1], 0, v[138:139]
	s_add_i32 m0, s12, 0x2000
	s_nop 0
	global_load_lds_dwordx4 v[10:11], off
	v_lshl_add_u64 v[10:11], v[148:149], 0, s[40:41]
	s_mov_b32 m0, s51
	s_nop 0
	global_load_lds_dwordx4 v[10:11], off
	v_lshl_add_u64 v[10:11], v[144:145], 0, s[40:41]
	s_mov_b32 m0, s53
	s_nop 0
	global_load_lds_dwordx4 v[10:11], off
	s_waitcnt vmcnt(8)
	s_waitcnt lgkmcnt(0)
	s_setprio 1
	s_barrier
	v_mfma_f32_16x16x32_bf16 v[20:23], v[6:9], v[32:35], v[158:161]
	v_mfma_f32_16x16x32_bf16 v[56:59], v[28:31], v[44:47], v[20:23]
	v_mfma_f32_16x16x32_bf16 v[20:23], v[62:65], v[32:35], v[162:165]
	v_mfma_f32_16x16x32_bf16 v[52:55], v[210:213], v[44:47], v[20:23]
	v_mfma_f32_16x16x32_bf16 v[20:23], v[6:9], v[230:233], v[166:169]
	v_mfma_f32_16x16x32_bf16 v[40:43], v[28:31], v[234:237], v[20:23]
	v_mfma_f32_16x16x32_bf16 v[20:23], v[62:65], v[230:233], v[170:173]
	v_mfma_f32_16x16x32_bf16 v[36:39], v[210:213], v[234:237], v[20:23]
	v_mfma_f32_16x16x32_bf16 v[20:23], v[6:9], v[238:241], v[174:177]
	v_mfma_f32_16x16x32_bf16 v[2:5], v[6:9], v[246:249], v[2:5]
	v_mfma_f32_16x16x32_bf16 v[24:27], v[28:31], v[242:245], v[20:23]
	v_mfma_f32_16x16x32_bf16 v[20:23], v[62:65], v[238:241], v[178:181]
	v_mfma_f32_16x16x32_bf16 v[8:11], v[28:31], v[250:253], v[2:5]
	v_mfma_f32_16x16x32_bf16 v[2:5], v[62:65], v[246:249], v[12:15]
	v_mfma_f32_16x16x32_bf16 v[20:23], v[210:213], v[242:245], v[20:23]
	v_mfma_f32_16x16x32_bf16 v[4:7], v[210:213], v[250:253], v[2:5]
	v_mfma_f32_16x16x32_bf16 v[12:15], v[214:217], v[32:35], v[182:185]
	v_mfma_f32_16x16x32_bf16 v[64:67], v[218:221], v[44:47], v[12:15]
	v_mfma_f32_16x16x32_bf16 v[12:15], v[222:225], v[32:35], v[186:189]
	v_mfma_f32_16x16x32_bf16 v[60:63], v[226:229], v[44:47], v[12:15]
	v_mfma_f32_16x16x32_bf16 v[12:15], v[214:217], v[230:233], v[190:193]
	v_mfma_f32_16x16x32_bf16 v[48:51], v[218:221], v[234:237], v[12:15]
	v_mfma_f32_16x16x32_bf16 v[12:15], v[222:225], v[230:233], v[194:197]
	v_mfma_f32_16x16x32_bf16 v[44:47], v[226:229], v[234:237], v[12:15]
	v_mfma_f32_16x16x32_bf16 v[12:15], v[214:217], v[238:241], v[198:201]
	v_mfma_f32_16x16x32_bf16 v[32:35], v[218:221], v[242:245], v[12:15]
	v_mfma_f32_16x16x32_bf16 v[12:15], v[222:225], v[238:241], v[202:205]
	v_mfma_f32_16x16x32_bf16 v[28:31], v[226:229], v[242:245], v[12:15]
	v_mfma_f32_16x16x32_bf16 v[12:15], v[214:217], v[246:249], v[16:19]
	v_mfma_f32_16x16x32_bf16 v[16:19], v[218:221], v[250:253], v[12:15]
	v_mfma_f32_16x16x32_bf16 v[12:15], v[222:225], v[246:249], v[206:209]
	v_mfma_f32_16x16x32_bf16 v[12:15], v[226:229], v[250:253], v[12:15]
	s_barrier
	s_setprio 0
	s_mov_b32 s22, 2
	s_branch .LBB0_667

.LBB0_668:
	ds_read_b128 v[158:161], v155
	ds_read_b128 v[162:165], v155 offset:1024
	ds_read_b128 v[166:169], v155 offset:2048
	ds_read_b128 v[170:173], v155 offset:3072
	ds_read_b128 v[174:177], v156
	ds_read_b128 v[178:181], v156 offset:1024
	ds_read_b128 v[182:185], v156 offset:2048
	ds_read_b128 v[186:189], v156 offset:3072
	s_add_u32 s12, s70, s34
	s_addc_u32 s13, s71, 0
	s_cmp_eq_u32 s34, s6
	s_cselect_b32 s23, s0, s13
	s_cselect_b32 s22, s1, s12
	s_cselect_b32 s55, s43, s69
	s_cselect_b32 s54, s66, s68
	s_add_i32 s73, s21, 0xc000
	v_lshl_add_u64 v[144:145], v[2:3], 0, s[34:35]
	s_mov_b32 m0, s73
	s_add_i32 s72, s21, 0xe000
	ds_read_b128 v[190:193], v157
	ds_read_b128 v[194:197], v157 offset:1024
	ds_read_b128 v[198:201], v157 offset:2048
	ds_read_b128 v[202:205], v157 offset:3072
	ds_read_b128 v[206:209], v157 offset:4096
	ds_read_b128 v[210:213], v157 offset:5120
	ds_read_b128 v[214:217], v157 offset:6144
	ds_read_b128 v[218:221], v157 offset:7168
	global_load_lds_dwordx4 v[144:145], off
	v_lshl_add_u64 v[144:145], v[148:149], 0, s[34:35]
	s_mov_b32 m0, s72
	s_nop 0
	global_load_lds_dwordx4 v[144:145], off
	s_waitcnt vmcnt(8)
	s_waitcnt lgkmcnt(0)
	s_setprio 1
	s_barrier
	v_mfma_f32_16x16x32_bf16 v[120:123], v[158:161], v[190:193], v[120:123]
	v_mfma_f32_16x16x32_bf16 v[116:119], v[166:169], v[190:193], v[116:119]
	v_mfma_f32_16x16x32_bf16 v[104:107], v[158:161], v[198:201], v[104:107]
	v_mfma_f32_16x16x32_bf16 v[100:103], v[166:169], v[198:201], v[100:103]
	v_mfma_f32_16x16x32_bf16 v[88:91], v[158:161], v[206:209], v[88:91]
	v_mfma_f32_16x16x32_bf16 v[84:87], v[166:169], v[206:209], v[84:87]
	v_mfma_f32_16x16x32_bf16 v[72:75], v[158:161], v[214:217], v[72:75]
	v_mfma_f32_16x16x32_bf16 v[68:71], v[166:169], v[214:217], v[68:71]
	v_mfma_f32_16x16x32_bf16 v[120:123], v[162:165], v[194:197], v[120:123]
	v_mfma_f32_16x16x32_bf16 v[116:119], v[170:173], v[194:197], v[116:119]
	v_mfma_f32_16x16x32_bf16 v[104:107], v[162:165], v[202:205], v[104:107]
	v_mfma_f32_16x16x32_bf16 v[100:103], v[170:173], v[202:205], v[100:103]
	v_mfma_f32_16x16x32_bf16 v[88:91], v[162:165], v[210:213], v[88:91]
	v_mfma_f32_16x16x32_bf16 v[84:87], v[170:173], v[210:213], v[84:87]
	v_mfma_f32_16x16x32_bf16 v[72:75], v[162:165], v[218:221], v[72:75]
	v_mfma_f32_16x16x32_bf16 v[68:71], v[170:173], v[218:221], v[68:71]
	v_mfma_f32_16x16x32_bf16 v[128:131], v[174:177], v[190:193], v[128:131]
	v_mfma_f32_16x16x32_bf16 v[124:127], v[182:185], v[190:193], v[124:127]
	v_mfma_f32_16x16x32_bf16 v[112:115], v[174:177], v[198:201], v[112:115]
	v_mfma_f32_16x16x32_bf16 v[108:111], v[182:185], v[198:201], v[108:111]
	v_mfma_f32_16x16x32_bf16 v[96:99], v[174:177], v[206:209], v[96:99]
	v_mfma_f32_16x16x32_bf16 v[92:95], v[182:185], v[206:209], v[92:95]
	v_mfma_f32_16x16x32_bf16 v[80:83], v[174:177], v[214:217], v[80:83]
	v_mfma_f32_16x16x32_bf16 v[76:79], v[182:185], v[214:217], v[76:79]
	v_mfma_f32_16x16x32_bf16 v[128:131], v[178:181], v[194:197], v[128:131]
	v_mfma_f32_16x16x32_bf16 v[124:127], v[186:189], v[194:197], v[124:127]
	v_mfma_f32_16x16x32_bf16 v[112:115], v[178:181], v[202:205], v[112:115]
	v_mfma_f32_16x16x32_bf16 v[108:111], v[186:189], v[202:205], v[108:111]
	v_mfma_f32_16x16x32_bf16 v[96:99], v[178:181], v[210:213], v[96:99]
	v_mfma_f32_16x16x32_bf16 v[92:95], v[186:189], v[210:213], v[92:95]
	v_mfma_f32_16x16x32_bf16 v[80:83], v[178:181], v[218:221], v[80:83]
	v_mfma_f32_16x16x32_bf16 v[76:79], v[186:189], v[218:221], v[76:79]
	s_barrier
	s_setprio 0
	s_add_i32 s12, s58, s20
	v_lshl_add_u64 v[144:145], s[54:55], 0, v[134:135]
	s_mov_b32 m0, s12
	ds_read_b128 v[190:193], v157 offset:16384
	ds_read_b128 v[194:197], v157 offset:17408
	ds_read_b128 v[198:201], v157 offset:18432
	ds_read_b128 v[202:205], v157 offset:19456
	ds_read_b128 v[206:209], v157 offset:20480
	ds_read_b128 v[210:213], v157 offset:21504
	ds_read_b128 v[214:217], v157 offset:22528
	ds_read_b128 v[218:221], v157 offset:23552
	global_load_lds_dwordx4 v[144:145], off
	s_add_i32 m0, s12, 0x2000
	s_add_u32 s12, s54, 0x4000
	v_lshl_add_u64 v[144:145], s[54:55], 0, v[138:139]
	s_addc_u32 s13, s55, 0
	s_add_i32 s14, s59, s20
	global_load_lds_dwordx4 v[144:145], off
	v_lshl_add_u64 v[144:145], s[12:13], 0, v[134:135]
	s_mov_b32 m0, s14
	v_lshl_add_u64 v[222:223], s[22:23], 0, v[136:137]
	global_load_lds_dwordx4 v[144:145], off
	v_lshl_add_u64 v[144:145], s[12:13], 0, v[138:139]
	s_add_i32 m0, s14, 0x2000
	s_nop 0
	global_load_lds_dwordx4 v[144:145], off
	v_lshl_add_u64 v[144:145], s[22:23], 0, v[132:133]
	s_mov_b32 m0, s21
	s_nop 0
	global_load_lds_dwordx4 v[144:145], off
	s_mov_b32 m0, s24
	s_nop 0
	global_load_lds_dwordx4 v[222:223], off
	s_waitcnt vmcnt(8)
	s_waitcnt lgkmcnt(0)
	s_setprio 1
	s_barrier
	v_mfma_f32_16x16x32_bf16 v[56:59], v[158:161], v[190:193], v[56:59]
	v_mfma_f32_16x16x32_bf16 v[52:55], v[166:169], v[190:193], v[52:55]
	v_mfma_f32_16x16x32_bf16 v[40:43], v[158:161], v[198:201], v[40:43]
	v_mfma_f32_16x16x32_bf16 v[36:39], v[166:169], v[198:201], v[36:39]
	v_mfma_f32_16x16x32_bf16 v[24:27], v[158:161], v[206:209], v[24:27]
	v_mfma_f32_16x16x32_bf16 v[20:23], v[166:169], v[206:209], v[20:23]
	v_mfma_f32_16x16x32_bf16 v[8:11], v[158:161], v[214:217], v[8:11]
	v_mfma_f32_16x16x32_bf16 v[4:7], v[166:169], v[214:217], v[4:7]
	v_mfma_f32_16x16x32_bf16 v[56:59], v[162:165], v[194:197], v[56:59]
	v_mfma_f32_16x16x32_bf16 v[52:55], v[170:173], v[194:197], v[52:55]
	v_mfma_f32_16x16x32_bf16 v[40:43], v[162:165], v[202:205], v[40:43]
	v_mfma_f32_16x16x32_bf16 v[36:39], v[170:173], v[202:205], v[36:39]
	v_mfma_f32_16x16x32_bf16 v[24:27], v[162:165], v[210:213], v[24:27]
	v_mfma_f32_16x16x32_bf16 v[20:23], v[170:173], v[210:213], v[20:23]
	v_mfma_f32_16x16x32_bf16 v[8:11], v[162:165], v[218:221], v[8:11]
	v_mfma_f32_16x16x32_bf16 v[4:7], v[170:173], v[218:221], v[4:7]
	v_mfma_f32_16x16x32_bf16 v[64:67], v[174:177], v[190:193], v[64:67]
	v_mfma_f32_16x16x32_bf16 v[60:63], v[182:185], v[190:193], v[60:63]
	v_mfma_f32_16x16x32_bf16 v[48:51], v[174:177], v[198:201], v[48:51]
	v_mfma_f32_16x16x32_bf16 v[44:47], v[182:185], v[198:201], v[44:47]
	v_mfma_f32_16x16x32_bf16 v[32:35], v[174:177], v[206:209], v[32:35]
	v_mfma_f32_16x16x32_bf16 v[28:31], v[182:185], v[206:209], v[28:31]
	v_mfma_f32_16x16x32_bf16 v[16:19], v[174:177], v[214:217], v[16:19]
	v_mfma_f32_16x16x32_bf16 v[12:15], v[182:185], v[214:217], v[12:15]
	v_mfma_f32_16x16x32_bf16 v[64:67], v[178:181], v[194:197], v[64:67]
	v_mfma_f32_16x16x32_bf16 v[60:63], v[186:189], v[194:197], v[60:63]
	v_mfma_f32_16x16x32_bf16 v[48:51], v[178:181], v[202:205], v[48:51]
	v_mfma_f32_16x16x32_bf16 v[44:47], v[186:189], v[202:205], v[44:47]
	v_mfma_f32_16x16x32_bf16 v[32:35], v[178:181], v[210:213], v[32:35]
	v_mfma_f32_16x16x32_bf16 v[28:31], v[186:189], v[210:213], v[28:31]
	v_mfma_f32_16x16x32_bf16 v[16:19], v[178:181], v[218:221], v[16:19]
	v_mfma_f32_16x16x32_bf16 v[12:15], v[186:189], v[218:221], v[12:15]
	s_barrier
	s_setprio 0
	s_add_i32 s14, 0, 0x18000
	v_add_u32_e32 v1, s14, v152
	s_add_i32 s74, 0, 0x1c000
	ds_read_b128 v[158:161], v1
	ds_read_b128 v[162:165], v1 offset:1024
	ds_read_b128 v[166:169], v1 offset:2048
	ds_read_b128 v[170:173], v1 offset:3072
	v_add_u32_e32 v1, s74, v152
	ds_read_b128 v[174:177], v1
	ds_read_b128 v[178:181], v1 offset:1024
	ds_read_b128 v[182:185], v1 offset:2048
	ds_read_b128 v[186:189], v1 offset:3072
	s_add_u32 s12, s22, 0x100000
	s_addc_u32 s13, s23, 0
	s_mov_b32 m0, s25
	v_lshl_add_u64 v[224:225], s[12:13], 0, v[132:133]
	ds_read_b128 v[190:193], v157 offset:32768
	ds_read_b128 v[194:197], v157 offset:33792
	ds_read_b128 v[198:201], v157 offset:34816
	ds_read_b128 v[202:205], v157 offset:35840
	ds_read_b128 v[206:209], v157 offset:36864
	ds_read_b128 v[210:213], v157 offset:37888
	ds_read_b128 v[214:217], v157 offset:38912
	ds_read_b128 v[218:221], v157 offset:39936
	global_load_lds_dwordx4 v[224:225], off
	v_lshl_add_u64 v[224:225], s[12:13], 0, v[136:137]
	s_mov_b32 m0, s33
	s_nop 0
	global_load_lds_dwordx4 v[224:225], off
	s_waitcnt vmcnt(8)
	s_waitcnt lgkmcnt(0)
	s_setprio 1
	s_barrier
	v_mfma_f32_16x16x32_bf16 v[120:123], v[158:161], v[190:193], v[120:123]
	v_mfma_f32_16x16x32_bf16 v[116:119], v[166:169], v[190:193], v[116:119]
	v_mfma_f32_16x16x32_bf16 v[104:107], v[158:161], v[198:201], v[104:107]
	v_mfma_f32_16x16x32_bf16 v[100:103], v[166:169], v[198:201], v[100:103]
	v_mfma_f32_16x16x32_bf16 v[88:91], v[158:161], v[206:209], v[88:91]
	v_mfma_f32_16x16x32_bf16 v[84:87], v[166:169], v[206:209], v[84:87]
	v_mfma_f32_16x16x32_bf16 v[72:75], v[158:161], v[214:217], v[72:75]
	v_mfma_f32_16x16x32_bf16 v[68:71], v[166:169], v[214:217], v[68:71]
	v_mfma_f32_16x16x32_bf16 v[120:123], v[162:165], v[194:197], v[120:123]
	v_mfma_f32_16x16x32_bf16 v[116:119], v[170:173], v[194:197], v[116:119]
	v_mfma_f32_16x16x32_bf16 v[104:107], v[162:165], v[202:205], v[104:107]
	v_mfma_f32_16x16x32_bf16 v[100:103], v[170:173], v[202:205], v[100:103]
	v_mfma_f32_16x16x32_bf16 v[88:91], v[162:165], v[210:213], v[88:91]
	v_mfma_f32_16x16x32_bf16 v[84:87], v[170:173], v[210:213], v[84:87]
	v_mfma_f32_16x16x32_bf16 v[72:75], v[162:165], v[218:221], v[72:75]
	v_mfma_f32_16x16x32_bf16 v[68:71], v[170:173], v[218:221], v[68:71]
	v_mfma_f32_16x16x32_bf16 v[128:131], v[174:177], v[190:193], v[128:131]
	v_mfma_f32_16x16x32_bf16 v[124:127], v[182:185], v[190:193], v[124:127]
	v_mfma_f32_16x16x32_bf16 v[112:115], v[174:177], v[198:201], v[112:115]
	v_mfma_f32_16x16x32_bf16 v[108:111], v[182:185], v[198:201], v[108:111]
	v_mfma_f32_16x16x32_bf16 v[96:99], v[174:177], v[206:209], v[96:99]
	v_mfma_f32_16x16x32_bf16 v[92:95], v[182:185], v[206:209], v[92:95]
	v_mfma_f32_16x16x32_bf16 v[80:83], v[174:177], v[214:217], v[80:83]
	v_mfma_f32_16x16x32_bf16 v[76:79], v[182:185], v[214:217], v[76:79]
	v_mfma_f32_16x16x32_bf16 v[128:131], v[178:181], v[194:197], v[128:131]
	v_mfma_f32_16x16x32_bf16 v[124:127], v[186:189], v[194:197], v[124:127]
	v_mfma_f32_16x16x32_bf16 v[112:115], v[178:181], v[202:205], v[112:115]
	v_mfma_f32_16x16x32_bf16 v[108:111], v[186:189], v[202:205], v[108:111]
	v_mfma_f32_16x16x32_bf16 v[96:99], v[178:181], v[210:213], v[96:99]
	v_mfma_f32_16x16x32_bf16 v[92:95], v[186:189], v[210:213], v[92:95]
	v_mfma_f32_16x16x32_bf16 v[80:83], v[178:181], v[218:221], v[80:83]
	v_mfma_f32_16x16x32_bf16 v[76:79], v[186:189], v[218:221], v[76:79]
	s_barrier
	s_setprio 0
	s_add_u32 s12, s54, 0x8000
	s_addc_u32 s13, s55, 0
	s_add_i32 s14, s14, s20
	v_lshl_add_u64 v[224:225], s[12:13], 0, v[134:135]
	s_mov_b32 m0, s14
	ds_read_b128 v[190:193], v157 offset:49152
	ds_read_b128 v[194:197], v157 offset:50176
	ds_read_b128 v[198:201], v157 offset:51200
	ds_read_b128 v[202:205], v157 offset:52224
	ds_read_b128 v[206:209], v157 offset:53248
	ds_read_b128 v[210:213], v157 offset:54272
	ds_read_b128 v[214:217], v157 offset:55296
	ds_read_b128 v[218:221], v157 offset:56320
	global_load_lds_dwordx4 v[224:225], off
	s_add_i32 m0, s14, 0x2000
	v_lshl_add_u64 v[224:225], s[12:13], 0, v[138:139]
	s_add_u32 s12, s54, 0xc000
	s_addc_u32 s13, s55, 0
	s_add_i32 s14, s74, s20
	global_load_lds_dwordx4 v[224:225], off
	v_lshl_add_u64 v[224:225], s[12:13], 0, v[134:135]
	s_mov_b32 m0, s14
	v_lshl_add_u64 v[144:145], v[144:145], 0, s[30:31]
	global_load_lds_dwordx4 v[224:225], off
	v_lshl_add_u64 v[224:225], s[12:13], 0, v[138:139]
	s_add_i32 m0, s14, 0x2000
	s_nop 0
	global_load_lds_dwordx4 v[224:225], off
	s_mov_b32 m0, s51
	s_nop 0
	global_load_lds_dwordx4 v[144:145], off
	v_lshl_add_u64 v[144:145], v[222:223], 0, s[30:31]
	s_mov_b32 m0, s53
	s_nop 0
	global_load_lds_dwordx4 v[144:145], off
	s_waitcnt vmcnt(8)
	s_waitcnt lgkmcnt(0)
	s_setprio 1
	s_barrier
	v_mfma_f32_16x16x32_bf16 v[56:59], v[158:161], v[190:193], v[56:59]
	v_mfma_f32_16x16x32_bf16 v[52:55], v[166:169], v[190:193], v[52:55]
	v_mfma_f32_16x16x32_bf16 v[40:43], v[158:161], v[198:201], v[40:43]
	v_mfma_f32_16x16x32_bf16 v[36:39], v[166:169], v[198:201], v[36:39]
	v_mfma_f32_16x16x32_bf16 v[24:27], v[158:161], v[206:209], v[24:27]
	v_mfma_f32_16x16x32_bf16 v[20:23], v[166:169], v[206:209], v[20:23]
	v_mfma_f32_16x16x32_bf16 v[8:11], v[158:161], v[214:217], v[8:11]
	v_mfma_f32_16x16x32_bf16 v[4:7], v[166:169], v[214:217], v[4:7]
	v_mfma_f32_16x16x32_bf16 v[56:59], v[162:165], v[194:197], v[56:59]
	v_mfma_f32_16x16x32_bf16 v[52:55], v[170:173], v[194:197], v[52:55]
	v_mfma_f32_16x16x32_bf16 v[40:43], v[162:165], v[202:205], v[40:43]
	v_mfma_f32_16x16x32_bf16 v[36:39], v[170:173], v[202:205], v[36:39]
	v_mfma_f32_16x16x32_bf16 v[24:27], v[162:165], v[210:213], v[24:27]
	v_mfma_f32_16x16x32_bf16 v[20:23], v[170:173], v[210:213], v[20:23]
	v_mfma_f32_16x16x32_bf16 v[8:11], v[162:165], v[218:221], v[8:11]
	v_mfma_f32_16x16x32_bf16 v[4:7], v[170:173], v[218:221], v[4:7]
	v_mfma_f32_16x16x32_bf16 v[64:67], v[174:177], v[190:193], v[64:67]
	v_mfma_f32_16x16x32_bf16 v[60:63], v[182:185], v[190:193], v[60:63]
	v_mfma_f32_16x16x32_bf16 v[48:51], v[174:177], v[198:201], v[48:51]
	v_mfma_f32_16x16x32_bf16 v[44:47], v[182:185], v[198:201], v[44:47]
	v_mfma_f32_16x16x32_bf16 v[32:35], v[174:177], v[206:209], v[32:35]
	v_mfma_f32_16x16x32_bf16 v[28:31], v[182:185], v[206:209], v[28:31]
	v_mfma_f32_16x16x32_bf16 v[16:19], v[174:177], v[214:217], v[16:19]
	v_mfma_f32_16x16x32_bf16 v[12:15], v[182:185], v[214:217], v[12:15]
	v_mfma_f32_16x16x32_bf16 v[64:67], v[178:181], v[194:197], v[64:67]
	v_mfma_f32_16x16x32_bf16 v[60:63], v[186:189], v[194:197], v[60:63]
	v_mfma_f32_16x16x32_bf16 v[48:51], v[178:181], v[202:205], v[48:51]
	v_mfma_f32_16x16x32_bf16 v[44:47], v[186:189], v[202:205], v[44:47]
	v_mfma_f32_16x16x32_bf16 v[32:35], v[178:181], v[210:213], v[32:35]
	v_mfma_f32_16x16x32_bf16 v[28:31], v[186:189], v[210:213], v[28:31]
	v_mfma_f32_16x16x32_bf16 v[16:19], v[178:181], v[218:221], v[16:19]
	v_mfma_f32_16x16x32_bf16 v[12:15], v[186:189], v[218:221], v[12:15]
	s_barrier
	s_setprio 0
	s_add_i32 s67, s67, 2
	s_add_u32 s68, s68, 0x10000
	s_addc_u32 s69, s69, 0
	s_add_u32 s70, s70, 0x100
	s_addc_u32 s71, s71, 0
	s_add_u32 s6, s6, 0xffffff00
	s_addc_u32 s7, s7, -1
	v_lshl_add_u64 v[2:3], v[2:3], 0, s[38:39]
	s_cmp_gt_u32 s67, 61
	v_lshl_add_u64 v[148:149], v[148:149], 0, s[38:39]
	s_cbranch_scc0 .LBB0_668
	s_and_b64 vcc, exec, s[36:37]
	s_cbranch_vccnz .LBB0_676
	s_and_b64 s[0:1], s[10:11], s[4:5]
	s_andn2_b64 vcc, exec, s[0:1]
	s_cbranch_vccz .LBB0_677

.LBB0_757:
	ds_read_b128 v[2:5], v153
	ds_read_b128 v[6:9], v153 offset:1024
	ds_read_b128 v[10:13], v153 offset:2048
	ds_read_b128 v[14:17], v153 offset:3072
	ds_read_b128 v[18:21], v154
	ds_read_b128 v[22:25], v154 offset:1024
	ds_read_b128 v[26:29], v154 offset:2048
	ds_read_b128 v[30:33], v154 offset:3072
	s_add_u32 s0, s50, 0x10000
	s_addc_u32 s1, s51, 0
	ds_read_b128 v[34:37], v155
	ds_read_b128 v[38:41], v155 offset:1024
	ds_read_b128 v[42:45], v155 offset:2048
	ds_read_b128 v[46:49], v155 offset:3072
	ds_read_b128 v[50:53], v155 offset:4096
	ds_read_b128 v[54:57], v155 offset:5120
	ds_read_b128 v[58:61], v155 offset:6144
	ds_read_b128 v[62:65], v155 offset:7168
	s_waitcnt vmcnt(24)
	s_waitcnt lgkmcnt(0)
	s_setprio 1
	s_barrier
	v_mfma_f32_16x16x32_bf16 v[66:69], v[2:5], v[34:37], 0
	v_mfma_f32_16x16x32_bf16 v[70:73], v[10:13], v[34:37], 0
	v_mfma_f32_16x16x32_bf16 v[74:77], v[2:5], v[42:45], 0
	v_mfma_f32_16x16x32_bf16 v[78:81], v[10:13], v[42:45], 0
	v_mfma_f32_16x16x32_bf16 v[82:85], v[2:5], v[50:53], 0
	v_mfma_f32_16x16x32_bf16 v[86:89], v[10:13], v[50:53], 0
	v_mfma_f32_16x16x32_bf16 v[90:93], v[2:5], v[58:61], 0
	v_mfma_f32_16x16x32_bf16 v[94:97], v[10:13], v[58:61], 0
	v_mfma_f32_16x16x32_bf16 v[66:69], v[6:9], v[38:41], v[66:69]
	v_mfma_f32_16x16x32_bf16 v[70:73], v[14:17], v[38:41], v[70:73]
	v_mfma_f32_16x16x32_bf16 v[74:77], v[6:9], v[46:49], v[74:77]
	v_mfma_f32_16x16x32_bf16 v[78:81], v[14:17], v[46:49], v[78:81]
	v_mfma_f32_16x16x32_bf16 v[82:85], v[6:9], v[54:57], v[82:85]
	v_mfma_f32_16x16x32_bf16 v[86:89], v[14:17], v[54:57], v[86:89]
	v_mfma_f32_16x16x32_bf16 v[90:93], v[6:9], v[62:65], v[90:93]
	v_mfma_f32_16x16x32_bf16 v[104:107], v[14:17], v[62:65], v[94:97]
	v_mfma_f32_16x16x32_bf16 v[94:97], v[18:21], v[34:37], 0
	v_mfma_f32_16x16x32_bf16 v[34:37], v[26:29], v[34:37], 0
	v_mfma_f32_16x16x32_bf16 v[108:111], v[22:25], v[38:41], v[94:97]
	v_mfma_f32_16x16x32_bf16 v[34:37], v[30:33], v[38:41], v[34:37]
	v_mfma_f32_16x16x32_bf16 v[38:41], v[18:21], v[42:45], 0
	v_mfma_f32_16x16x32_bf16 v[42:45], v[26:29], v[42:45], 0
	v_mfma_f32_16x16x32_bf16 v[38:41], v[22:25], v[46:49], v[38:41]
	v_mfma_f32_16x16x32_bf16 v[42:45], v[30:33], v[46:49], v[42:45]
	v_mfma_f32_16x16x32_bf16 v[46:49], v[18:21], v[50:53], 0
	v_mfma_f32_16x16x32_bf16 v[50:53], v[26:29], v[50:53], 0
	v_mfma_f32_16x16x32_bf16 v[46:49], v[22:25], v[54:57], v[46:49]
	v_mfma_f32_16x16x32_bf16 v[50:53], v[30:33], v[54:57], v[50:53]
	v_mfma_f32_16x16x32_bf16 v[54:57], v[18:21], v[58:61], 0
	v_mfma_f32_16x16x32_bf16 v[58:61], v[26:29], v[58:61], 0
	v_mfma_f32_16x16x32_bf16 v[54:57], v[22:25], v[62:65], v[54:57]
	v_mfma_f32_16x16x32_bf16 v[58:61], v[30:33], v[62:65], v[58:61]
	s_barrier
	s_setprio 0
	s_add_i32 s12, s57, s2
	v_lshl_add_u64 v[102:103], s[0:1], 0, v[134:135]
	s_mov_b32 m0, s12
	ds_read_b128 v[62:65], v155 offset:16384
	ds_read_b128 v[94:97], v155 offset:17408
	ds_read_b128 v[98:101], v155 offset:18432
	ds_read_b128 v[112:115], v155 offset:19456
	ds_read_b128 v[116:119], v155 offset:20480
	ds_read_b128 v[120:123], v155 offset:21504
	ds_read_b128 v[124:127], v155 offset:22528
	ds_read_b128 v[128:131], v155 offset:23552
	global_load_lds_dwordx4 v[102:103], off
	s_add_i32 m0, s12, 0x2000
	v_lshl_add_u64 v[102:103], s[0:1], 0, v[138:139]
	s_add_u32 s0, s50, 0x14000
	s_addc_u32 s1, s51, 0
	s_add_i32 s12, s58, s2
	global_load_lds_dwordx4 v[102:103], off
	v_lshl_add_u64 v[102:103], s[0:1], 0, v[134:135]
	s_mov_b32 m0, s12
	v_lshl_add_u64 v[148:149], s[52:53], 0, v[132:133]
	global_load_lds_dwordx4 v[102:103], off
	v_lshl_add_u64 v[102:103], s[0:1], 0, v[138:139]
	s_add_i32 m0, s12, 0x2000
	v_lshl_add_u64 v[144:145], s[52:53], 0, v[136:137]
	global_load_lds_dwordx4 v[102:103], off
	v_lshl_add_u64 v[102:103], v[148:149], 0, s[44:45]
	s_mov_b32 m0, s19
	s_nop 0
	global_load_lds_dwordx4 v[102:103], off
	v_lshl_add_u64 v[102:103], v[144:145], 0, s[44:45]
	s_mov_b32 m0, s20
	s_nop 0
	global_load_lds_dwordx4 v[102:103], off
	s_waitcnt vmcnt(24)
	s_waitcnt lgkmcnt(0)
	s_setprio 1
	s_barrier
	v_mfma_f32_16x16x32_bf16 v[158:161], v[2:5], v[62:65], 0
	v_mfma_f32_16x16x32_bf16 v[166:169], v[2:5], v[98:101], 0
	v_mfma_f32_16x16x32_bf16 v[174:177], v[2:5], v[116:119], 0
	v_mfma_f32_16x16x32_bf16 v[2:5], v[2:5], v[124:127], 0
	v_mfma_f32_16x16x32_bf16 v[158:161], v[6:9], v[94:97], v[158:161]
	v_mfma_f32_16x16x32_bf16 v[166:169], v[6:9], v[112:115], v[166:169]
	v_mfma_f32_16x16x32_bf16 v[174:177], v[6:9], v[120:123], v[174:177]
	v_mfma_f32_16x16x32_bf16 v[2:5], v[6:9], v[128:131], v[2:5]
	v_mfma_f32_16x16x32_bf16 v[6:9], v[10:13], v[124:127], 0
	v_mfma_f32_16x16x32_bf16 v[162:165], v[10:13], v[62:65], 0
	v_mfma_f32_16x16x32_bf16 v[170:173], v[10:13], v[98:101], 0
	v_mfma_f32_16x16x32_bf16 v[178:181], v[10:13], v[116:119], 0
	v_mfma_f32_16x16x32_bf16 v[6:9], v[14:17], v[128:131], v[6:9]
	v_mfma_f32_16x16x32_bf16 v[162:165], v[14:17], v[94:97], v[162:165]
	v_mfma_f32_16x16x32_bf16 v[170:173], v[14:17], v[112:115], v[170:173]
	v_mfma_f32_16x16x32_bf16 v[178:181], v[14:17], v[120:123], v[178:181]
	v_mfma_f32_16x16x32_bf16 v[14:17], v[26:29], v[62:65], 0
	v_mfma_f32_16x16x32_bf16 v[182:185], v[30:33], v[94:97], v[14:17]
	v_mfma_f32_16x16x32_bf16 v[14:17], v[18:21], v[98:101], 0
	v_mfma_f32_16x16x32_bf16 v[186:189], v[22:25], v[112:115], v[14:17]
	v_mfma_f32_16x16x32_bf16 v[14:17], v[26:29], v[98:101], 0
	v_mfma_f32_16x16x32_bf16 v[190:193], v[30:33], v[112:115], v[14:17]
	v_mfma_f32_16x16x32_bf16 v[14:17], v[18:21], v[116:119], 0
	v_mfma_f32_16x16x32_bf16 v[194:197], v[22:25], v[120:123], v[14:17]
	v_mfma_f32_16x16x32_bf16 v[14:17], v[26:29], v[116:119], 0
	v_mfma_f32_16x16x32_bf16 v[10:13], v[18:21], v[62:65], 0
	v_mfma_f32_16x16x32_bf16 v[198:201], v[30:33], v[120:123], v[14:17]
	v_mfma_f32_16x16x32_bf16 v[14:17], v[18:21], v[124:127], 0
	v_mfma_f32_16x16x32_bf16 v[10:13], v[22:25], v[94:97], v[10:13]
	v_mfma_f32_16x16x32_bf16 v[202:205], v[22:25], v[128:131], v[14:17]
	v_mfma_f32_16x16x32_bf16 v[14:17], v[26:29], v[124:127], 0
	v_mfma_f32_16x16x32_bf16 v[206:209], v[30:33], v[128:131], v[14:17]
	s_barrier
	s_setprio 0
	s_add_i32 s12, 0, 0x18000
	v_add_u32_e32 v1, s12, v151
	s_add_i32 s13, 0, 0x1c000
	s_nop 1
	ds_read_b128 v[14:17], v1
	ds_read_b128 v[24:27], v1 offset:1024
	ds_read_b128 v[28:31], v1 offset:2048
	ds_read_b128 v[210:213], v1 offset:3072
	v_add_u32_e32 v1, s13, v151
	ds_read_b128 v[214:217], v1
	ds_read_b128 v[218:221], v1 offset:1024
	ds_read_b128 v[222:225], v1 offset:2048
	ds_read_b128 v[226:229], v1 offset:3072
	s_add_u32 s0, s52, 0x2b0100
	s_addc_u32 s1, s53, 0
	s_mov_b32 m0, s21
	v_lshl_add_u64 v[22:23], s[0:1], 0, v[132:133]
	ds_read_b128 v[18:21], v155 offset:32768
	ds_read_b128 v[120:123], v155 offset:33792
	ds_read_b128 v[230:233], v155 offset:34816
	ds_read_b128 v[234:237], v155 offset:35840
	ds_read_b128 v[238:241], v155 offset:36864
	ds_read_b128 v[242:245], v155 offset:37888
	ds_read_b128 v[246:249], v155 offset:38912
	ds_read_b128 v[250:253], v155 offset:39936
	global_load_lds_dwordx4 v[22:23], off
	v_lshl_add_u64 v[22:23], s[0:1], 0, v[136:137]
	s_mov_b32 m0, s24
	s_nop 0
	global_load_lds_dwordx4 v[22:23], off
	s_waitcnt vmcnt(24)
	s_waitcnt lgkmcnt(0)
	s_setprio 1
	s_barrier
	v_mfma_f32_16x16x32_bf16 v[62:65], v[14:17], v[18:21], v[66:69]
	v_mfma_f32_16x16x32_bf16 v[128:131], v[24:27], v[120:123], v[62:65]
	v_mfma_f32_16x16x32_bf16 v[62:65], v[28:31], v[18:21], v[70:73]
	v_mfma_f32_16x16x32_bf16 v[116:119], v[210:213], v[120:123], v[62:65]
	v_mfma_f32_16x16x32_bf16 v[62:65], v[14:17], v[230:233], v[74:77]
	v_mfma_f32_16x16x32_bf16 v[112:115], v[24:27], v[234:237], v[62:65]
	v_mfma_f32_16x16x32_bf16 v[62:65], v[28:31], v[230:233], v[78:81]
	v_mfma_f32_16x16x32_bf16 v[100:103], v[210:213], v[234:237], v[62:65]
	v_mfma_f32_16x16x32_bf16 v[62:65], v[14:17], v[238:241], v[82:85]
	v_mfma_f32_16x16x32_bf16 v[96:99], v[24:27], v[242:245], v[62:65]
	v_mfma_f32_16x16x32_bf16 v[62:65], v[28:31], v[238:241], v[86:89]
	v_mfma_f32_16x16x32_bf16 v[84:87], v[210:213], v[242:245], v[62:65]
	v_mfma_f32_16x16x32_bf16 v[62:65], v[14:17], v[246:249], v[90:93]
	v_mfma_f32_16x16x32_bf16 v[80:83], v[24:27], v[250:253], v[62:65]
	v_mfma_f32_16x16x32_bf16 v[62:65], v[28:31], v[246:249], v[104:107]
	v_mfma_f32_16x16x32_bf16 v[64:67], v[210:213], v[250:253], v[62:65]
	v_mfma_f32_16x16x32_bf16 v[68:71], v[214:217], v[18:21], v[108:111]
	v_mfma_f32_16x16x32_bf16 v[18:21], v[222:225], v[18:21], v[34:37]
	v_mfma_f32_16x16x32_bf16 v[124:127], v[218:221], v[120:123], v[68:71]
	v_mfma_f32_16x16x32_bf16 v[120:123], v[226:229], v[120:123], v[18:21]
	v_mfma_f32_16x16x32_bf16 v[18:21], v[214:217], v[230:233], v[38:41]
	v_mfma_f32_16x16x32_bf16 v[108:111], v[218:221], v[234:237], v[18:21]
	v_mfma_f32_16x16x32_bf16 v[18:21], v[222:225], v[230:233], v[42:45]
	v_mfma_f32_16x16x32_bf16 v[104:107], v[226:229], v[234:237], v[18:21]
	v_mfma_f32_16x16x32_bf16 v[18:21], v[214:217], v[238:241], v[46:49]
	v_mfma_f32_16x16x32_bf16 v[92:95], v[218:221], v[242:245], v[18:21]
	v_mfma_f32_16x16x32_bf16 v[18:21], v[222:225], v[238:241], v[50:53]
	v_mfma_f32_16x16x32_bf16 v[88:91], v[226:229], v[242:245], v[18:21]
	v_mfma_f32_16x16x32_bf16 v[18:21], v[214:217], v[246:249], v[54:57]
	v_mfma_f32_16x16x32_bf16 v[72:75], v[218:221], v[250:253], v[18:21]
	v_mfma_f32_16x16x32_bf16 v[18:21], v[222:225], v[246:249], v[58:61]
	v_mfma_f32_16x16x32_bf16 v[68:71], v[226:229], v[250:253], v[18:21]
	s_barrier
	s_setprio 0
	s_add_u32 s0, s50, 0x18000
	s_addc_u32 s1, s51, 0
	s_add_i32 s12, s12, s2
	s_nop 1
	v_lshl_add_u64 v[18:19], s[0:1], 0, v[134:135]
	s_mov_b32 m0, s12
	ds_read_b128 v[40:43], v155 offset:49152
	ds_read_b128 v[44:47], v155 offset:50176
	ds_read_b128 v[230:233], v155 offset:51200
	ds_read_b128 v[234:237], v155 offset:52224
	ds_read_b128 v[238:241], v155 offset:53248
	ds_read_b128 v[242:245], v155 offset:54272
	ds_read_b128 v[246:249], v155 offset:55296
	ds_read_b128 v[250:253], v155 offset:56320
	global_load_lds_dwordx4 v[18:19], off
	s_add_i32 m0, s12, 0x2000
	v_lshl_add_u64 v[18:19], s[0:1], 0, v[138:139]
	s_add_u32 s0, s50, 0x1c000
	s_addc_u32 s1, s51, 0
	s_add_i32 s12, s13, s2
	global_load_lds_dwordx4 v[18:19], off
	v_lshl_add_u64 v[18:19], s[0:1], 0, v[134:135]
	s_mov_b32 m0, s12
	s_nop 0
	global_load_lds_dwordx4 v[18:19], off
	v_lshl_add_u64 v[18:19], s[0:1], 0, v[138:139]
	s_add_i32 m0, s12, 0x2000
	s_nop 0
	global_load_lds_dwordx4 v[18:19], off
	v_lshl_add_u64 v[18:19], v[148:149], 0, s[46:47]
	s_mov_b32 m0, s33
	s_nop 0
	global_load_lds_dwordx4 v[18:19], off
	v_lshl_add_u64 v[18:19], v[144:145], 0, s[46:47]
	s_mov_b32 m0, s54
	s_nop 0
	global_load_lds_dwordx4 v[18:19], off
	s_waitcnt vmcnt(8)
	s_waitcnt lgkmcnt(0)
	s_setprio 1
	s_barrier
	v_mfma_f32_16x16x32_bf16 v[18:21], v[14:17], v[40:43], v[158:161]
	v_mfma_f32_16x16x32_bf16 v[76:79], v[24:27], v[44:47], v[18:21]
	v_mfma_f32_16x16x32_bf16 v[18:21], v[28:31], v[40:43], v[162:165]
	v_mfma_f32_16x16x32_bf16 v[52:55], v[210:213], v[44:47], v[18:21]
	v_mfma_f32_16x16x32_bf16 v[18:21], v[14:17], v[230:233], v[166:169]
	v_mfma_f32_16x16x32_bf16 v[48:51], v[24:27], v[234:237], v[18:21]
	v_mfma_f32_16x16x32_bf16 v[18:21], v[28:31], v[230:233], v[170:173]
	v_mfma_f32_16x16x32_bf16 v[36:39], v[210:213], v[234:237], v[18:21]
	v_mfma_f32_16x16x32_bf16 v[18:21], v[14:17], v[238:241], v[174:177]
	v_mfma_f32_16x16x32_bf16 v[32:35], v[24:27], v[242:245], v[18:21]
	v_mfma_f32_16x16x32_bf16 v[18:21], v[28:31], v[238:241], v[178:181]
	v_mfma_f32_16x16x32_bf16 v[2:5], v[14:17], v[246:249], v[2:5]
	v_mfma_f32_16x16x32_bf16 v[20:23], v[210:213], v[242:245], v[18:21]
	v_mfma_f32_16x16x32_bf16 v[16:19], v[24:27], v[250:253], v[2:5]
	v_mfma_f32_16x16x32_bf16 v[2:5], v[28:31], v[246:249], v[6:9]
	v_mfma_f32_16x16x32_bf16 v[4:7], v[210:213], v[250:253], v[2:5]
	v_mfma_f32_16x16x32_bf16 v[8:11], v[214:217], v[40:43], v[10:13]
	v_mfma_f32_16x16x32_bf16 v[60:63], v[218:221], v[44:47], v[8:11]
	v_mfma_f32_16x16x32_bf16 v[8:11], v[222:225], v[40:43], v[182:185]
	v_mfma_f32_16x16x32_bf16 v[56:59], v[226:229], v[44:47], v[8:11]
	v_mfma_f32_16x16x32_bf16 v[8:11], v[214:217], v[230:233], v[186:189]
	v_mfma_f32_16x16x32_bf16 v[44:47], v[218:221], v[234:237], v[8:11]
	v_mfma_f32_16x16x32_bf16 v[8:11], v[222:225], v[230:233], v[190:193]
	v_mfma_f32_16x16x32_bf16 v[40:43], v[226:229], v[234:237], v[8:11]
	v_mfma_f32_16x16x32_bf16 v[8:11], v[214:217], v[238:241], v[194:197]
	v_mfma_f32_16x16x32_bf16 v[28:31], v[218:221], v[242:245], v[8:11]
	v_mfma_f32_16x16x32_bf16 v[8:11], v[222:225], v[238:241], v[198:201]
	v_mfma_f32_16x16x32_bf16 v[24:27], v[226:229], v[242:245], v[8:11]
	v_mfma_f32_16x16x32_bf16 v[8:11], v[214:217], v[246:249], v[202:205]
	v_mfma_f32_16x16x32_bf16 v[12:15], v[218:221], v[250:253], v[8:11]
	v_mfma_f32_16x16x32_bf16 v[8:11], v[222:225], v[246:249], v[206:209]
	v_mfma_f32_16x16x32_bf16 v[8:11], v[226:229], v[250:253], v[8:11]
	s_barrier
	s_setprio 0
	s_mov_b32 s22, 2
	s_branch .LBB0_761

.LBB0_762:
	ds_read_b128 v[158:161], v153
	ds_read_b128 v[162:165], v153 offset:1024
	ds_read_b128 v[166:169], v153 offset:2048
	ds_read_b128 v[170:173], v153 offset:3072
	ds_read_b128 v[174:177], v154
	ds_read_b128 v[178:181], v154 offset:1024
	ds_read_b128 v[182:185], v154 offset:2048
	ds_read_b128 v[186:189], v154 offset:3072
	s_add_u32 s12, s65, s30
	s_addc_u32 s13, s66, 0
	s_cmp_eq_u32 s30, s50
	s_cselect_b32 s23, s11, s13
	s_cselect_b32 s22, s10, s12
	s_cselect_b32 s53, s49, s64
	s_cselect_b32 s52, s48, s1
	s_add_i32 s68, s19, 0xc000
	v_lshl_add_u64 v[144:145], v[2:3], 0, s[30:31]
	s_mov_b32 m0, s68
	s_add_i32 s67, s19, 0xe000
	ds_read_b128 v[190:193], v155
	ds_read_b128 v[194:197], v155 offset:1024
	ds_read_b128 v[198:201], v155 offset:2048
	ds_read_b128 v[202:205], v155 offset:3072
	ds_read_b128 v[206:209], v155 offset:4096
	ds_read_b128 v[210:213], v155 offset:5120
	ds_read_b128 v[214:217], v155 offset:6144
	ds_read_b128 v[218:221], v155 offset:7168
	global_load_lds_dwordx4 v[144:145], off
	v_lshl_add_u64 v[144:145], v[148:149], 0, s[30:31]
	s_mov_b32 m0, s67
	s_nop 0
	global_load_lds_dwordx4 v[144:145], off
	s_waitcnt vmcnt(8)
	s_waitcnt lgkmcnt(0)
	s_setprio 1
	s_barrier
	v_mfma_f32_16x16x32_bf16 v[128:131], v[158:161], v[190:193], v[128:131]
	v_mfma_f32_16x16x32_bf16 v[116:119], v[166:169], v[190:193], v[116:119]
	v_mfma_f32_16x16x32_bf16 v[112:115], v[158:161], v[198:201], v[112:115]
	v_mfma_f32_16x16x32_bf16 v[100:103], v[166:169], v[198:201], v[100:103]
	v_mfma_f32_16x16x32_bf16 v[96:99], v[158:161], v[206:209], v[96:99]
	v_mfma_f32_16x16x32_bf16 v[84:87], v[166:169], v[206:209], v[84:87]
	v_mfma_f32_16x16x32_bf16 v[80:83], v[158:161], v[214:217], v[80:83]
	v_mfma_f32_16x16x32_bf16 v[64:67], v[166:169], v[214:217], v[64:67]
	v_mfma_f32_16x16x32_bf16 v[128:131], v[162:165], v[194:197], v[128:131]
	v_mfma_f32_16x16x32_bf16 v[116:119], v[170:173], v[194:197], v[116:119]
	v_mfma_f32_16x16x32_bf16 v[112:115], v[162:165], v[202:205], v[112:115]
	v_mfma_f32_16x16x32_bf16 v[100:103], v[170:173], v[202:205], v[100:103]
	v_mfma_f32_16x16x32_bf16 v[96:99], v[162:165], v[210:213], v[96:99]
	v_mfma_f32_16x16x32_bf16 v[84:87], v[170:173], v[210:213], v[84:87]
	v_mfma_f32_16x16x32_bf16 v[80:83], v[162:165], v[218:221], v[80:83]
	v_mfma_f32_16x16x32_bf16 v[64:67], v[170:173], v[218:221], v[64:67]
	v_mfma_f32_16x16x32_bf16 v[124:127], v[174:177], v[190:193], v[124:127]
	v_mfma_f32_16x16x32_bf16 v[120:123], v[182:185], v[190:193], v[120:123]
	v_mfma_f32_16x16x32_bf16 v[108:111], v[174:177], v[198:201], v[108:111]
	v_mfma_f32_16x16x32_bf16 v[104:107], v[182:185], v[198:201], v[104:107]
	v_mfma_f32_16x16x32_bf16 v[92:95], v[174:177], v[206:209], v[92:95]
	v_mfma_f32_16x16x32_bf16 v[88:91], v[182:185], v[206:209], v[88:91]
	v_mfma_f32_16x16x32_bf16 v[72:75], v[174:177], v[214:217], v[72:75]
	v_mfma_f32_16x16x32_bf16 v[68:71], v[182:185], v[214:217], v[68:71]
	v_mfma_f32_16x16x32_bf16 v[124:127], v[178:181], v[194:197], v[124:127]
	v_mfma_f32_16x16x32_bf16 v[120:123], v[186:189], v[194:197], v[120:123]
	v_mfma_f32_16x16x32_bf16 v[108:111], v[178:181], v[202:205], v[108:111]
	v_mfma_f32_16x16x32_bf16 v[104:107], v[186:189], v[202:205], v[104:107]
	v_mfma_f32_16x16x32_bf16 v[92:95], v[178:181], v[210:213], v[92:95]
	v_mfma_f32_16x16x32_bf16 v[88:91], v[186:189], v[210:213], v[88:91]
	v_mfma_f32_16x16x32_bf16 v[72:75], v[178:181], v[218:221], v[72:75]
	v_mfma_f32_16x16x32_bf16 v[68:71], v[186:189], v[218:221], v[68:71]
	s_barrier
	s_setprio 0
	s_add_i32 s12, s57, s2
	v_lshl_add_u64 v[144:145], s[52:53], 0, v[134:135]
	s_mov_b32 m0, s12
	ds_read_b128 v[190:193], v155 offset:16384
	ds_read_b128 v[194:197], v155 offset:17408
	ds_read_b128 v[198:201], v155 offset:18432
	ds_read_b128 v[202:205], v155 offset:19456
	ds_read_b128 v[206:209], v155 offset:20480
	ds_read_b128 v[210:213], v155 offset:21504
	ds_read_b128 v[214:217], v155 offset:22528
	ds_read_b128 v[218:221], v155 offset:23552
	global_load_lds_dwordx4 v[144:145], off
	s_add_i32 m0, s12, 0x2000
	s_add_u32 s12, s52, 0x4000
	v_lshl_add_u64 v[144:145], s[52:53], 0, v[138:139]
	s_addc_u32 s13, s53, 0
	s_add_i32 s14, s58, s2
	global_load_lds_dwordx4 v[144:145], off
	v_lshl_add_u64 v[144:145], s[12:13], 0, v[134:135]
	s_mov_b32 m0, s14
	v_lshl_add_u64 v[222:223], s[22:23], 0, v[136:137]
	global_load_lds_dwordx4 v[144:145], off
	v_lshl_add_u64 v[144:145], s[12:13], 0, v[138:139]
	s_add_i32 m0, s14, 0x2000
	s_nop 0
	global_load_lds_dwordx4 v[144:145], off
	v_lshl_add_u64 v[144:145], s[22:23], 0, v[132:133]
	s_mov_b32 m0, s19
	s_nop 0
	global_load_lds_dwordx4 v[144:145], off
	s_mov_b32 m0, s20
	s_nop 0
	global_load_lds_dwordx4 v[222:223], off
	s_waitcnt vmcnt(8)
	s_waitcnt lgkmcnt(0)
	s_setprio 1
	s_barrier
	v_mfma_f32_16x16x32_bf16 v[76:79], v[158:161], v[190:193], v[76:79]
	v_mfma_f32_16x16x32_bf16 v[52:55], v[166:169], v[190:193], v[52:55]
	v_mfma_f32_16x16x32_bf16 v[48:51], v[158:161], v[198:201], v[48:51]
	v_mfma_f32_16x16x32_bf16 v[36:39], v[166:169], v[198:201], v[36:39]
	v_mfma_f32_16x16x32_bf16 v[32:35], v[158:161], v[206:209], v[32:35]
	v_mfma_f32_16x16x32_bf16 v[20:23], v[166:169], v[206:209], v[20:23]
	v_mfma_f32_16x16x32_bf16 v[16:19], v[158:161], v[214:217], v[16:19]
	v_mfma_f32_16x16x32_bf16 v[4:7], v[166:169], v[214:217], v[4:7]
	v_mfma_f32_16x16x32_bf16 v[76:79], v[162:165], v[194:197], v[76:79]
	v_mfma_f32_16x16x32_bf16 v[52:55], v[170:173], v[194:197], v[52:55]
	v_mfma_f32_16x16x32_bf16 v[48:51], v[162:165], v[202:205], v[48:51]
	v_mfma_f32_16x16x32_bf16 v[36:39], v[170:173], v[202:205], v[36:39]
	v_mfma_f32_16x16x32_bf16 v[32:35], v[162:165], v[210:213], v[32:35]
	v_mfma_f32_16x16x32_bf16 v[20:23], v[170:173], v[210:213], v[20:23]
	v_mfma_f32_16x16x32_bf16 v[16:19], v[162:165], v[218:221], v[16:19]
	v_mfma_f32_16x16x32_bf16 v[4:7], v[170:173], v[218:221], v[4:7]
	v_mfma_f32_16x16x32_bf16 v[60:63], v[174:177], v[190:193], v[60:63]
	v_mfma_f32_16x16x32_bf16 v[56:59], v[182:185], v[190:193], v[56:59]
	v_mfma_f32_16x16x32_bf16 v[44:47], v[174:177], v[198:201], v[44:47]
	v_mfma_f32_16x16x32_bf16 v[40:43], v[182:185], v[198:201], v[40:43]
	v_mfma_f32_16x16x32_bf16 v[28:31], v[174:177], v[206:209], v[28:31]
	v_mfma_f32_16x16x32_bf16 v[24:27], v[182:185], v[206:209], v[24:27]
	v_mfma_f32_16x16x32_bf16 v[12:15], v[174:177], v[214:217], v[12:15]
	v_mfma_f32_16x16x32_bf16 v[8:11], v[182:185], v[214:217], v[8:11]
	v_mfma_f32_16x16x32_bf16 v[60:63], v[178:181], v[194:197], v[60:63]
	v_mfma_f32_16x16x32_bf16 v[56:59], v[186:189], v[194:197], v[56:59]
	v_mfma_f32_16x16x32_bf16 v[44:47], v[178:181], v[202:205], v[44:47]
	v_mfma_f32_16x16x32_bf16 v[40:43], v[186:189], v[202:205], v[40:43]
	v_mfma_f32_16x16x32_bf16 v[28:31], v[178:181], v[210:213], v[28:31]
	v_mfma_f32_16x16x32_bf16 v[24:27], v[186:189], v[210:213], v[24:27]
	v_mfma_f32_16x16x32_bf16 v[12:15], v[178:181], v[218:221], v[12:15]
	v_mfma_f32_16x16x32_bf16 v[8:11], v[186:189], v[218:221], v[8:11]
	s_barrier
	s_setprio 0
	s_add_i32 s14, 0, 0x18000
	v_add_u32_e32 v1, s14, v151
	s_add_i32 s69, 0, 0x1c000
	ds_read_b128 v[158:161], v1
	ds_read_b128 v[162:165], v1 offset:1024
	ds_read_b128 v[166:169], v1 offset:2048
	ds_read_b128 v[170:173], v1 offset:3072
	v_add_u32_e32 v1, s69, v151
	ds_read_b128 v[174:177], v1
	ds_read_b128 v[178:181], v1 offset:1024
	ds_read_b128 v[182:185], v1 offset:2048
	ds_read_b128 v[186:189], v1 offset:3072
	s_add_u32 s12, s22, 0x2b0000
	s_addc_u32 s13, s23, 0
	s_mov_b32 m0, s21
	v_lshl_add_u64 v[224:225], s[12:13], 0, v[132:133]
	ds_read_b128 v[190:193], v155 offset:32768
	ds_read_b128 v[194:197], v155 offset:33792
	ds_read_b128 v[198:201], v155 offset:34816
	ds_read_b128 v[202:205], v155 offset:35840
	ds_read_b128 v[206:209], v155 offset:36864
	ds_read_b128 v[210:213], v155 offset:37888
	ds_read_b128 v[214:217], v155 offset:38912
	ds_read_b128 v[218:221], v155 offset:39936
	global_load_lds_dwordx4 v[224:225], off
	v_lshl_add_u64 v[224:225], s[12:13], 0, v[136:137]
	s_mov_b32 m0, s24
	s_nop 0
	global_load_lds_dwordx4 v[224:225], off
	s_waitcnt vmcnt(8)
	s_waitcnt lgkmcnt(0)
	s_setprio 1
	s_barrier
	v_mfma_f32_16x16x32_bf16 v[128:131], v[158:161], v[190:193], v[128:131]
	v_mfma_f32_16x16x32_bf16 v[116:119], v[166:169], v[190:193], v[116:119]
	v_mfma_f32_16x16x32_bf16 v[112:115], v[158:161], v[198:201], v[112:115]
	v_mfma_f32_16x16x32_bf16 v[100:103], v[166:169], v[198:201], v[100:103]
	v_mfma_f32_16x16x32_bf16 v[96:99], v[158:161], v[206:209], v[96:99]
	v_mfma_f32_16x16x32_bf16 v[84:87], v[166:169], v[206:209], v[84:87]
	v_mfma_f32_16x16x32_bf16 v[80:83], v[158:161], v[214:217], v[80:83]
	v_mfma_f32_16x16x32_bf16 v[64:67], v[166:169], v[214:217], v[64:67]
	v_mfma_f32_16x16x32_bf16 v[128:131], v[162:165], v[194:197], v[128:131]
	v_mfma_f32_16x16x32_bf16 v[116:119], v[170:173], v[194:197], v[116:119]
	v_mfma_f32_16x16x32_bf16 v[112:115], v[162:165], v[202:205], v[112:115]
	v_mfma_f32_16x16x32_bf16 v[100:103], v[170:173], v[202:205], v[100:103]
	v_mfma_f32_16x16x32_bf16 v[96:99], v[162:165], v[210:213], v[96:99]
	v_mfma_f32_16x16x32_bf16 v[84:87], v[170:173], v[210:213], v[84:87]
	v_mfma_f32_16x16x32_bf16 v[80:83], v[162:165], v[218:221], v[80:83]
	v_mfma_f32_16x16x32_bf16 v[64:67], v[170:173], v[218:221], v[64:67]
	v_mfma_f32_16x16x32_bf16 v[124:127], v[174:177], v[190:193], v[124:127]
	v_mfma_f32_16x16x32_bf16 v[120:123], v[182:185], v[190:193], v[120:123]
	v_mfma_f32_16x16x32_bf16 v[108:111], v[174:177], v[198:201], v[108:111]
	v_mfma_f32_16x16x32_bf16 v[104:107], v[182:185], v[198:201], v[104:107]
	v_mfma_f32_16x16x32_bf16 v[92:95], v[174:177], v[206:209], v[92:95]
	v_mfma_f32_16x16x32_bf16 v[88:91], v[182:185], v[206:209], v[88:91]
	v_mfma_f32_16x16x32_bf16 v[72:75], v[174:177], v[214:217], v[72:75]
	v_mfma_f32_16x16x32_bf16 v[68:71], v[182:185], v[214:217], v[68:71]
	v_mfma_f32_16x16x32_bf16 v[124:127], v[178:181], v[194:197], v[124:127]
	v_mfma_f32_16x16x32_bf16 v[120:123], v[186:189], v[194:197], v[120:123]
	v_mfma_f32_16x16x32_bf16 v[108:111], v[178:181], v[202:205], v[108:111]
	v_mfma_f32_16x16x32_bf16 v[104:107], v[186:189], v[202:205], v[104:107]
	v_mfma_f32_16x16x32_bf16 v[92:95], v[178:181], v[210:213], v[92:95]
	v_mfma_f32_16x16x32_bf16 v[88:91], v[186:189], v[210:213], v[88:91]
	v_mfma_f32_16x16x32_bf16 v[72:75], v[178:181], v[218:221], v[72:75]
	v_mfma_f32_16x16x32_bf16 v[68:71], v[186:189], v[218:221], v[68:71]
	s_barrier
	s_setprio 0
	s_add_u32 s12, s52, 0x8000
	s_addc_u32 s13, s53, 0
	s_add_i32 s14, s14, s2
	v_lshl_add_u64 v[224:225], s[12:13], 0, v[134:135]
	s_mov_b32 m0, s14
	ds_read_b128 v[190:193], v155 offset:49152
	ds_read_b128 v[194:197], v155 offset:50176
	ds_read_b128 v[198:201], v155 offset:51200
	ds_read_b128 v[202:205], v155 offset:52224
	ds_read_b128 v[206:209], v155 offset:53248
	ds_read_b128 v[210:213], v155 offset:54272
	ds_read_b128 v[214:217], v155 offset:55296
	ds_read_b128 v[218:221], v155 offset:56320
	global_load_lds_dwordx4 v[224:225], off
	s_add_i32 m0, s14, 0x2000
	v_lshl_add_u64 v[224:225], s[12:13], 0, v[138:139]
	s_add_u32 s12, s52, 0xc000
	s_addc_u32 s13, s53, 0
	s_add_i32 s14, s69, s2
	global_load_lds_dwordx4 v[224:225], off
	v_lshl_add_u64 v[224:225], s[12:13], 0, v[134:135]
	s_mov_b32 m0, s14
	v_lshl_add_u64 v[144:145], v[144:145], 0, s[40:41]
	global_load_lds_dwordx4 v[224:225], off
	v_lshl_add_u64 v[224:225], s[12:13], 0, v[138:139]
	s_add_i32 m0, s14, 0x2000
	s_nop 0
	global_load_lds_dwordx4 v[224:225], off
	s_mov_b32 m0, s33
	s_nop 0
	global_load_lds_dwordx4 v[144:145], off
	v_lshl_add_u64 v[144:145], v[222:223], 0, s[40:41]
	s_mov_b32 m0, s54
	s_nop 0
	global_load_lds_dwordx4 v[144:145], off
	s_waitcnt vmcnt(8)
	s_waitcnt lgkmcnt(0)
	s_setprio 1
	s_barrier
	v_mfma_f32_16x16x32_bf16 v[76:79], v[158:161], v[190:193], v[76:79]
	v_mfma_f32_16x16x32_bf16 v[52:55], v[166:169], v[190:193], v[52:55]
	v_mfma_f32_16x16x32_bf16 v[48:51], v[158:161], v[198:201], v[48:51]
	v_mfma_f32_16x16x32_bf16 v[36:39], v[166:169], v[198:201], v[36:39]
	v_mfma_f32_16x16x32_bf16 v[32:35], v[158:161], v[206:209], v[32:35]
	v_mfma_f32_16x16x32_bf16 v[20:23], v[166:169], v[206:209], v[20:23]
	v_mfma_f32_16x16x32_bf16 v[16:19], v[158:161], v[214:217], v[16:19]
	v_mfma_f32_16x16x32_bf16 v[4:7], v[166:169], v[214:217], v[4:7]
	v_mfma_f32_16x16x32_bf16 v[76:79], v[162:165], v[194:197], v[76:79]
	v_mfma_f32_16x16x32_bf16 v[52:55], v[170:173], v[194:197], v[52:55]
	v_mfma_f32_16x16x32_bf16 v[48:51], v[162:165], v[202:205], v[48:51]
	v_mfma_f32_16x16x32_bf16 v[36:39], v[170:173], v[202:205], v[36:39]
	v_mfma_f32_16x16x32_bf16 v[32:35], v[162:165], v[210:213], v[32:35]
	v_mfma_f32_16x16x32_bf16 v[20:23], v[170:173], v[210:213], v[20:23]
	v_mfma_f32_16x16x32_bf16 v[16:19], v[162:165], v[218:221], v[16:19]
	v_mfma_f32_16x16x32_bf16 v[4:7], v[170:173], v[218:221], v[4:7]
	v_mfma_f32_16x16x32_bf16 v[60:63], v[174:177], v[190:193], v[60:63]
	v_mfma_f32_16x16x32_bf16 v[56:59], v[182:185], v[190:193], v[56:59]
	v_mfma_f32_16x16x32_bf16 v[44:47], v[174:177], v[198:201], v[44:47]
	v_mfma_f32_16x16x32_bf16 v[40:43], v[182:185], v[198:201], v[40:43]
	v_mfma_f32_16x16x32_bf16 v[28:31], v[174:177], v[206:209], v[28:31]
	v_mfma_f32_16x16x32_bf16 v[24:27], v[182:185], v[206:209], v[24:27]
	v_mfma_f32_16x16x32_bf16 v[12:15], v[174:177], v[214:217], v[12:15]
	v_mfma_f32_16x16x32_bf16 v[8:11], v[182:185], v[214:217], v[8:11]
	v_mfma_f32_16x16x32_bf16 v[60:63], v[178:181], v[194:197], v[60:63]
	v_mfma_f32_16x16x32_bf16 v[56:59], v[186:189], v[194:197], v[56:59]
	v_mfma_f32_16x16x32_bf16 v[44:47], v[178:181], v[202:205], v[44:47]
	v_mfma_f32_16x16x32_bf16 v[40:43], v[186:189], v[202:205], v[40:43]
	v_mfma_f32_16x16x32_bf16 v[28:31], v[178:181], v[210:213], v[28:31]
	v_mfma_f32_16x16x32_bf16 v[24:27], v[186:189], v[210:213], v[24:27]
	v_mfma_f32_16x16x32_bf16 v[12:15], v[178:181], v[218:221], v[12:15]
	v_mfma_f32_16x16x32_bf16 v[8:11], v[186:189], v[218:221], v[8:11]
	s_barrier
	s_setprio 0
	s_add_i32 s0, s0, 2
	s_add_u32 s1, s1, 0x10000
	s_addc_u32 s64, s64, 0
	s_add_u32 s65, s65, 0x100
	s_addc_u32 s66, s66, 0
	s_add_u32 s50, s50, 0xffffff00
	s_addc_u32 s51, s51, -1
	v_lshl_add_u64 v[2:3], v[2:3], 0, s[44:45]
	s_cmpk_gt_u32 s0, 0xa9
	v_lshl_add_u64 v[148:149], v[148:149], 0, s[44:45]
	s_cbranch_scc0 .LBB0_762
	s_and_b64 vcc, exec, s[42:43]
	s_cbranch_vccz .LBB0_765
	s_barrier

.LBB0_797:
	s_cmp_lg_u32 s67, 0
	s_mov_b32 s22, 0
	s_cbranch_scc0 .LBB0_799
	ds_read_b128 v[2:5], v155
	ds_read_b128 v[6:9], v155 offset:1024
	ds_read_b128 v[10:13], v155 offset:2048
	ds_read_b128 v[14:17], v155 offset:3072
	ds_read_b128 v[18:21], v156
	ds_read_b128 v[22:25], v156 offset:1024
	ds_read_b128 v[26:29], v156 offset:2048
	ds_read_b128 v[30:33], v156 offset:3072
	s_add_u32 s0, s56, 0x10000
	s_addc_u32 s1, s57, 0
	ds_read_b128 v[34:37], v157
	ds_read_b128 v[38:41], v157 offset:1024
	ds_read_b128 v[42:45], v157 offset:2048
	ds_read_b128 v[46:49], v157 offset:3072
	ds_read_b128 v[50:53], v157 offset:4096
	ds_read_b128 v[54:57], v157 offset:5120
	ds_read_b128 v[58:61], v157 offset:6144
	ds_read_b128 v[62:65], v157 offset:7168
	s_waitcnt vmcnt(16)
	s_waitcnt lgkmcnt(0)
	s_setprio 1
	s_barrier
	v_mfma_f32_16x16x32_bf16 v[86:89], v[10:13], v[50:53], 0
	v_mfma_f32_16x16x32_bf16 v[92:95], v[14:17], v[54:57], v[86:89]
	v_mfma_f32_16x16x32_bf16 v[86:89], v[2:5], v[58:61], 0
	v_mfma_f32_16x16x32_bf16 v[66:69], v[2:5], v[34:37], 0
	v_mfma_f32_16x16x32_bf16 v[70:73], v[10:13], v[34:37], 0
	v_mfma_f32_16x16x32_bf16 v[74:77], v[2:5], v[42:45], 0
	v_mfma_f32_16x16x32_bf16 v[78:81], v[10:13], v[42:45], 0
	v_mfma_f32_16x16x32_bf16 v[82:85], v[2:5], v[50:53], 0
	v_mfma_f32_16x16x32_bf16 v[96:99], v[6:9], v[62:65], v[86:89]
	v_mfma_f32_16x16x32_bf16 v[86:89], v[10:13], v[58:61], 0
	v_mfma_f32_16x16x32_bf16 v[66:69], v[6:9], v[38:41], v[66:69]
	v_mfma_f32_16x16x32_bf16 v[70:73], v[14:17], v[38:41], v[70:73]
	v_mfma_f32_16x16x32_bf16 v[74:77], v[6:9], v[46:49], v[74:77]
	v_mfma_f32_16x16x32_bf16 v[78:81], v[14:17], v[46:49], v[78:81]
	v_mfma_f32_16x16x32_bf16 v[82:85], v[6:9], v[54:57], v[82:85]
	v_mfma_f32_16x16x32_bf16 v[108:111], v[14:17], v[62:65], v[86:89]
	v_mfma_f32_16x16x32_bf16 v[86:89], v[18:21], v[34:37], 0
	v_mfma_f32_16x16x32_bf16 v[34:37], v[26:29], v[34:37], 0
	v_mfma_f32_16x16x32_bf16 v[112:115], v[22:25], v[38:41], v[86:89]
	v_mfma_f32_16x16x32_bf16 v[34:37], v[30:33], v[38:41], v[34:37]
	v_mfma_f32_16x16x32_bf16 v[38:41], v[18:21], v[42:45], 0
	v_mfma_f32_16x16x32_bf16 v[42:45], v[26:29], v[42:45], 0
	v_mfma_f32_16x16x32_bf16 v[38:41], v[22:25], v[46:49], v[38:41]
	v_mfma_f32_16x16x32_bf16 v[42:45], v[30:33], v[46:49], v[42:45]
	v_mfma_f32_16x16x32_bf16 v[46:49], v[18:21], v[50:53], 0
	v_mfma_f32_16x16x32_bf16 v[50:53], v[26:29], v[50:53], 0
	v_mfma_f32_16x16x32_bf16 v[46:49], v[22:25], v[54:57], v[46:49]
	v_mfma_f32_16x16x32_bf16 v[50:53], v[30:33], v[54:57], v[50:53]
	v_mfma_f32_16x16x32_bf16 v[54:57], v[18:21], v[58:61], 0
	v_mfma_f32_16x16x32_bf16 v[58:61], v[26:29], v[58:61], 0
	v_mfma_f32_16x16x32_bf16 v[54:57], v[22:25], v[62:65], v[54:57]
	v_mfma_f32_16x16x32_bf16 v[58:61], v[30:33], v[62:65], v[58:61]
	s_barrier
	s_setprio 0
	s_add_i32 s12, s60, s2
	v_lshl_add_u64 v[90:91], s[0:1], 0, v[134:135]
	s_mov_b32 m0, s12
	ds_read_b128 v[62:65], v157 offset:16384
	ds_read_b128 v[86:89], v157 offset:17408
	ds_read_b128 v[100:103], v157 offset:18432
	ds_read_b128 v[104:107], v157 offset:19456
	ds_read_b128 v[116:119], v157 offset:20480
	ds_read_b128 v[120:123], v157 offset:21504
	ds_read_b128 v[124:127], v157 offset:22528
	ds_read_b128 v[128:131], v157 offset:23552
	global_load_lds_dwordx4 v[90:91], off
	s_add_i32 m0, s12, 0x2000
	v_lshl_add_u64 v[90:91], s[0:1], 0, v[138:139]
	s_add_u32 s0, s56, 0x14000
	s_addc_u32 s1, s57, 0
	s_add_i32 s12, s61, s2
	global_load_lds_dwordx4 v[90:91], off
	v_lshl_add_u64 v[90:91], s[0:1], 0, v[134:135]
	s_mov_b32 m0, s12
	v_lshl_add_u64 v[148:149], s[8:9], 0, v[132:133]
	global_load_lds_dwordx4 v[90:91], off
	v_lshl_add_u64 v[90:91], s[0:1], 0, v[138:139]
	s_add_i32 m0, s12, 0x2000
	v_lshl_add_u64 v[144:145], s[8:9], 0, v[136:137]
	global_load_lds_dwordx4 v[90:91], off
	v_lshl_add_u64 v[90:91], v[148:149], 0, s[40:41]
	s_mov_b32 m0, s33
	s_nop 0
	global_load_lds_dwordx4 v[90:91], off
	v_lshl_add_u64 v[90:91], v[144:145], 0, s[40:41]
	s_mov_b32 m0, s53
	s_nop 0
	global_load_lds_dwordx4 v[90:91], off
	s_waitcnt vmcnt(16)
	s_waitcnt lgkmcnt(0)
	s_setprio 1
	s_barrier
	v_mfma_f32_16x16x32_bf16 v[158:161], v[2:5], v[62:65], 0
	v_mfma_f32_16x16x32_bf16 v[166:169], v[2:5], v[100:103], 0
	v_mfma_f32_16x16x32_bf16 v[174:177], v[2:5], v[116:119], 0
	v_mfma_f32_16x16x32_bf16 v[2:5], v[2:5], v[124:127], 0
	v_mfma_f32_16x16x32_bf16 v[158:161], v[6:9], v[86:89], v[158:161]
	v_mfma_f32_16x16x32_bf16 v[162:165], v[10:13], v[62:65], 0
	v_mfma_f32_16x16x32_bf16 v[166:169], v[6:9], v[104:107], v[166:169]
	v_mfma_f32_16x16x32_bf16 v[170:173], v[10:13], v[100:103], 0
	v_mfma_f32_16x16x32_bf16 v[174:177], v[6:9], v[120:123], v[174:177]
	v_mfma_f32_16x16x32_bf16 v[178:181], v[10:13], v[116:119], 0
	v_mfma_f32_16x16x32_bf16 v[2:5], v[6:9], v[128:131], v[2:5]
	v_mfma_f32_16x16x32_bf16 v[6:9], v[10:13], v[124:127], 0
	v_mfma_f32_16x16x32_bf16 v[162:165], v[14:17], v[86:89], v[162:165]
	v_mfma_f32_16x16x32_bf16 v[170:173], v[14:17], v[104:107], v[170:173]
	v_mfma_f32_16x16x32_bf16 v[178:181], v[14:17], v[120:123], v[178:181]
	v_mfma_f32_16x16x32_bf16 v[12:15], v[14:17], v[128:131], v[6:9]
	v_mfma_f32_16x16x32_bf16 v[6:9], v[18:21], v[62:65], 0
	v_mfma_f32_16x16x32_bf16 v[182:185], v[22:25], v[86:89], v[6:9]
	v_mfma_f32_16x16x32_bf16 v[6:9], v[26:29], v[62:65], 0
	v_mfma_f32_16x16x32_bf16 v[186:189], v[30:33], v[86:89], v[6:9]
	v_mfma_f32_16x16x32_bf16 v[6:9], v[18:21], v[100:103], 0
	v_mfma_f32_16x16x32_bf16 v[190:193], v[22:25], v[104:107], v[6:9]
	v_mfma_f32_16x16x32_bf16 v[6:9], v[26:29], v[100:103], 0
	v_mfma_f32_16x16x32_bf16 v[194:197], v[30:33], v[104:107], v[6:9]
	v_mfma_f32_16x16x32_bf16 v[6:9], v[18:21], v[116:119], 0
	v_mfma_f32_16x16x32_bf16 v[198:201], v[22:25], v[120:123], v[6:9]
	v_mfma_f32_16x16x32_bf16 v[6:9], v[26:29], v[116:119], 0
	v_mfma_f32_16x16x32_bf16 v[202:205], v[30:33], v[120:123], v[6:9]
	v_mfma_f32_16x16x32_bf16 v[6:9], v[18:21], v[124:127], 0
	v_mfma_f32_16x16x32_bf16 v[16:19], v[22:25], v[128:131], v[6:9]
	v_mfma_f32_16x16x32_bf16 v[6:9], v[26:29], v[124:127], 0
	v_mfma_f32_16x16x32_bf16 v[206:209], v[30:33], v[128:131], v[6:9]
	s_barrier
	s_setprio 0
	s_add_i32 s12, 0, 0x18000
	v_add_u32_e32 v1, s12, v152
	s_add_i32 s13, 0, 0x1c000
	s_nop 1
	ds_read_b128 v[6:9], v1
	ds_read_b128 v[28:31], v1 offset:1024
	ds_read_b128 v[62:65], v1 offset:2048
	ds_read_b128 v[210:213], v1 offset:3072
	v_add_u32_e32 v1, s13, v152
	ds_read_b128 v[214:217], v1
	ds_read_b128 v[218:221], v1 offset:1024
	ds_read_b128 v[222:225], v1 offset:2048
	ds_read_b128 v[226:229], v1 offset:3072
	s_add_u32 s0, s8, 0x100100
	s_addc_u32 s1, s9, 0
	s_mov_b32 m0, s55
	v_lshl_add_u64 v[10:11], s[0:1], 0, v[132:133]
	ds_read_b128 v[20:23], v157 offset:32768
	ds_read_b128 v[24:27], v157 offset:33792
	ds_read_b128 v[230:233], v157 offset:34816
	ds_read_b128 v[234:237], v157 offset:35840
	ds_read_b128 v[238:241], v157 offset:36864
	ds_read_b128 v[242:245], v157 offset:37888
	ds_read_b128 v[246:249], v157 offset:38912
	ds_read_b128 v[250:253], v157 offset:39936
	global_load_lds_dwordx4 v[10:11], off
	v_lshl_add_u64 v[10:11], s[0:1], 0, v[136:137]
	s_mov_b32 m0, s58
	s_nop 0
	global_load_lds_dwordx4 v[10:11], off
	s_waitcnt vmcnt(16)
	s_waitcnt lgkmcnt(0)
	s_setprio 1
	s_barrier
	v_mfma_f32_16x16x32_bf16 v[66:69], v[6:9], v[20:23], v[66:69]
	v_mfma_f32_16x16x32_bf16 v[120:123], v[28:31], v[24:27], v[66:69]
	v_mfma_f32_16x16x32_bf16 v[66:69], v[62:65], v[20:23], v[70:73]
	v_mfma_f32_16x16x32_bf16 v[116:119], v[210:213], v[24:27], v[66:69]
	v_mfma_f32_16x16x32_bf16 v[66:69], v[6:9], v[230:233], v[74:77]
	v_mfma_f32_16x16x32_bf16 v[104:107], v[28:31], v[234:237], v[66:69]
	v_mfma_f32_16x16x32_bf16 v[66:69], v[62:65], v[230:233], v[78:81]
	v_mfma_f32_16x16x32_bf16 v[100:103], v[210:213], v[234:237], v[66:69]
	v_mfma_f32_16x16x32_bf16 v[66:69], v[6:9], v[238:241], v[82:85]
	v_mfma_f32_16x16x32_bf16 v[88:91], v[28:31], v[242:245], v[66:69]
	v_mfma_f32_16x16x32_bf16 v[66:69], v[62:65], v[238:241], v[92:95]
	v_mfma_f32_16x16x32_bf16 v[84:87], v[210:213], v[242:245], v[66:69]
	v_mfma_f32_16x16x32_bf16 v[66:69], v[6:9], v[246:249], v[96:99]
	v_mfma_f32_16x16x32_bf16 v[72:75], v[28:31], v[250:253], v[66:69]
	v_mfma_f32_16x16x32_bf16 v[66:69], v[62:65], v[246:249], v[108:111]
	v_mfma_f32_16x16x32_bf16 v[68:71], v[210:213], v[250:253], v[66:69]
	v_mfma_f32_16x16x32_bf16 v[76:79], v[214:217], v[20:23], v[112:115]
	v_mfma_f32_16x16x32_bf16 v[20:23], v[222:225], v[20:23], v[34:37]
	v_mfma_f32_16x16x32_bf16 v[124:127], v[226:229], v[24:27], v[20:23]
	v_mfma_f32_16x16x32_bf16 v[20:23], v[214:217], v[230:233], v[38:41]
	v_mfma_f32_16x16x32_bf16 v[112:115], v[218:221], v[234:237], v[20:23]
	v_mfma_f32_16x16x32_bf16 v[20:23], v[222:225], v[230:233], v[42:45]
	v_mfma_f32_16x16x32_bf16 v[108:111], v[226:229], v[234:237], v[20:23]
	v_mfma_f32_16x16x32_bf16 v[20:23], v[214:217], v[238:241], v[46:49]
	v_mfma_f32_16x16x32_bf16 v[96:99], v[218:221], v[242:245], v[20:23]
	v_mfma_f32_16x16x32_bf16 v[20:23], v[222:225], v[238:241], v[50:53]
	v_mfma_f32_16x16x32_bf16 v[92:95], v[226:229], v[242:245], v[20:23]
	v_mfma_f32_16x16x32_bf16 v[20:23], v[214:217], v[246:249], v[54:57]
	v_mfma_f32_16x16x32_bf16 v[80:83], v[218:221], v[250:253], v[20:23]
	v_mfma_f32_16x16x32_bf16 v[20:23], v[222:225], v[246:249], v[58:61]
	v_mfma_f32_16x16x32_bf16 v[128:131], v[218:221], v[24:27], v[76:79]
	v_mfma_f32_16x16x32_bf16 v[76:79], v[226:229], v[250:253], v[20:23]
	s_barrier
	s_setprio 0
	s_add_u32 s0, s56, 0x18000
	s_addc_u32 s1, s57, 0
	s_add_i32 s12, s12, s2
	v_lshl_add_u64 v[10:11], s[0:1], 0, v[134:135]
	s_mov_b32 m0, s12
	ds_read_b128 v[32:35], v157 offset:49152
	ds_read_b128 v[44:47], v157 offset:50176
	ds_read_b128 v[230:233], v157 offset:51200
	ds_read_b128 v[234:237], v157 offset:52224
	ds_read_b128 v[238:241], v157 offset:53248
	ds_read_b128 v[242:245], v157 offset:54272
	ds_read_b128 v[246:249], v157 offset:55296
	ds_read_b128 v[250:253], v157 offset:56320
	global_load_lds_dwordx4 v[10:11], off
	s_add_i32 m0, s12, 0x2000
	v_lshl_add_u64 v[10:11], s[0:1], 0, v[138:139]
	s_add_u32 s0, s56, 0x1c000
	s_addc_u32 s1, s57, 0
	s_add_i32 s12, s13, s2
	global_load_lds_dwordx4 v[10:11], off
	v_lshl_add_u64 v[10:11], s[0:1], 0, v[134:135]
	s_mov_b32 m0, s12
	s_nop 0
	global_load_lds_dwordx4 v[10:11], off
	v_lshl_add_u64 v[10:11], s[0:1], 0, v[138:139]
	s_add_i32 m0, s12, 0x2000
	s_nop 0
	global_load_lds_dwordx4 v[10:11], off
	v_lshl_add_u64 v[10:11], v[148:149], 0, s[42:43]
	s_mov_b32 m0, s16
	s_nop 0
	global_load_lds_dwordx4 v[10:11], off
	v_lshl_add_u64 v[10:11], v[144:145], 0, s[42:43]
	s_mov_b32 m0, s59
	s_nop 0
	global_load_lds_dwordx4 v[10:11], off
	s_waitcnt vmcnt(8)
	s_waitcnt lgkmcnt(0)
	s_setprio 1
	s_barrier
	v_mfma_f32_16x16x32_bf16 v[20:23], v[6:9], v[32:35], v[158:161]
	v_mfma_f32_16x16x32_bf16 v[56:59], v[28:31], v[44:47], v[20:23]
	v_mfma_f32_16x16x32_bf16 v[20:23], v[62:65], v[32:35], v[162:165]
	v_mfma_f32_16x16x32_bf16 v[52:55], v[210:213], v[44:47], v[20:23]
	v_mfma_f32_16x16x32_bf16 v[20:23], v[6:9], v[230:233], v[166:169]
	v_mfma_f32_16x16x32_bf16 v[40:43], v[28:31], v[234:237], v[20:23]
	v_mfma_f32_16x16x32_bf16 v[20:23], v[62:65], v[230:233], v[170:173]
	v_mfma_f32_16x16x32_bf16 v[36:39], v[210:213], v[234:237], v[20:23]
	v_mfma_f32_16x16x32_bf16 v[20:23], v[6:9], v[238:241], v[174:177]
	v_mfma_f32_16x16x32_bf16 v[2:5], v[6:9], v[246:249], v[2:5]
	v_mfma_f32_16x16x32_bf16 v[24:27], v[28:31], v[242:245], v[20:23]
	v_mfma_f32_16x16x32_bf16 v[20:23], v[62:65], v[238:241], v[178:181]
	v_mfma_f32_16x16x32_bf16 v[8:11], v[28:31], v[250:253], v[2:5]
	v_mfma_f32_16x16x32_bf16 v[2:5], v[62:65], v[246:249], v[12:15]
	v_mfma_f32_16x16x32_bf16 v[20:23], v[210:213], v[242:245], v[20:23]
	v_mfma_f32_16x16x32_bf16 v[4:7], v[210:213], v[250:253], v[2:5]
	v_mfma_f32_16x16x32_bf16 v[12:15], v[214:217], v[32:35], v[182:185]
	v_mfma_f32_16x16x32_bf16 v[64:67], v[218:221], v[44:47], v[12:15]
	v_mfma_f32_16x16x32_bf16 v[12:15], v[222:225], v[32:35], v[186:189]
	v_mfma_f32_16x16x32_bf16 v[60:63], v[226:229], v[44:47], v[12:15]
	v_mfma_f32_16x16x32_bf16 v[12:15], v[214:217], v[230:233], v[190:193]
	v_mfma_f32_16x16x32_bf16 v[48:51], v[218:221], v[234:237], v[12:15]
	v_mfma_f32_16x16x32_bf16 v[12:15], v[222:225], v[230:233], v[194:197]
	v_mfma_f32_16x16x32_bf16 v[44:47], v[226:229], v[234:237], v[12:15]
	v_mfma_f32_16x16x32_bf16 v[12:15], v[214:217], v[238:241], v[198:201]
	v_mfma_f32_16x16x32_bf16 v[32:35], v[218:221], v[242:245], v[12:15]
	v_mfma_f32_16x16x32_bf16 v[12:15], v[222:225], v[238:241], v[202:205]
	v_mfma_f32_16x16x32_bf16 v[28:31], v[226:229], v[242:245], v[12:15]
	v_mfma_f32_16x16x32_bf16 v[12:15], v[214:217], v[246:249], v[16:19]
	v_mfma_f32_16x16x32_bf16 v[16:19], v[218:221], v[250:253], v[12:15]
	v_mfma_f32_16x16x32_bf16 v[12:15], v[222:225], v[246:249], v[206:209]
	v_mfma_f32_16x16x32_bf16 v[12:15], v[226:229], v[250:253], v[12:15]
	s_barrier
	s_setprio 0
	s_mov_b32 s22, 2
	s_branch .LBB0_800

.LBB0_801:
	ds_read_b128 v[158:161], v155
	ds_read_b128 v[162:165], v155 offset:1024
	ds_read_b128 v[166:169], v155 offset:2048
	ds_read_b128 v[170:173], v155 offset:3072
	ds_read_b128 v[174:177], v156
	ds_read_b128 v[178:181], v156 offset:1024
	ds_read_b128 v[182:185], v156 offset:2048
	ds_read_b128 v[186:189], v156 offset:3072
	s_add_u32 s12, s72, s36
	s_addc_u32 s13, s73, 0
	s_cmp_eq_u32 s36, s8
	s_cselect_b32 s23, s0, s13
	s_cselect_b32 s22, s1, s12
	s_cselect_b32 s57, s45, s71
	s_cselect_b32 s56, s68, s70
	s_add_i32 s75, s33, 0xc000
	v_lshl_add_u64 v[144:145], v[2:3], 0, s[36:37]
	s_mov_b32 m0, s75
	s_add_i32 s74, s33, 0xe000
	ds_read_b128 v[190:193], v157
	ds_read_b128 v[194:197], v157 offset:1024
	ds_read_b128 v[198:201], v157 offset:2048
	ds_read_b128 v[202:205], v157 offset:3072
	ds_read_b128 v[206:209], v157 offset:4096
	ds_read_b128 v[210:213], v157 offset:5120
	ds_read_b128 v[214:217], v157 offset:6144
	ds_read_b128 v[218:221], v157 offset:7168
	global_load_lds_dwordx4 v[144:145], off
	v_lshl_add_u64 v[144:145], v[148:149], 0, s[36:37]
	s_mov_b32 m0, s74
	s_nop 0
	global_load_lds_dwordx4 v[144:145], off
	s_waitcnt vmcnt(8)
	s_waitcnt lgkmcnt(0)
	s_setprio 1
	s_barrier
	v_mfma_f32_16x16x32_bf16 v[120:123], v[158:161], v[190:193], v[120:123]
	v_mfma_f32_16x16x32_bf16 v[116:119], v[166:169], v[190:193], v[116:119]
	v_mfma_f32_16x16x32_bf16 v[104:107], v[158:161], v[198:201], v[104:107]
	v_mfma_f32_16x16x32_bf16 v[100:103], v[166:169], v[198:201], v[100:103]
	v_mfma_f32_16x16x32_bf16 v[88:91], v[158:161], v[206:209], v[88:91]
	v_mfma_f32_16x16x32_bf16 v[84:87], v[166:169], v[206:209], v[84:87]
	v_mfma_f32_16x16x32_bf16 v[72:75], v[158:161], v[214:217], v[72:75]
	v_mfma_f32_16x16x32_bf16 v[68:71], v[166:169], v[214:217], v[68:71]
	v_mfma_f32_16x16x32_bf16 v[120:123], v[162:165], v[194:197], v[120:123]
	v_mfma_f32_16x16x32_bf16 v[116:119], v[170:173], v[194:197], v[116:119]
	v_mfma_f32_16x16x32_bf16 v[104:107], v[162:165], v[202:205], v[104:107]
	v_mfma_f32_16x16x32_bf16 v[100:103], v[170:173], v[202:205], v[100:103]
	v_mfma_f32_16x16x32_bf16 v[88:91], v[162:165], v[210:213], v[88:91]
	v_mfma_f32_16x16x32_bf16 v[84:87], v[170:173], v[210:213], v[84:87]
	v_mfma_f32_16x16x32_bf16 v[72:75], v[162:165], v[218:221], v[72:75]
	v_mfma_f32_16x16x32_bf16 v[68:71], v[170:173], v[218:221], v[68:71]
	v_mfma_f32_16x16x32_bf16 v[128:131], v[174:177], v[190:193], v[128:131]
	v_mfma_f32_16x16x32_bf16 v[124:127], v[182:185], v[190:193], v[124:127]
	v_mfma_f32_16x16x32_bf16 v[112:115], v[174:177], v[198:201], v[112:115]
	v_mfma_f32_16x16x32_bf16 v[108:111], v[182:185], v[198:201], v[108:111]
	v_mfma_f32_16x16x32_bf16 v[96:99], v[174:177], v[206:209], v[96:99]
	v_mfma_f32_16x16x32_bf16 v[92:95], v[182:185], v[206:209], v[92:95]
	v_mfma_f32_16x16x32_bf16 v[80:83], v[174:177], v[214:217], v[80:83]
	v_mfma_f32_16x16x32_bf16 v[76:79], v[182:185], v[214:217], v[76:79]
	v_mfma_f32_16x16x32_bf16 v[128:131], v[178:181], v[194:197], v[128:131]
	v_mfma_f32_16x16x32_bf16 v[124:127], v[186:189], v[194:197], v[124:127]
	v_mfma_f32_16x16x32_bf16 v[112:115], v[178:181], v[202:205], v[112:115]
	v_mfma_f32_16x16x32_bf16 v[108:111], v[186:189], v[202:205], v[108:111]
	v_mfma_f32_16x16x32_bf16 v[96:99], v[178:181], v[210:213], v[96:99]
	v_mfma_f32_16x16x32_bf16 v[92:95], v[186:189], v[210:213], v[92:95]
	v_mfma_f32_16x16x32_bf16 v[80:83], v[178:181], v[218:221], v[80:83]
	v_mfma_f32_16x16x32_bf16 v[76:79], v[186:189], v[218:221], v[76:79]
	s_barrier
	s_setprio 0
	s_add_i32 s12, s60, s2
	v_lshl_add_u64 v[144:145], s[56:57], 0, v[134:135]
	s_mov_b32 m0, s12
	ds_read_b128 v[190:193], v157 offset:16384
	ds_read_b128 v[194:197], v157 offset:17408
	ds_read_b128 v[198:201], v157 offset:18432
	ds_read_b128 v[202:205], v157 offset:19456
	ds_read_b128 v[206:209], v157 offset:20480
	ds_read_b128 v[210:213], v157 offset:21504
	ds_read_b128 v[214:217], v157 offset:22528
	ds_read_b128 v[218:221], v157 offset:23552
	global_load_lds_dwordx4 v[144:145], off
	s_add_i32 m0, s12, 0x2000
	s_add_u32 s12, s56, 0x4000
	v_lshl_add_u64 v[144:145], s[56:57], 0, v[138:139]
	s_addc_u32 s13, s57, 0
	s_add_i32 s14, s61, s2
	global_load_lds_dwordx4 v[144:145], off
	v_lshl_add_u64 v[144:145], s[12:13], 0, v[134:135]
	s_mov_b32 m0, s14
	v_lshl_add_u64 v[222:223], s[22:23], 0, v[136:137]
	global_load_lds_dwordx4 v[144:145], off
	v_lshl_add_u64 v[144:145], s[12:13], 0, v[138:139]
	s_add_i32 m0, s14, 0x2000
	s_nop 0
	global_load_lds_dwordx4 v[144:145], off
	v_lshl_add_u64 v[144:145], s[22:23], 0, v[132:133]
	s_mov_b32 m0, s33
	s_nop 0
	global_load_lds_dwordx4 v[144:145], off
	s_mov_b32 m0, s53
	s_nop 0
	global_load_lds_dwordx4 v[222:223], off
	s_waitcnt vmcnt(8)
	s_waitcnt lgkmcnt(0)
	s_setprio 1
	s_barrier
	v_mfma_f32_16x16x32_bf16 v[56:59], v[158:161], v[190:193], v[56:59]
	v_mfma_f32_16x16x32_bf16 v[52:55], v[166:169], v[190:193], v[52:55]
	v_mfma_f32_16x16x32_bf16 v[40:43], v[158:161], v[198:201], v[40:43]
	v_mfma_f32_16x16x32_bf16 v[36:39], v[166:169], v[198:201], v[36:39]
	v_mfma_f32_16x16x32_bf16 v[24:27], v[158:161], v[206:209], v[24:27]
	v_mfma_f32_16x16x32_bf16 v[20:23], v[166:169], v[206:209], v[20:23]
	v_mfma_f32_16x16x32_bf16 v[8:11], v[158:161], v[214:217], v[8:11]
	v_mfma_f32_16x16x32_bf16 v[4:7], v[166:169], v[214:217], v[4:7]
	v_mfma_f32_16x16x32_bf16 v[56:59], v[162:165], v[194:197], v[56:59]
	v_mfma_f32_16x16x32_bf16 v[52:55], v[170:173], v[194:197], v[52:55]
	v_mfma_f32_16x16x32_bf16 v[40:43], v[162:165], v[202:205], v[40:43]
	v_mfma_f32_16x16x32_bf16 v[36:39], v[170:173], v[202:205], v[36:39]
	v_mfma_f32_16x16x32_bf16 v[24:27], v[162:165], v[210:213], v[24:27]
	v_mfma_f32_16x16x32_bf16 v[20:23], v[170:173], v[210:213], v[20:23]
	v_mfma_f32_16x16x32_bf16 v[8:11], v[162:165], v[218:221], v[8:11]
	v_mfma_f32_16x16x32_bf16 v[4:7], v[170:173], v[218:221], v[4:7]
	v_mfma_f32_16x16x32_bf16 v[64:67], v[174:177], v[190:193], v[64:67]
	v_mfma_f32_16x16x32_bf16 v[60:63], v[182:185], v[190:193], v[60:63]
	v_mfma_f32_16x16x32_bf16 v[48:51], v[174:177], v[198:201], v[48:51]
	v_mfma_f32_16x16x32_bf16 v[44:47], v[182:185], v[198:201], v[44:47]
	v_mfma_f32_16x16x32_bf16 v[32:35], v[174:177], v[206:209], v[32:35]
	v_mfma_f32_16x16x32_bf16 v[28:31], v[182:185], v[206:209], v[28:31]
	v_mfma_f32_16x16x32_bf16 v[16:19], v[174:177], v[214:217], v[16:19]
	v_mfma_f32_16x16x32_bf16 v[12:15], v[182:185], v[214:217], v[12:15]
	v_mfma_f32_16x16x32_bf16 v[64:67], v[178:181], v[194:197], v[64:67]
	v_mfma_f32_16x16x32_bf16 v[60:63], v[186:189], v[194:197], v[60:63]
	v_mfma_f32_16x16x32_bf16 v[48:51], v[178:181], v[202:205], v[48:51]
	v_mfma_f32_16x16x32_bf16 v[44:47], v[186:189], v[202:205], v[44:47]
	v_mfma_f32_16x16x32_bf16 v[32:35], v[178:181], v[210:213], v[32:35]
	v_mfma_f32_16x16x32_bf16 v[28:31], v[186:189], v[210:213], v[28:31]
	v_mfma_f32_16x16x32_bf16 v[16:19], v[178:181], v[218:221], v[16:19]
	v_mfma_f32_16x16x32_bf16 v[12:15], v[186:189], v[218:221], v[12:15]
	s_barrier
	s_setprio 0
	s_add_i32 s14, 0, 0x18000
	v_add_u32_e32 v1, s14, v152
	s_add_i32 s76, 0, 0x1c000
	ds_read_b128 v[158:161], v1
	ds_read_b128 v[162:165], v1 offset:1024
	ds_read_b128 v[166:169], v1 offset:2048
	ds_read_b128 v[170:173], v1 offset:3072
	v_add_u32_e32 v1, s76, v152
	ds_read_b128 v[174:177], v1
	ds_read_b128 v[178:181], v1 offset:1024
	ds_read_b128 v[182:185], v1 offset:2048
	ds_read_b128 v[186:189], v1 offset:3072
	s_add_u32 s12, s22, 0x100000
	s_addc_u32 s13, s23, 0
	s_mov_b32 m0, s55
	v_lshl_add_u64 v[224:225], s[12:13], 0, v[132:133]
	ds_read_b128 v[190:193], v157 offset:32768
	ds_read_b128 v[194:197], v157 offset:33792
	ds_read_b128 v[198:201], v157 offset:34816
	ds_read_b128 v[202:205], v157 offset:35840
	ds_read_b128 v[206:209], v157 offset:36864
	ds_read_b128 v[210:213], v157 offset:37888
	ds_read_b128 v[214:217], v157 offset:38912
	ds_read_b128 v[218:221], v157 offset:39936
	global_load_lds_dwordx4 v[224:225], off
	v_lshl_add_u64 v[224:225], s[12:13], 0, v[136:137]
	s_mov_b32 m0, s58
	s_nop 0
	global_load_lds_dwordx4 v[224:225], off
	s_waitcnt vmcnt(8)
	s_waitcnt lgkmcnt(0)
	s_setprio 1
	s_barrier
	v_mfma_f32_16x16x32_bf16 v[120:123], v[158:161], v[190:193], v[120:123]
	v_mfma_f32_16x16x32_bf16 v[116:119], v[166:169], v[190:193], v[116:119]
	v_mfma_f32_16x16x32_bf16 v[104:107], v[158:161], v[198:201], v[104:107]
	v_mfma_f32_16x16x32_bf16 v[100:103], v[166:169], v[198:201], v[100:103]
	v_mfma_f32_16x16x32_bf16 v[88:91], v[158:161], v[206:209], v[88:91]
	v_mfma_f32_16x16x32_bf16 v[84:87], v[166:169], v[206:209], v[84:87]
	v_mfma_f32_16x16x32_bf16 v[72:75], v[158:161], v[214:217], v[72:75]
	v_mfma_f32_16x16x32_bf16 v[68:71], v[166:169], v[214:217], v[68:71]
	v_mfma_f32_16x16x32_bf16 v[120:123], v[162:165], v[194:197], v[120:123]
	v_mfma_f32_16x16x32_bf16 v[116:119], v[170:173], v[194:197], v[116:119]
	v_mfma_f32_16x16x32_bf16 v[104:107], v[162:165], v[202:205], v[104:107]
	v_mfma_f32_16x16x32_bf16 v[100:103], v[170:173], v[202:205], v[100:103]
	v_mfma_f32_16x16x32_bf16 v[88:91], v[162:165], v[210:213], v[88:91]
	v_mfma_f32_16x16x32_bf16 v[84:87], v[170:173], v[210:213], v[84:87]
	v_mfma_f32_16x16x32_bf16 v[72:75], v[162:165], v[218:221], v[72:75]
	v_mfma_f32_16x16x32_bf16 v[68:71], v[170:173], v[218:221], v[68:71]
	v_mfma_f32_16x16x32_bf16 v[128:131], v[174:177], v[190:193], v[128:131]
	v_mfma_f32_16x16x32_bf16 v[124:127], v[182:185], v[190:193], v[124:127]
	v_mfma_f32_16x16x32_bf16 v[112:115], v[174:177], v[198:201], v[112:115]
	v_mfma_f32_16x16x32_bf16 v[108:111], v[182:185], v[198:201], v[108:111]
	v_mfma_f32_16x16x32_bf16 v[96:99], v[174:177], v[206:209], v[96:99]
	v_mfma_f32_16x16x32_bf16 v[92:95], v[182:185], v[206:209], v[92:95]
	v_mfma_f32_16x16x32_bf16 v[80:83], v[174:177], v[214:217], v[80:83]
	v_mfma_f32_16x16x32_bf16 v[76:79], v[182:185], v[214:217], v[76:79]
	v_mfma_f32_16x16x32_bf16 v[128:131], v[178:181], v[194:197], v[128:131]
	v_mfma_f32_16x16x32_bf16 v[124:127], v[186:189], v[194:197], v[124:127]
	v_mfma_f32_16x16x32_bf16 v[112:115], v[178:181], v[202:205], v[112:115]
	v_mfma_f32_16x16x32_bf16 v[108:111], v[186:189], v[202:205], v[108:111]
	v_mfma_f32_16x16x32_bf16 v[96:99], v[178:181], v[210:213], v[96:99]
	v_mfma_f32_16x16x32_bf16 v[92:95], v[186:189], v[210:213], v[92:95]
	v_mfma_f32_16x16x32_bf16 v[80:83], v[178:181], v[218:221], v[80:83]
	v_mfma_f32_16x16x32_bf16 v[76:79], v[186:189], v[218:221], v[76:79]
	s_barrier
	s_setprio 0
	s_add_u32 s12, s56, 0x8000
	s_addc_u32 s13, s57, 0
	s_add_i32 s14, s14, s2
	v_lshl_add_u64 v[224:225], s[12:13], 0, v[134:135]
	s_mov_b32 m0, s14
	ds_read_b128 v[190:193], v157 offset:49152
	ds_read_b128 v[194:197], v157 offset:50176
	ds_read_b128 v[198:201], v157 offset:51200
	ds_read_b128 v[202:205], v157 offset:52224
	ds_read_b128 v[206:209], v157 offset:53248
	ds_read_b128 v[210:213], v157 offset:54272
	ds_read_b128 v[214:217], v157 offset:55296
	ds_read_b128 v[218:221], v157 offset:56320
	global_load_lds_dwordx4 v[224:225], off
	s_add_i32 m0, s14, 0x2000
	v_lshl_add_u64 v[224:225], s[12:13], 0, v[138:139]
	s_add_u32 s12, s56, 0xc000
	s_addc_u32 s13, s57, 0
	s_add_i32 s14, s76, s2
	global_load_lds_dwordx4 v[224:225], off
	v_lshl_add_u64 v[224:225], s[12:13], 0, v[134:135]
	s_mov_b32 m0, s14
	v_lshl_add_u64 v[144:145], v[144:145], 0, s[34:35]
	global_load_lds_dwordx4 v[224:225], off
	v_lshl_add_u64 v[224:225], s[12:13], 0, v[138:139]
	s_add_i32 m0, s14, 0x2000
	s_nop 0
	global_load_lds_dwordx4 v[224:225], off
	s_mov_b32 m0, s16
	s_nop 0
	global_load_lds_dwordx4 v[144:145], off
	v_lshl_add_u64 v[144:145], v[222:223], 0, s[34:35]
	s_mov_b32 m0, s59
	s_nop 0
	global_load_lds_dwordx4 v[144:145], off
	s_waitcnt vmcnt(8)
	s_waitcnt lgkmcnt(0)
	s_setprio 1
	s_barrier
	v_mfma_f32_16x16x32_bf16 v[56:59], v[158:161], v[190:193], v[56:59]
	v_mfma_f32_16x16x32_bf16 v[52:55], v[166:169], v[190:193], v[52:55]
	v_mfma_f32_16x16x32_bf16 v[40:43], v[158:161], v[198:201], v[40:43]
	v_mfma_f32_16x16x32_bf16 v[36:39], v[166:169], v[198:201], v[36:39]
	v_mfma_f32_16x16x32_bf16 v[24:27], v[158:161], v[206:209], v[24:27]
	v_mfma_f32_16x16x32_bf16 v[20:23], v[166:169], v[206:209], v[20:23]
	v_mfma_f32_16x16x32_bf16 v[8:11], v[158:161], v[214:217], v[8:11]
	v_mfma_f32_16x16x32_bf16 v[4:7], v[166:169], v[214:217], v[4:7]
	v_mfma_f32_16x16x32_bf16 v[56:59], v[162:165], v[194:197], v[56:59]
	v_mfma_f32_16x16x32_bf16 v[52:55], v[170:173], v[194:197], v[52:55]
	v_mfma_f32_16x16x32_bf16 v[40:43], v[162:165], v[202:205], v[40:43]
	v_mfma_f32_16x16x32_bf16 v[36:39], v[170:173], v[202:205], v[36:39]
	v_mfma_f32_16x16x32_bf16 v[24:27], v[162:165], v[210:213], v[24:27]
	v_mfma_f32_16x16x32_bf16 v[20:23], v[170:173], v[210:213], v[20:23]
	v_mfma_f32_16x16x32_bf16 v[8:11], v[162:165], v[218:221], v[8:11]
	v_mfma_f32_16x16x32_bf16 v[4:7], v[170:173], v[218:221], v[4:7]
	v_mfma_f32_16x16x32_bf16 v[64:67], v[174:177], v[190:193], v[64:67]
	v_mfma_f32_16x16x32_bf16 v[60:63], v[182:185], v[190:193], v[60:63]
	v_mfma_f32_16x16x32_bf16 v[48:51], v[174:177], v[198:201], v[48:51]
	v_mfma_f32_16x16x32_bf16 v[44:47], v[182:185], v[198:201], v[44:47]
	v_mfma_f32_16x16x32_bf16 v[32:35], v[174:177], v[206:209], v[32:35]
	v_mfma_f32_16x16x32_bf16 v[28:31], v[182:185], v[206:209], v[28:31]
	v_mfma_f32_16x16x32_bf16 v[16:19], v[174:177], v[214:217], v[16:19]
	v_mfma_f32_16x16x32_bf16 v[12:15], v[182:185], v[214:217], v[12:15]
	v_mfma_f32_16x16x32_bf16 v[64:67], v[178:181], v[194:197], v[64:67]
	v_mfma_f32_16x16x32_bf16 v[60:63], v[186:189], v[194:197], v[60:63]
	v_mfma_f32_16x16x32_bf16 v[48:51], v[178:181], v[202:205], v[48:51]
	v_mfma_f32_16x16x32_bf16 v[44:47], v[186:189], v[202:205], v[44:47]
	v_mfma_f32_16x16x32_bf16 v[32:35], v[178:181], v[210:213], v[32:35]
	v_mfma_f32_16x16x32_bf16 v[28:31], v[186:189], v[210:213], v[28:31]
	v_mfma_f32_16x16x32_bf16 v[16:19], v[178:181], v[218:221], v[16:19]
	v_mfma_f32_16x16x32_bf16 v[12:15], v[186:189], v[218:221], v[12:15]
	s_barrier
	s_setprio 0
	s_add_i32 s69, s69, 2
	s_add_u32 s70, s70, 0x10000
	s_addc_u32 s71, s71, 0
	s_add_u32 s72, s72, 0x100
	s_addc_u32 s73, s73, 0
	s_add_u32 s8, s8, 0xffffff00
	s_addc_u32 s9, s9, -1
	v_lshl_add_u64 v[2:3], v[2:3], 0, s[40:41]
	s_cmp_gt_u32 s69, 61
	v_lshl_add_u64 v[148:149], v[148:149], 0, s[40:41]
	s_cbranch_scc0 .LBB0_801
	s_and_b64 vcc, exec, s[38:39]
	s_cbranch_vccnz .LBB0_809
	s_and_b64 s[0:1], s[10:11], s[6:7]
	s_andn2_b64 vcc, exec, s[0:1]
	s_cbranch_vccz .LBB0_810

.LBB0_891:
	ds_read_b128 v[2:5], v153
	ds_read_b128 v[6:9], v153 offset:1024
	ds_read_b128 v[10:13], v153 offset:2048
	ds_read_b128 v[14:17], v153 offset:3072
	ds_read_b128 v[18:21], v154
	ds_read_b128 v[22:25], v154 offset:1024
	ds_read_b128 v[26:29], v154 offset:2048
	ds_read_b128 v[30:33], v154 offset:3072
	s_add_u32 s0, s46, 0x10000
	s_addc_u32 s1, s47, 0
	ds_read_b128 v[34:37], v155
	ds_read_b128 v[38:41], v155 offset:1024
	ds_read_b128 v[42:45], v155 offset:2048
	ds_read_b128 v[46:49], v155 offset:3072
	ds_read_b128 v[50:53], v155 offset:4096
	ds_read_b128 v[54:57], v155 offset:5120
	ds_read_b128 v[58:61], v155 offset:6144
	ds_read_b128 v[62:65], v155 offset:7168
	s_waitcnt vmcnt(24)
	s_waitcnt lgkmcnt(0)
	s_setprio 1
	s_barrier
	v_mfma_f32_16x16x32_bf16 v[66:69], v[2:5], v[34:37], 0
	v_mfma_f32_16x16x32_bf16 v[70:73], v[10:13], v[34:37], 0
	v_mfma_f32_16x16x32_bf16 v[74:77], v[2:5], v[42:45], 0
	v_mfma_f32_16x16x32_bf16 v[78:81], v[10:13], v[42:45], 0
	v_mfma_f32_16x16x32_bf16 v[82:85], v[2:5], v[50:53], 0
	v_mfma_f32_16x16x32_bf16 v[86:89], v[10:13], v[50:53], 0
	v_mfma_f32_16x16x32_bf16 v[90:93], v[2:5], v[58:61], 0
	v_mfma_f32_16x16x32_bf16 v[94:97], v[10:13], v[58:61], 0
	v_mfma_f32_16x16x32_bf16 v[66:69], v[6:9], v[38:41], v[66:69]
	v_mfma_f32_16x16x32_bf16 v[70:73], v[14:17], v[38:41], v[70:73]
	v_mfma_f32_16x16x32_bf16 v[74:77], v[6:9], v[46:49], v[74:77]
	v_mfma_f32_16x16x32_bf16 v[78:81], v[14:17], v[46:49], v[78:81]
	v_mfma_f32_16x16x32_bf16 v[82:85], v[6:9], v[54:57], v[82:85]
	v_mfma_f32_16x16x32_bf16 v[86:89], v[14:17], v[54:57], v[86:89]
	v_mfma_f32_16x16x32_bf16 v[90:93], v[6:9], v[62:65], v[90:93]
	v_mfma_f32_16x16x32_bf16 v[104:107], v[14:17], v[62:65], v[94:97]
	v_mfma_f32_16x16x32_bf16 v[94:97], v[18:21], v[34:37], 0
	v_mfma_f32_16x16x32_bf16 v[34:37], v[26:29], v[34:37], 0
	v_mfma_f32_16x16x32_bf16 v[108:111], v[22:25], v[38:41], v[94:97]
	v_mfma_f32_16x16x32_bf16 v[34:37], v[30:33], v[38:41], v[34:37]
	v_mfma_f32_16x16x32_bf16 v[38:41], v[18:21], v[42:45], 0
	v_mfma_f32_16x16x32_bf16 v[42:45], v[26:29], v[42:45], 0
	v_mfma_f32_16x16x32_bf16 v[38:41], v[22:25], v[46:49], v[38:41]
	v_mfma_f32_16x16x32_bf16 v[42:45], v[30:33], v[46:49], v[42:45]
	v_mfma_f32_16x16x32_bf16 v[46:49], v[18:21], v[50:53], 0
	v_mfma_f32_16x16x32_bf16 v[50:53], v[26:29], v[50:53], 0
	v_mfma_f32_16x16x32_bf16 v[46:49], v[22:25], v[54:57], v[46:49]
	v_mfma_f32_16x16x32_bf16 v[50:53], v[30:33], v[54:57], v[50:53]
	v_mfma_f32_16x16x32_bf16 v[54:57], v[18:21], v[58:61], 0
	v_mfma_f32_16x16x32_bf16 v[58:61], v[26:29], v[58:61], 0
	v_mfma_f32_16x16x32_bf16 v[54:57], v[22:25], v[62:65], v[54:57]
	v_mfma_f32_16x16x32_bf16 v[58:61], v[30:33], v[62:65], v[58:61]
	s_barrier
	s_setprio 0
	s_add_i32 s12, s52, s17
	v_lshl_add_u64 v[102:103], s[0:1], 0, v[134:135]
	s_mov_b32 m0, s12
	ds_read_b128 v[62:65], v155 offset:16384
	ds_read_b128 v[94:97], v155 offset:17408
	ds_read_b128 v[98:101], v155 offset:18432
	ds_read_b128 v[112:115], v155 offset:19456
	ds_read_b128 v[116:119], v155 offset:20480
	ds_read_b128 v[120:123], v155 offset:21504
	ds_read_b128 v[124:127], v155 offset:22528
	ds_read_b128 v[128:131], v155 offset:23552
	global_load_lds_dwordx4 v[102:103], off
	s_add_i32 m0, s12, 0x2000
	v_lshl_add_u64 v[102:103], s[0:1], 0, v[138:139]
	s_add_u32 s0, s46, 0x14000
	s_addc_u32 s1, s47, 0
	s_add_i32 s12, s53, s17
	global_load_lds_dwordx4 v[102:103], off
	v_lshl_add_u64 v[102:103], s[0:1], 0, v[134:135]
	s_mov_b32 m0, s12
	v_lshl_add_u64 v[148:149], s[48:49], 0, v[132:133]
	global_load_lds_dwordx4 v[102:103], off
	v_lshl_add_u64 v[102:103], s[0:1], 0, v[138:139]
	s_add_i32 m0, s12, 0x2000
	v_lshl_add_u64 v[144:145], s[48:49], 0, v[136:137]
	global_load_lds_dwordx4 v[102:103], off
	v_lshl_add_u64 v[102:103], v[148:149], 0, s[40:41]
	s_mov_b32 m0, s18
	s_nop 0
	global_load_lds_dwordx4 v[102:103], off
	v_lshl_add_u64 v[102:103], v[144:145], 0, s[40:41]
	s_mov_b32 m0, s19
	s_nop 0
	global_load_lds_dwordx4 v[102:103], off
	s_waitcnt vmcnt(24)
	s_waitcnt lgkmcnt(0)
	s_setprio 1
	s_barrier
	v_mfma_f32_16x16x32_bf16 v[158:161], v[2:5], v[62:65], 0
	v_mfma_f32_16x16x32_bf16 v[166:169], v[2:5], v[98:101], 0
	v_mfma_f32_16x16x32_bf16 v[174:177], v[2:5], v[116:119], 0
	v_mfma_f32_16x16x32_bf16 v[2:5], v[2:5], v[124:127], 0
	v_mfma_f32_16x16x32_bf16 v[158:161], v[6:9], v[94:97], v[158:161]
	v_mfma_f32_16x16x32_bf16 v[166:169], v[6:9], v[112:115], v[166:169]
	v_mfma_f32_16x16x32_bf16 v[174:177], v[6:9], v[120:123], v[174:177]
	v_mfma_f32_16x16x32_bf16 v[2:5], v[6:9], v[128:131], v[2:5]
	v_mfma_f32_16x16x32_bf16 v[6:9], v[10:13], v[124:127], 0
	v_mfma_f32_16x16x32_bf16 v[162:165], v[10:13], v[62:65], 0
	v_mfma_f32_16x16x32_bf16 v[170:173], v[10:13], v[98:101], 0
	v_mfma_f32_16x16x32_bf16 v[178:181], v[10:13], v[116:119], 0
	v_mfma_f32_16x16x32_bf16 v[6:9], v[14:17], v[128:131], v[6:9]
	v_mfma_f32_16x16x32_bf16 v[162:165], v[14:17], v[94:97], v[162:165]
	v_mfma_f32_16x16x32_bf16 v[170:173], v[14:17], v[112:115], v[170:173]
	v_mfma_f32_16x16x32_bf16 v[178:181], v[14:17], v[120:123], v[178:181]
	v_mfma_f32_16x16x32_bf16 v[14:17], v[26:29], v[62:65], 0
	v_mfma_f32_16x16x32_bf16 v[182:185], v[30:33], v[94:97], v[14:17]
	v_mfma_f32_16x16x32_bf16 v[14:17], v[18:21], v[98:101], 0
	v_mfma_f32_16x16x32_bf16 v[186:189], v[22:25], v[112:115], v[14:17]
	v_mfma_f32_16x16x32_bf16 v[14:17], v[26:29], v[98:101], 0
	v_mfma_f32_16x16x32_bf16 v[190:193], v[30:33], v[112:115], v[14:17]
	v_mfma_f32_16x16x32_bf16 v[14:17], v[18:21], v[116:119], 0
	v_mfma_f32_16x16x32_bf16 v[194:197], v[22:25], v[120:123], v[14:17]
	v_mfma_f32_16x16x32_bf16 v[14:17], v[26:29], v[116:119], 0
	v_mfma_f32_16x16x32_bf16 v[10:13], v[18:21], v[62:65], 0
	v_mfma_f32_16x16x32_bf16 v[198:201], v[30:33], v[120:123], v[14:17]
	v_mfma_f32_16x16x32_bf16 v[14:17], v[18:21], v[124:127], 0
	v_mfma_f32_16x16x32_bf16 v[10:13], v[22:25], v[94:97], v[10:13]
	v_mfma_f32_16x16x32_bf16 v[202:205], v[22:25], v[128:131], v[14:17]
	v_mfma_f32_16x16x32_bf16 v[14:17], v[26:29], v[124:127], 0
	v_mfma_f32_16x16x32_bf16 v[206:209], v[30:33], v[128:131], v[14:17]
	s_barrier
	s_setprio 0
	s_add_i32 s12, 0, 0x18000
	v_add_u32_e32 v1, s12, v151
	s_add_i32 s13, 0, 0x1c000
	s_nop 1
	ds_read_b128 v[14:17], v1
	ds_read_b128 v[24:27], v1 offset:1024
	ds_read_b128 v[28:31], v1 offset:2048
	ds_read_b128 v[210:213], v1 offset:3072
	v_add_u32_e32 v1, s13, v151
	ds_read_b128 v[214:217], v1
	ds_read_b128 v[218:221], v1 offset:1024
	ds_read_b128 v[222:225], v1 offset:2048
	ds_read_b128 v[226:229], v1 offset:3072
	s_add_u32 s0, s48, 0x2b0100
	s_addc_u32 s1, s49, 0
	s_mov_b32 m0, s20
	v_lshl_add_u64 v[22:23], s[0:1], 0, v[132:133]
	ds_read_b128 v[18:21], v155 offset:32768
	ds_read_b128 v[120:123], v155 offset:33792
	ds_read_b128 v[230:233], v155 offset:34816
	ds_read_b128 v[234:237], v155 offset:35840
	ds_read_b128 v[238:241], v155 offset:36864
	ds_read_b128 v[242:245], v155 offset:37888
	ds_read_b128 v[246:249], v155 offset:38912
	ds_read_b128 v[250:253], v155 offset:39936
	global_load_lds_dwordx4 v[22:23], off
	v_lshl_add_u64 v[22:23], s[0:1], 0, v[136:137]
	s_mov_b32 m0, s21
	s_nop 0
	global_load_lds_dwordx4 v[22:23], off
	s_waitcnt vmcnt(24)
	s_waitcnt lgkmcnt(0)
	s_setprio 1
	s_barrier
	v_mfma_f32_16x16x32_bf16 v[62:65], v[14:17], v[18:21], v[66:69]
	v_mfma_f32_16x16x32_bf16 v[128:131], v[24:27], v[120:123], v[62:65]
	v_mfma_f32_16x16x32_bf16 v[62:65], v[28:31], v[18:21], v[70:73]
	v_mfma_f32_16x16x32_bf16 v[116:119], v[210:213], v[120:123], v[62:65]
	v_mfma_f32_16x16x32_bf16 v[62:65], v[14:17], v[230:233], v[74:77]
	v_mfma_f32_16x16x32_bf16 v[112:115], v[24:27], v[234:237], v[62:65]
	v_mfma_f32_16x16x32_bf16 v[62:65], v[28:31], v[230:233], v[78:81]
	v_mfma_f32_16x16x32_bf16 v[100:103], v[210:213], v[234:237], v[62:65]
	v_mfma_f32_16x16x32_bf16 v[62:65], v[14:17], v[238:241], v[82:85]
	v_mfma_f32_16x16x32_bf16 v[96:99], v[24:27], v[242:245], v[62:65]
	v_mfma_f32_16x16x32_bf16 v[62:65], v[28:31], v[238:241], v[86:89]
	v_mfma_f32_16x16x32_bf16 v[84:87], v[210:213], v[242:245], v[62:65]
	v_mfma_f32_16x16x32_bf16 v[62:65], v[14:17], v[246:249], v[90:93]
	v_mfma_f32_16x16x32_bf16 v[80:83], v[24:27], v[250:253], v[62:65]
	v_mfma_f32_16x16x32_bf16 v[62:65], v[28:31], v[246:249], v[104:107]
	v_mfma_f32_16x16x32_bf16 v[64:67], v[210:213], v[250:253], v[62:65]
	v_mfma_f32_16x16x32_bf16 v[68:71], v[214:217], v[18:21], v[108:111]
	v_mfma_f32_16x16x32_bf16 v[18:21], v[222:225], v[18:21], v[34:37]
	v_mfma_f32_16x16x32_bf16 v[124:127], v[218:221], v[120:123], v[68:71]
	v_mfma_f32_16x16x32_bf16 v[120:123], v[226:229], v[120:123], v[18:21]
	v_mfma_f32_16x16x32_bf16 v[18:21], v[214:217], v[230:233], v[38:41]
	v_mfma_f32_16x16x32_bf16 v[108:111], v[218:221], v[234:237], v[18:21]
	v_mfma_f32_16x16x32_bf16 v[18:21], v[222:225], v[230:233], v[42:45]
	v_mfma_f32_16x16x32_bf16 v[104:107], v[226:229], v[234:237], v[18:21]
	v_mfma_f32_16x16x32_bf16 v[18:21], v[214:217], v[238:241], v[46:49]
	v_mfma_f32_16x16x32_bf16 v[92:95], v[218:221], v[242:245], v[18:21]
	v_mfma_f32_16x16x32_bf16 v[18:21], v[222:225], v[238:241], v[50:53]
	v_mfma_f32_16x16x32_bf16 v[88:91], v[226:229], v[242:245], v[18:21]
	v_mfma_f32_16x16x32_bf16 v[18:21], v[214:217], v[246:249], v[54:57]
	v_mfma_f32_16x16x32_bf16 v[72:75], v[218:221], v[250:253], v[18:21]
	v_mfma_f32_16x16x32_bf16 v[18:21], v[222:225], v[246:249], v[58:61]
	v_mfma_f32_16x16x32_bf16 v[68:71], v[226:229], v[250:253], v[18:21]
	s_barrier
	s_setprio 0
	s_add_u32 s0, s46, 0x18000
	s_addc_u32 s1, s47, 0
	s_add_i32 s12, s12, s17
	s_nop 1
	v_lshl_add_u64 v[18:19], s[0:1], 0, v[134:135]
	s_mov_b32 m0, s12
	ds_read_b128 v[40:43], v155 offset:49152
	ds_read_b128 v[44:47], v155 offset:50176
	ds_read_b128 v[230:233], v155 offset:51200
	ds_read_b128 v[234:237], v155 offset:52224
	ds_read_b128 v[238:241], v155 offset:53248
	ds_read_b128 v[242:245], v155 offset:54272
	ds_read_b128 v[246:249], v155 offset:55296
	ds_read_b128 v[250:253], v155 offset:56320
	global_load_lds_dwordx4 v[18:19], off
	s_add_i32 m0, s12, 0x2000
	v_lshl_add_u64 v[18:19], s[0:1], 0, v[138:139]
	s_add_u32 s0, s46, 0x1c000
	s_addc_u32 s1, s47, 0
	s_add_i32 s12, s13, s17
	global_load_lds_dwordx4 v[18:19], off
	v_lshl_add_u64 v[18:19], s[0:1], 0, v[134:135]
	s_mov_b32 m0, s12
	s_nop 0
	global_load_lds_dwordx4 v[18:19], off
	v_lshl_add_u64 v[18:19], s[0:1], 0, v[138:139]
	s_add_i32 m0, s12, 0x2000
	s_nop 0
	global_load_lds_dwordx4 v[18:19], off
	v_lshl_add_u64 v[18:19], v[148:149], 0, s[42:43]
	s_mov_b32 m0, s25
	s_nop 0
	global_load_lds_dwordx4 v[18:19], off
	v_lshl_add_u64 v[18:19], v[144:145], 0, s[42:43]
	s_mov_b32 m0, s33
	s_nop 0
	global_load_lds_dwordx4 v[18:19], off
	s_waitcnt vmcnt(8)
	s_waitcnt lgkmcnt(0)
	s_setprio 1
	s_barrier
	v_mfma_f32_16x16x32_bf16 v[18:21], v[14:17], v[40:43], v[158:161]
	v_mfma_f32_16x16x32_bf16 v[76:79], v[24:27], v[44:47], v[18:21]
	v_mfma_f32_16x16x32_bf16 v[18:21], v[28:31], v[40:43], v[162:165]
	v_mfma_f32_16x16x32_bf16 v[52:55], v[210:213], v[44:47], v[18:21]
	v_mfma_f32_16x16x32_bf16 v[18:21], v[14:17], v[230:233], v[166:169]
	v_mfma_f32_16x16x32_bf16 v[48:51], v[24:27], v[234:237], v[18:21]
	v_mfma_f32_16x16x32_bf16 v[18:21], v[28:31], v[230:233], v[170:173]
	v_mfma_f32_16x16x32_bf16 v[36:39], v[210:213], v[234:237], v[18:21]
	v_mfma_f32_16x16x32_bf16 v[18:21], v[14:17], v[238:241], v[174:177]
	v_mfma_f32_16x16x32_bf16 v[32:35], v[24:27], v[242:245], v[18:21]
	v_mfma_f32_16x16x32_bf16 v[18:21], v[28:31], v[238:241], v[178:181]
	v_mfma_f32_16x16x32_bf16 v[2:5], v[14:17], v[246:249], v[2:5]
	v_mfma_f32_16x16x32_bf16 v[20:23], v[210:213], v[242:245], v[18:21]
	v_mfma_f32_16x16x32_bf16 v[16:19], v[24:27], v[250:253], v[2:5]
	v_mfma_f32_16x16x32_bf16 v[2:5], v[28:31], v[246:249], v[6:9]
	v_mfma_f32_16x16x32_bf16 v[4:7], v[210:213], v[250:253], v[2:5]
	v_mfma_f32_16x16x32_bf16 v[8:11], v[214:217], v[40:43], v[10:13]
	v_mfma_f32_16x16x32_bf16 v[60:63], v[218:221], v[44:47], v[8:11]
	v_mfma_f32_16x16x32_bf16 v[8:11], v[222:225], v[40:43], v[182:185]
	v_mfma_f32_16x16x32_bf16 v[56:59], v[226:229], v[44:47], v[8:11]
	v_mfma_f32_16x16x32_bf16 v[8:11], v[214:217], v[230:233], v[186:189]
	v_mfma_f32_16x16x32_bf16 v[44:47], v[218:221], v[234:237], v[8:11]
	v_mfma_f32_16x16x32_bf16 v[8:11], v[222:225], v[230:233], v[190:193]
	v_mfma_f32_16x16x32_bf16 v[40:43], v[226:229], v[234:237], v[8:11]
	v_mfma_f32_16x16x32_bf16 v[8:11], v[214:217], v[238:241], v[194:197]
	v_mfma_f32_16x16x32_bf16 v[28:31], v[218:221], v[242:245], v[8:11]
	v_mfma_f32_16x16x32_bf16 v[8:11], v[222:225], v[238:241], v[198:201]
	v_mfma_f32_16x16x32_bf16 v[24:27], v[226:229], v[242:245], v[8:11]
	v_mfma_f32_16x16x32_bf16 v[8:11], v[214:217], v[246:249], v[202:205]
	v_mfma_f32_16x16x32_bf16 v[12:15], v[218:221], v[250:253], v[8:11]
	v_mfma_f32_16x16x32_bf16 v[8:11], v[222:225], v[246:249], v[206:209]
	v_mfma_f32_16x16x32_bf16 v[8:11], v[226:229], v[250:253], v[8:11]
	s_barrier
	s_setprio 0
	s_mov_b32 s22, 2
	s_branch .LBB0_895

.LBB0_896:
	ds_read_b128 v[158:161], v153
	ds_read_b128 v[162:165], v153 offset:1024
	ds_read_b128 v[166:169], v153 offset:2048
	ds_read_b128 v[170:173], v153 offset:3072
	ds_read_b128 v[174:177], v154
	ds_read_b128 v[178:181], v154 offset:1024
	ds_read_b128 v[182:185], v154 offset:2048
	ds_read_b128 v[186:189], v154 offset:3072
	s_add_u32 s12, s60, s26
	s_addc_u32 s13, s61, 0
	s_cmp_eq_u32 s26, s46
	s_cselect_b32 s23, s9, s13
	s_cselect_b32 s22, s8, s12
	s_cselect_b32 s49, s45, s59
	s_cselect_b32 s48, s44, s1
	s_add_i32 s63, s18, 0xc000
	v_lshl_add_u64 v[144:145], v[2:3], 0, s[26:27]
	s_mov_b32 m0, s63
	s_add_i32 s62, s18, 0xe000
	ds_read_b128 v[190:193], v155
	ds_read_b128 v[194:197], v155 offset:1024
	ds_read_b128 v[198:201], v155 offset:2048
	ds_read_b128 v[202:205], v155 offset:3072
	ds_read_b128 v[206:209], v155 offset:4096
	ds_read_b128 v[210:213], v155 offset:5120
	ds_read_b128 v[214:217], v155 offset:6144
	ds_read_b128 v[218:221], v155 offset:7168
	global_load_lds_dwordx4 v[144:145], off
	v_lshl_add_u64 v[144:145], v[148:149], 0, s[26:27]
	s_mov_b32 m0, s62
	s_nop 0
	global_load_lds_dwordx4 v[144:145], off
	s_waitcnt vmcnt(8)
	s_waitcnt lgkmcnt(0)
	s_setprio 1
	s_barrier
	v_mfma_f32_16x16x32_bf16 v[128:131], v[158:161], v[190:193], v[128:131]
	v_mfma_f32_16x16x32_bf16 v[116:119], v[166:169], v[190:193], v[116:119]
	v_mfma_f32_16x16x32_bf16 v[112:115], v[158:161], v[198:201], v[112:115]
	v_mfma_f32_16x16x32_bf16 v[100:103], v[166:169], v[198:201], v[100:103]
	v_mfma_f32_16x16x32_bf16 v[96:99], v[158:161], v[206:209], v[96:99]
	v_mfma_f32_16x16x32_bf16 v[84:87], v[166:169], v[206:209], v[84:87]
	v_mfma_f32_16x16x32_bf16 v[80:83], v[158:161], v[214:217], v[80:83]
	v_mfma_f32_16x16x32_bf16 v[64:67], v[166:169], v[214:217], v[64:67]
	v_mfma_f32_16x16x32_bf16 v[128:131], v[162:165], v[194:197], v[128:131]
	v_mfma_f32_16x16x32_bf16 v[116:119], v[170:173], v[194:197], v[116:119]
	v_mfma_f32_16x16x32_bf16 v[112:115], v[162:165], v[202:205], v[112:115]
	v_mfma_f32_16x16x32_bf16 v[100:103], v[170:173], v[202:205], v[100:103]
	v_mfma_f32_16x16x32_bf16 v[96:99], v[162:165], v[210:213], v[96:99]
	v_mfma_f32_16x16x32_bf16 v[84:87], v[170:173], v[210:213], v[84:87]
	v_mfma_f32_16x16x32_bf16 v[80:83], v[162:165], v[218:221], v[80:83]
	v_mfma_f32_16x16x32_bf16 v[64:67], v[170:173], v[218:221], v[64:67]
	v_mfma_f32_16x16x32_bf16 v[124:127], v[174:177], v[190:193], v[124:127]
	v_mfma_f32_16x16x32_bf16 v[120:123], v[182:185], v[190:193], v[120:123]
	v_mfma_f32_16x16x32_bf16 v[108:111], v[174:177], v[198:201], v[108:111]
	v_mfma_f32_16x16x32_bf16 v[104:107], v[182:185], v[198:201], v[104:107]
	v_mfma_f32_16x16x32_bf16 v[92:95], v[174:177], v[206:209], v[92:95]
	v_mfma_f32_16x16x32_bf16 v[88:91], v[182:185], v[206:209], v[88:91]
	v_mfma_f32_16x16x32_bf16 v[72:75], v[174:177], v[214:217], v[72:75]
	v_mfma_f32_16x16x32_bf16 v[68:71], v[182:185], v[214:217], v[68:71]
	v_mfma_f32_16x16x32_bf16 v[124:127], v[178:181], v[194:197], v[124:127]
	v_mfma_f32_16x16x32_bf16 v[120:123], v[186:189], v[194:197], v[120:123]
	v_mfma_f32_16x16x32_bf16 v[108:111], v[178:181], v[202:205], v[108:111]
	v_mfma_f32_16x16x32_bf16 v[104:107], v[186:189], v[202:205], v[104:107]
	v_mfma_f32_16x16x32_bf16 v[92:95], v[178:181], v[210:213], v[92:95]
	v_mfma_f32_16x16x32_bf16 v[88:91], v[186:189], v[210:213], v[88:91]
	v_mfma_f32_16x16x32_bf16 v[72:75], v[178:181], v[218:221], v[72:75]
	v_mfma_f32_16x16x32_bf16 v[68:71], v[186:189], v[218:221], v[68:71]
	s_barrier
	s_setprio 0
	s_add_i32 s12, s52, s17
	v_lshl_add_u64 v[144:145], s[48:49], 0, v[134:135]
	s_mov_b32 m0, s12
	ds_read_b128 v[190:193], v155 offset:16384
	ds_read_b128 v[194:197], v155 offset:17408
	ds_read_b128 v[198:201], v155 offset:18432
	ds_read_b128 v[202:205], v155 offset:19456
	ds_read_b128 v[206:209], v155 offset:20480
	ds_read_b128 v[210:213], v155 offset:21504
	ds_read_b128 v[214:217], v155 offset:22528
	ds_read_b128 v[218:221], v155 offset:23552
	global_load_lds_dwordx4 v[144:145], off
	s_add_i32 m0, s12, 0x2000
	s_add_u32 s12, s48, 0x4000
	v_lshl_add_u64 v[144:145], s[48:49], 0, v[138:139]
	s_addc_u32 s13, s49, 0
	s_add_i32 s14, s53, s17
	global_load_lds_dwordx4 v[144:145], off
	v_lshl_add_u64 v[144:145], s[12:13], 0, v[134:135]
	s_mov_b32 m0, s14
	v_lshl_add_u64 v[222:223], s[22:23], 0, v[136:137]
	global_load_lds_dwordx4 v[144:145], off
	v_lshl_add_u64 v[144:145], s[12:13], 0, v[138:139]
	s_add_i32 m0, s14, 0x2000
	s_nop 0
	global_load_lds_dwordx4 v[144:145], off
	v_lshl_add_u64 v[144:145], s[22:23], 0, v[132:133]
	s_mov_b32 m0, s18
	s_nop 0
	global_load_lds_dwordx4 v[144:145], off
	s_mov_b32 m0, s19
	s_nop 0
	global_load_lds_dwordx4 v[222:223], off
	s_waitcnt vmcnt(8)
	s_waitcnt lgkmcnt(0)
	s_setprio 1
	s_barrier
	v_mfma_f32_16x16x32_bf16 v[76:79], v[158:161], v[190:193], v[76:79]
	v_mfma_f32_16x16x32_bf16 v[52:55], v[166:169], v[190:193], v[52:55]
	v_mfma_f32_16x16x32_bf16 v[48:51], v[158:161], v[198:201], v[48:51]
	v_mfma_f32_16x16x32_bf16 v[36:39], v[166:169], v[198:201], v[36:39]
	v_mfma_f32_16x16x32_bf16 v[32:35], v[158:161], v[206:209], v[32:35]
	v_mfma_f32_16x16x32_bf16 v[20:23], v[166:169], v[206:209], v[20:23]
	v_mfma_f32_16x16x32_bf16 v[16:19], v[158:161], v[214:217], v[16:19]
	v_mfma_f32_16x16x32_bf16 v[4:7], v[166:169], v[214:217], v[4:7]
	v_mfma_f32_16x16x32_bf16 v[76:79], v[162:165], v[194:197], v[76:79]
	v_mfma_f32_16x16x32_bf16 v[52:55], v[170:173], v[194:197], v[52:55]
	v_mfma_f32_16x16x32_bf16 v[48:51], v[162:165], v[202:205], v[48:51]
	v_mfma_f32_16x16x32_bf16 v[36:39], v[170:173], v[202:205], v[36:39]
	v_mfma_f32_16x16x32_bf16 v[32:35], v[162:165], v[210:213], v[32:35]
	v_mfma_f32_16x16x32_bf16 v[20:23], v[170:173], v[210:213], v[20:23]
	v_mfma_f32_16x16x32_bf16 v[16:19], v[162:165], v[218:221], v[16:19]
	v_mfma_f32_16x16x32_bf16 v[4:7], v[170:173], v[218:221], v[4:7]
	v_mfma_f32_16x16x32_bf16 v[60:63], v[174:177], v[190:193], v[60:63]
	v_mfma_f32_16x16x32_bf16 v[56:59], v[182:185], v[190:193], v[56:59]
	v_mfma_f32_16x16x32_bf16 v[44:47], v[174:177], v[198:201], v[44:47]
	v_mfma_f32_16x16x32_bf16 v[40:43], v[182:185], v[198:201], v[40:43]
	v_mfma_f32_16x16x32_bf16 v[28:31], v[174:177], v[206:209], v[28:31]
	v_mfma_f32_16x16x32_bf16 v[24:27], v[182:185], v[206:209], v[24:27]
	v_mfma_f32_16x16x32_bf16 v[12:15], v[174:177], v[214:217], v[12:15]
	v_mfma_f32_16x16x32_bf16 v[8:11], v[182:185], v[214:217], v[8:11]
	v_mfma_f32_16x16x32_bf16 v[60:63], v[178:181], v[194:197], v[60:63]
	v_mfma_f32_16x16x32_bf16 v[56:59], v[186:189], v[194:197], v[56:59]
	v_mfma_f32_16x16x32_bf16 v[44:47], v[178:181], v[202:205], v[44:47]
	v_mfma_f32_16x16x32_bf16 v[40:43], v[186:189], v[202:205], v[40:43]
	v_mfma_f32_16x16x32_bf16 v[28:31], v[178:181], v[210:213], v[28:31]
	v_mfma_f32_16x16x32_bf16 v[24:27], v[186:189], v[210:213], v[24:27]
	v_mfma_f32_16x16x32_bf16 v[12:15], v[178:181], v[218:221], v[12:15]
	v_mfma_f32_16x16x32_bf16 v[8:11], v[186:189], v[218:221], v[8:11]
	s_barrier
	s_setprio 0
	s_add_i32 s14, 0, 0x18000
	v_add_u32_e32 v1, s14, v151
	s_add_i32 s64, 0, 0x1c000
	ds_read_b128 v[158:161], v1
	ds_read_b128 v[162:165], v1 offset:1024
	ds_read_b128 v[166:169], v1 offset:2048
	ds_read_b128 v[170:173], v1 offset:3072
	v_add_u32_e32 v1, s64, v151
	ds_read_b128 v[174:177], v1
	ds_read_b128 v[178:181], v1 offset:1024
	ds_read_b128 v[182:185], v1 offset:2048
	ds_read_b128 v[186:189], v1 offset:3072
	s_add_u32 s12, s22, 0x2b0000
	s_addc_u32 s13, s23, 0
	s_mov_b32 m0, s20
	v_lshl_add_u64 v[224:225], s[12:13], 0, v[132:133]
	ds_read_b128 v[190:193], v155 offset:32768
	ds_read_b128 v[194:197], v155 offset:33792
	ds_read_b128 v[198:201], v155 offset:34816
	ds_read_b128 v[202:205], v155 offset:35840
	ds_read_b128 v[206:209], v155 offset:36864
	ds_read_b128 v[210:213], v155 offset:37888
	ds_read_b128 v[214:217], v155 offset:38912
	ds_read_b128 v[218:221], v155 offset:39936
	global_load_lds_dwordx4 v[224:225], off
	v_lshl_add_u64 v[224:225], s[12:13], 0, v[136:137]
	s_mov_b32 m0, s21
	s_nop 0
	global_load_lds_dwordx4 v[224:225], off
	s_waitcnt vmcnt(8)
	s_waitcnt lgkmcnt(0)
	s_setprio 1
	s_barrier
	v_mfma_f32_16x16x32_bf16 v[128:131], v[158:161], v[190:193], v[128:131]
	v_mfma_f32_16x16x32_bf16 v[116:119], v[166:169], v[190:193], v[116:119]
	v_mfma_f32_16x16x32_bf16 v[112:115], v[158:161], v[198:201], v[112:115]
	v_mfma_f32_16x16x32_bf16 v[100:103], v[166:169], v[198:201], v[100:103]
	v_mfma_f32_16x16x32_bf16 v[96:99], v[158:161], v[206:209], v[96:99]
	v_mfma_f32_16x16x32_bf16 v[84:87], v[166:169], v[206:209], v[84:87]
	v_mfma_f32_16x16x32_bf16 v[80:83], v[158:161], v[214:217], v[80:83]
	v_mfma_f32_16x16x32_bf16 v[64:67], v[166:169], v[214:217], v[64:67]
	v_mfma_f32_16x16x32_bf16 v[128:131], v[162:165], v[194:197], v[128:131]
	v_mfma_f32_16x16x32_bf16 v[116:119], v[170:173], v[194:197], v[116:119]
	v_mfma_f32_16x16x32_bf16 v[112:115], v[162:165], v[202:205], v[112:115]
	v_mfma_f32_16x16x32_bf16 v[100:103], v[170:173], v[202:205], v[100:103]
	v_mfma_f32_16x16x32_bf16 v[96:99], v[162:165], v[210:213], v[96:99]
	v_mfma_f32_16x16x32_bf16 v[84:87], v[170:173], v[210:213], v[84:87]
	v_mfma_f32_16x16x32_bf16 v[80:83], v[162:165], v[218:221], v[80:83]
	v_mfma_f32_16x16x32_bf16 v[64:67], v[170:173], v[218:221], v[64:67]
	v_mfma_f32_16x16x32_bf16 v[124:127], v[174:177], v[190:193], v[124:127]
	v_mfma_f32_16x16x32_bf16 v[120:123], v[182:185], v[190:193], v[120:123]
	v_mfma_f32_16x16x32_bf16 v[108:111], v[174:177], v[198:201], v[108:111]
	v_mfma_f32_16x16x32_bf16 v[104:107], v[182:185], v[198:201], v[104:107]
	v_mfma_f32_16x16x32_bf16 v[92:95], v[174:177], v[206:209], v[92:95]
	v_mfma_f32_16x16x32_bf16 v[88:91], v[182:185], v[206:209], v[88:91]
	v_mfma_f32_16x16x32_bf16 v[72:75], v[174:177], v[214:217], v[72:75]
	v_mfma_f32_16x16x32_bf16 v[68:71], v[182:185], v[214:217], v[68:71]
	v_mfma_f32_16x16x32_bf16 v[124:127], v[178:181], v[194:197], v[124:127]
	v_mfma_f32_16x16x32_bf16 v[120:123], v[186:189], v[194:197], v[120:123]
	v_mfma_f32_16x16x32_bf16 v[108:111], v[178:181], v[202:205], v[108:111]
	v_mfma_f32_16x16x32_bf16 v[104:107], v[186:189], v[202:205], v[104:107]
	v_mfma_f32_16x16x32_bf16 v[92:95], v[178:181], v[210:213], v[92:95]
	v_mfma_f32_16x16x32_bf16 v[88:91], v[186:189], v[210:213], v[88:91]
	v_mfma_f32_16x16x32_bf16 v[72:75], v[178:181], v[218:221], v[72:75]
	v_mfma_f32_16x16x32_bf16 v[68:71], v[186:189], v[218:221], v[68:71]
	s_barrier
	s_setprio 0
	s_add_u32 s12, s48, 0x8000
	s_addc_u32 s13, s49, 0
	s_add_i32 s14, s14, s17
	v_lshl_add_u64 v[224:225], s[12:13], 0, v[134:135]
	s_mov_b32 m0, s14
	ds_read_b128 v[190:193], v155 offset:49152
	ds_read_b128 v[194:197], v155 offset:50176
	ds_read_b128 v[198:201], v155 offset:51200
	ds_read_b128 v[202:205], v155 offset:52224
	ds_read_b128 v[206:209], v155 offset:53248
	ds_read_b128 v[210:213], v155 offset:54272
	ds_read_b128 v[214:217], v155 offset:55296
	ds_read_b128 v[218:221], v155 offset:56320
	global_load_lds_dwordx4 v[224:225], off
	s_add_i32 m0, s14, 0x2000
	v_lshl_add_u64 v[224:225], s[12:13], 0, v[138:139]
	s_add_u32 s12, s48, 0xc000
	s_addc_u32 s13, s49, 0
	s_add_i32 s14, s64, s17
	global_load_lds_dwordx4 v[224:225], off
	v_lshl_add_u64 v[224:225], s[12:13], 0, v[134:135]
	s_mov_b32 m0, s14
	v_lshl_add_u64 v[144:145], v[144:145], 0, s[36:37]
	global_load_lds_dwordx4 v[224:225], off
	v_lshl_add_u64 v[224:225], s[12:13], 0, v[138:139]
	s_add_i32 m0, s14, 0x2000
	s_nop 0
	global_load_lds_dwordx4 v[224:225], off
	s_mov_b32 m0, s25
	s_nop 0
	global_load_lds_dwordx4 v[144:145], off
	v_lshl_add_u64 v[144:145], v[222:223], 0, s[36:37]
	s_mov_b32 m0, s33
	s_nop 0
	global_load_lds_dwordx4 v[144:145], off
	s_waitcnt vmcnt(8)
	s_waitcnt lgkmcnt(0)
	s_setprio 1
	s_barrier
	v_mfma_f32_16x16x32_bf16 v[76:79], v[158:161], v[190:193], v[76:79]
	v_mfma_f32_16x16x32_bf16 v[52:55], v[166:169], v[190:193], v[52:55]
	v_mfma_f32_16x16x32_bf16 v[48:51], v[158:161], v[198:201], v[48:51]
	v_mfma_f32_16x16x32_bf16 v[36:39], v[166:169], v[198:201], v[36:39]
	v_mfma_f32_16x16x32_bf16 v[32:35], v[158:161], v[206:209], v[32:35]
	v_mfma_f32_16x16x32_bf16 v[20:23], v[166:169], v[206:209], v[20:23]
	v_mfma_f32_16x16x32_bf16 v[16:19], v[158:161], v[214:217], v[16:19]
	v_mfma_f32_16x16x32_bf16 v[4:7], v[166:169], v[214:217], v[4:7]
	v_mfma_f32_16x16x32_bf16 v[76:79], v[162:165], v[194:197], v[76:79]
	v_mfma_f32_16x16x32_bf16 v[52:55], v[170:173], v[194:197], v[52:55]
	v_mfma_f32_16x16x32_bf16 v[48:51], v[162:165], v[202:205], v[48:51]
	v_mfma_f32_16x16x32_bf16 v[36:39], v[170:173], v[202:205], v[36:39]
	v_mfma_f32_16x16x32_bf16 v[32:35], v[162:165], v[210:213], v[32:35]
	v_mfma_f32_16x16x32_bf16 v[20:23], v[170:173], v[210:213], v[20:23]
	v_mfma_f32_16x16x32_bf16 v[16:19], v[162:165], v[218:221], v[16:19]
	v_mfma_f32_16x16x32_bf16 v[4:7], v[170:173], v[218:221], v[4:7]
	v_mfma_f32_16x16x32_bf16 v[60:63], v[174:177], v[190:193], v[60:63]
	v_mfma_f32_16x16x32_bf16 v[56:59], v[182:185], v[190:193], v[56:59]
	v_mfma_f32_16x16x32_bf16 v[44:47], v[174:177], v[198:201], v[44:47]
	v_mfma_f32_16x16x32_bf16 v[40:43], v[182:185], v[198:201], v[40:43]
	v_mfma_f32_16x16x32_bf16 v[28:31], v[174:177], v[206:209], v[28:31]
	v_mfma_f32_16x16x32_bf16 v[24:27], v[182:185], v[206:209], v[24:27]
	v_mfma_f32_16x16x32_bf16 v[12:15], v[174:177], v[214:217], v[12:15]
	v_mfma_f32_16x16x32_bf16 v[8:11], v[182:185], v[214:217], v[8:11]
	v_mfma_f32_16x16x32_bf16 v[60:63], v[178:181], v[194:197], v[60:63]
	v_mfma_f32_16x16x32_bf16 v[56:59], v[186:189], v[194:197], v[56:59]
	v_mfma_f32_16x16x32_bf16 v[44:47], v[178:181], v[202:205], v[44:47]
	v_mfma_f32_16x16x32_bf16 v[40:43], v[186:189], v[202:205], v[40:43]
	v_mfma_f32_16x16x32_bf16 v[28:31], v[178:181], v[210:213], v[28:31]
	v_mfma_f32_16x16x32_bf16 v[24:27], v[186:189], v[210:213], v[24:27]
	v_mfma_f32_16x16x32_bf16 v[12:15], v[178:181], v[218:221], v[12:15]
	v_mfma_f32_16x16x32_bf16 v[8:11], v[186:189], v[218:221], v[8:11]
	s_barrier
	s_setprio 0
	s_add_i32 s0, s0, 2
	s_add_u32 s1, s1, 0x10000
	s_addc_u32 s59, s59, 0
	s_add_u32 s60, s60, 0x100
	s_addc_u32 s61, s61, 0
	s_add_u32 s46, s46, 0xffffff00
	s_addc_u32 s47, s47, -1
	v_lshl_add_u64 v[2:3], v[2:3], 0, s[40:41]
	s_cmpk_gt_u32 s0, 0xa9
	v_lshl_add_u64 v[148:149], v[148:149], 0, s[40:41]
	s_cbranch_scc0 .LBB0_896
	s_and_b64 vcc, exec, s[38:39]
	s_cbranch_vccz .LBB0_899
	s_barrier

.LBB0_1049:
	s_cmp_lg_u32 s45, 0
	s_mov_b32 s22, 0
	s_cbranch_scc0 .LBB0_1051
	ds_read_b128 v[2:5], v155
	ds_read_b128 v[6:9], v155 offset:1024
	ds_read_b128 v[10:13], v155 offset:2048
	ds_read_b128 v[14:17], v155 offset:3072
	ds_read_b128 v[18:21], v156
	ds_read_b128 v[22:25], v156 offset:1024
	ds_read_b128 v[26:29], v156 offset:2048
	ds_read_b128 v[30:33], v156 offset:3072
	s_add_u32 s0, s52, 0x10000
	s_addc_u32 s1, s53, 0
	ds_read_b128 v[34:37], v157
	ds_read_b128 v[38:41], v157 offset:1024
	ds_read_b128 v[42:45], v157 offset:2048
	ds_read_b128 v[46:49], v157 offset:3072
	ds_read_b128 v[50:53], v157 offset:4096
	ds_read_b128 v[54:57], v157 offset:5120
	ds_read_b128 v[58:61], v157 offset:6144
	ds_read_b128 v[62:65], v157 offset:7168
	s_waitcnt vmcnt(24)
	s_waitcnt lgkmcnt(0)
	s_setprio 1
	s_barrier
	v_mfma_f32_16x16x32_bf16 v[90:93], v[2:5], v[58:61], 0
	v_mfma_f32_16x16x32_bf16 v[66:69], v[2:5], v[34:37], 0
	v_mfma_f32_16x16x32_bf16 v[70:73], v[10:13], v[34:37], 0
	v_mfma_f32_16x16x32_bf16 v[74:77], v[2:5], v[42:45], 0
	v_mfma_f32_16x16x32_bf16 v[78:81], v[10:13], v[42:45], 0
	v_mfma_f32_16x16x32_bf16 v[82:85], v[2:5], v[50:53], 0
	v_mfma_f32_16x16x32_bf16 v[86:89], v[10:13], v[50:53], 0
	v_mfma_f32_16x16x32_bf16 v[100:103], v[6:9], v[62:65], v[90:93]
	v_mfma_f32_16x16x32_bf16 v[90:93], v[10:13], v[58:61], 0
	v_mfma_f32_16x16x32_bf16 v[66:69], v[6:9], v[38:41], v[66:69]
	v_mfma_f32_16x16x32_bf16 v[70:73], v[14:17], v[38:41], v[70:73]
	v_mfma_f32_16x16x32_bf16 v[74:77], v[6:9], v[46:49], v[74:77]
	v_mfma_f32_16x16x32_bf16 v[78:81], v[14:17], v[46:49], v[78:81]
	v_mfma_f32_16x16x32_bf16 v[82:85], v[6:9], v[54:57], v[82:85]
	v_mfma_f32_16x16x32_bf16 v[86:89], v[14:17], v[54:57], v[86:89]
	v_mfma_f32_16x16x32_bf16 v[104:107], v[14:17], v[62:65], v[90:93]
	v_mfma_f32_16x16x32_bf16 v[90:93], v[18:21], v[34:37], 0
	v_mfma_f32_16x16x32_bf16 v[34:37], v[26:29], v[34:37], 0
	v_mfma_f32_16x16x32_bf16 v[116:119], v[22:25], v[38:41], v[90:93]
	v_mfma_f32_16x16x32_bf16 v[34:37], v[30:33], v[38:41], v[34:37]
	v_mfma_f32_16x16x32_bf16 v[38:41], v[18:21], v[42:45], 0
	v_mfma_f32_16x16x32_bf16 v[42:45], v[26:29], v[42:45], 0
	v_mfma_f32_16x16x32_bf16 v[38:41], v[22:25], v[46:49], v[38:41]
	v_mfma_f32_16x16x32_bf16 v[42:45], v[30:33], v[46:49], v[42:45]
	v_mfma_f32_16x16x32_bf16 v[46:49], v[18:21], v[50:53], 0
	v_mfma_f32_16x16x32_bf16 v[50:53], v[26:29], v[50:53], 0
	v_mfma_f32_16x16x32_bf16 v[46:49], v[22:25], v[54:57], v[46:49]
	v_mfma_f32_16x16x32_bf16 v[50:53], v[30:33], v[54:57], v[50:53]
	v_mfma_f32_16x16x32_bf16 v[54:57], v[18:21], v[58:61], 0
	v_mfma_f32_16x16x32_bf16 v[58:61], v[26:29], v[58:61], 0
	v_mfma_f32_16x16x32_bf16 v[54:57], v[22:25], v[62:65], v[54:57]
	v_mfma_f32_16x16x32_bf16 v[58:61], v[30:33], v[62:65], v[58:61]
	s_barrier
	s_setprio 0
	s_add_i32 s12, s58, s20
	v_lshl_add_u64 v[98:99], s[0:1], 0, v[134:135]
	s_mov_b32 m0, s12
	ds_read_b128 v[62:65], v157 offset:16384
	ds_read_b128 v[90:93], v157 offset:17408
	ds_read_b128 v[94:97], v157 offset:18432
	ds_read_b128 v[108:111], v157 offset:19456
	ds_read_b128 v[112:115], v157 offset:20480
	ds_read_b128 v[120:123], v157 offset:21504
	ds_read_b128 v[124:127], v157 offset:22528
	ds_read_b128 v[128:131], v157 offset:23552
	global_load_lds_dwordx4 v[98:99], off
	s_add_i32 m0, s12, 0x2000
	v_lshl_add_u64 v[98:99], s[0:1], 0, v[138:139]
	s_add_u32 s0, s52, 0x14000
	s_addc_u32 s1, s53, 0
	s_add_i32 s12, s59, s20
	global_load_lds_dwordx4 v[98:99], off
	v_lshl_add_u64 v[98:99], s[0:1], 0, v[134:135]
	s_mov_b32 m0, s12
	v_lshl_add_u64 v[150:151], s[6:7], 0, v[132:133]
	global_load_lds_dwordx4 v[98:99], off
	v_lshl_add_u64 v[98:99], s[0:1], 0, v[138:139]
	s_add_i32 m0, s12, 0x2000
	v_lshl_add_u64 v[252:253], s[6:7], 0, v[136:137]
	global_load_lds_dwordx4 v[98:99], off
	v_lshl_add_u64 v[98:99], v[150:151], 0, s[36:37]
	s_mov_b32 m0, s21
	s_nop 0
	global_load_lds_dwordx4 v[98:99], off
	v_lshl_add_u64 v[98:99], v[252:253], 0, s[36:37]
	s_mov_b32 m0, s24
	s_nop 0
	global_load_lds_dwordx4 v[98:99], off
	s_waitcnt vmcnt(24)
	s_waitcnt lgkmcnt(0)
	s_setprio 1
	s_barrier
	v_mfma_f32_16x16x32_bf16 v[160:163], v[2:5], v[62:65], 0
	v_mfma_f32_16x16x32_bf16 v[168:171], v[2:5], v[94:97], 0
	v_mfma_f32_16x16x32_bf16 v[176:179], v[2:5], v[112:115], 0
	v_mfma_f32_16x16x32_bf16 v[2:5], v[2:5], v[124:127], 0
	v_mfma_f32_16x16x32_bf16 v[160:163], v[6:9], v[90:93], v[160:163]
	v_mfma_f32_16x16x32_bf16 v[168:171], v[6:9], v[108:111], v[168:171]
	v_mfma_f32_16x16x32_bf16 v[176:179], v[6:9], v[120:123], v[176:179]
	v_mfma_f32_16x16x32_bf16 v[2:5], v[6:9], v[128:131], v[2:5]
	v_mfma_f32_16x16x32_bf16 v[6:9], v[10:13], v[124:127], 0
	v_mfma_f32_16x16x32_bf16 v[164:167], v[10:13], v[62:65], 0
	v_mfma_f32_16x16x32_bf16 v[172:175], v[10:13], v[94:97], 0
	v_mfma_f32_16x16x32_bf16 v[180:183], v[10:13], v[112:115], 0
	v_mfma_f32_16x16x32_bf16 v[6:9], v[14:17], v[128:131], v[6:9]
	v_mfma_f32_16x16x32_bf16 v[164:167], v[14:17], v[90:93], v[164:167]
	v_mfma_f32_16x16x32_bf16 v[172:175], v[14:17], v[108:111], v[172:175]
	v_mfma_f32_16x16x32_bf16 v[180:183], v[14:17], v[120:123], v[180:183]
	v_mfma_f32_16x16x32_bf16 v[10:13], v[18:21], v[62:65], 0
	v_mfma_f32_16x16x32_bf16 v[184:187], v[22:25], v[90:93], v[10:13]
	v_mfma_f32_16x16x32_bf16 v[10:13], v[26:29], v[62:65], 0
	v_mfma_f32_16x16x32_bf16 v[188:191], v[30:33], v[90:93], v[10:13]
	v_mfma_f32_16x16x32_bf16 v[10:13], v[18:21], v[94:97], 0
	v_mfma_f32_16x16x32_bf16 v[192:195], v[22:25], v[108:111], v[10:13]
	v_mfma_f32_16x16x32_bf16 v[10:13], v[26:29], v[94:97], 0
	v_mfma_f32_16x16x32_bf16 v[196:199], v[30:33], v[108:111], v[10:13]
	v_mfma_f32_16x16x32_bf16 v[10:13], v[18:21], v[112:115], 0
	v_mfma_f32_16x16x32_bf16 v[200:203], v[22:25], v[120:123], v[10:13]
	v_mfma_f32_16x16x32_bf16 v[10:13], v[26:29], v[112:115], 0
	v_mfma_f32_16x16x32_bf16 v[204:207], v[30:33], v[120:123], v[10:13]
	v_mfma_f32_16x16x32_bf16 v[10:13], v[18:21], v[124:127], 0
	v_mfma_f32_16x16x32_bf16 v[208:211], v[22:25], v[128:131], v[10:13]
	v_mfma_f32_16x16x32_bf16 v[10:13], v[26:29], v[124:127], 0
	v_mfma_f32_16x16x32_bf16 v[212:215], v[30:33], v[128:131], v[10:13]
	s_barrier
	s_setprio 0
	s_add_i32 s12, 0, 0x18000
	v_add_u32_e32 v0, s12, v154
	s_add_i32 s13, 0, 0x1c000
	s_nop 1
	ds_read_b128 v[10:13], v0
	ds_read_b128 v[14:17], v0 offset:1024
	ds_read_b128 v[20:23], v0 offset:2048
	ds_read_b128 v[24:27], v0 offset:3072
	v_add_u32_e32 v0, s13, v154
	ds_read_b128 v[216:219], v0
	ds_read_b128 v[220:223], v0 offset:1024
	ds_read_b128 v[224:227], v0 offset:2048
	ds_read_b128 v[228:231], v0 offset:3072
	s_add_u32 s0, s6, 0x100100
	s_addc_u32 s1, s7, 0
	s_mov_b32 m0, s25
	v_lshl_add_u64 v[18:19], s[0:1], 0, v[132:133]
	ds_read_b128 v[28:31], v157 offset:32768
	ds_read_b128 v[62:65], v157 offset:33792
	ds_read_b128 v[232:235], v157 offset:34816
	ds_read_b128 v[236:239], v157 offset:35840
	ds_read_b128 v[240:243], v157 offset:36864
	ds_read_b128 v[244:247], v157 offset:37888
	ds_read_b128 v[248:251], v157 offset:38912
	ds_read_b128 v[146:149], v157 offset:39936
	global_load_lds_dwordx4 v[18:19], off
	v_lshl_add_u64 v[18:19], s[0:1], 0, v[136:137]
	s_mov_b32 m0, s33
	s_nop 0
	global_load_lds_dwordx4 v[18:19], off
	s_waitcnt vmcnt(24)
	s_waitcnt lgkmcnt(0)
	s_setprio 1
	s_barrier
	v_mfma_f32_16x16x32_bf16 v[66:69], v[10:13], v[28:31], v[66:69]
	v_mfma_f32_16x16x32_bf16 v[128:131], v[14:17], v[62:65], v[66:69]
	v_mfma_f32_16x16x32_bf16 v[66:69], v[20:23], v[28:31], v[70:73]
	v_mfma_f32_16x16x32_bf16 v[124:127], v[24:27], v[62:65], v[66:69]
	v_mfma_f32_16x16x32_bf16 v[66:69], v[10:13], v[232:235], v[74:77]
	v_mfma_f32_16x16x32_bf16 v[112:115], v[14:17], v[236:239], v[66:69]
	v_mfma_f32_16x16x32_bf16 v[66:69], v[20:23], v[232:235], v[78:81]
	v_mfma_f32_16x16x32_bf16 v[108:111], v[24:27], v[236:239], v[66:69]
	v_mfma_f32_16x16x32_bf16 v[66:69], v[10:13], v[240:243], v[82:85]
	v_mfma_f32_16x16x32_bf16 v[96:99], v[14:17], v[244:247], v[66:69]
	v_mfma_f32_16x16x32_bf16 v[66:69], v[20:23], v[240:243], v[86:89]
	v_mfma_f32_16x16x32_bf16 v[92:95], v[24:27], v[244:247], v[66:69]
	v_mfma_f32_16x16x32_bf16 v[66:69], v[10:13], v[248:251], v[100:103]
	v_mfma_f32_16x16x32_bf16 v[80:83], v[14:17], v[146:149], v[66:69]
	v_mfma_f32_16x16x32_bf16 v[66:69], v[20:23], v[248:251], v[104:107]
	v_mfma_f32_16x16x32_bf16 v[76:79], v[24:27], v[146:149], v[66:69]
	v_mfma_f32_16x16x32_bf16 v[66:69], v[216:219], v[28:31], v[116:119]
	v_mfma_f32_16x16x32_bf16 v[28:31], v[224:227], v[28:31], v[34:37]
	v_mfma_f32_16x16x32_bf16 v[116:119], v[228:231], v[62:65], v[28:31]
	v_mfma_f32_16x16x32_bf16 v[28:31], v[216:219], v[232:235], v[38:41]
	v_mfma_f32_16x16x32_bf16 v[104:107], v[220:223], v[236:239], v[28:31]
	v_mfma_f32_16x16x32_bf16 v[28:31], v[224:227], v[232:235], v[42:45]
	v_mfma_f32_16x16x32_bf16 v[100:103], v[228:231], v[236:239], v[28:31]
	v_mfma_f32_16x16x32_bf16 v[28:31], v[216:219], v[240:243], v[46:49]
	v_mfma_f32_16x16x32_bf16 v[88:91], v[220:223], v[244:247], v[28:31]
	v_mfma_f32_16x16x32_bf16 v[28:31], v[224:227], v[240:243], v[50:53]
	v_mfma_f32_16x16x32_bf16 v[84:87], v[228:231], v[244:247], v[28:31]
	v_mfma_f32_16x16x32_bf16 v[28:31], v[216:219], v[248:251], v[54:57]
	v_mfma_f32_16x16x32_bf16 v[120:123], v[220:223], v[62:65], v[66:69]
	v_mfma_f32_16x16x32_bf16 v[64:67], v[220:223], v[146:149], v[28:31]
	v_mfma_f32_16x16x32_bf16 v[28:31], v[224:227], v[248:251], v[58:61]
	v_mfma_f32_16x16x32_bf16 v[60:63], v[228:231], v[146:149], v[28:31]
	s_barrier
	s_setprio 0
	s_add_u32 s0, s52, 0x18000
	s_addc_u32 s1, s53, 0
	s_add_i32 s12, s12, s20
	v_lshl_add_u64 v[18:19], s[0:1], 0, v[134:135]
	s_mov_b32 m0, s12
	ds_read_b128 v[36:39], v157 offset:49152
	ds_read_b128 v[40:43], v157 offset:50176
	ds_read_b128 v[146:149], v157 offset:51200
	ds_read_b128 v[232:235], v157 offset:52224
	ds_read_b128 v[236:239], v157 offset:53248
	ds_read_b128 v[240:243], v157 offset:54272
	ds_read_b128 v[244:247], v157 offset:55296
	ds_read_b128 v[248:251], v157 offset:56320
	global_load_lds_dwordx4 v[18:19], off
	s_add_i32 m0, s12, 0x2000
	v_lshl_add_u64 v[18:19], s[0:1], 0, v[138:139]
	s_add_u32 s0, s52, 0x1c000
	s_addc_u32 s1, s53, 0
	s_add_i32 s12, s13, s20
	global_load_lds_dwordx4 v[18:19], off
	v_lshl_add_u64 v[18:19], s[0:1], 0, v[134:135]
	s_mov_b32 m0, s12
	s_nop 0
	global_load_lds_dwordx4 v[18:19], off
	v_lshl_add_u64 v[18:19], s[0:1], 0, v[138:139]
	s_add_i32 m0, s12, 0x2000
	s_nop 0
	global_load_lds_dwordx4 v[18:19], off
	v_lshl_add_u64 v[18:19], v[150:151], 0, s[38:39]
	s_mov_b32 m0, s54
	s_nop 0
	global_load_lds_dwordx4 v[18:19], off
	v_lshl_add_u64 v[18:19], v[252:253], 0, s[38:39]
	s_mov_b32 m0, s55
	s_nop 0
	global_load_lds_dwordx4 v[18:19], off
	s_waitcnt vmcnt(8)
	s_waitcnt lgkmcnt(0)
	s_setprio 1
	s_barrier
	v_mfma_f32_16x16x32_bf16 v[28:31], v[10:13], v[36:39], v[160:163]
	v_mfma_f32_16x16x32_bf16 v[72:75], v[14:17], v[40:43], v[28:31]
	v_mfma_f32_16x16x32_bf16 v[28:31], v[20:23], v[36:39], v[164:167]
	v_mfma_f32_16x16x32_bf16 v[68:71], v[24:27], v[40:43], v[28:31]
	v_mfma_f32_16x16x32_bf16 v[28:31], v[10:13], v[146:149], v[168:171]
	v_mfma_f32_16x16x32_bf16 v[48:51], v[14:17], v[232:235], v[28:31]
	v_mfma_f32_16x16x32_bf16 v[28:31], v[20:23], v[146:149], v[172:175]
	v_mfma_f32_16x16x32_bf16 v[44:47], v[24:27], v[232:235], v[28:31]
	v_mfma_f32_16x16x32_bf16 v[28:31], v[10:13], v[236:239], v[176:179]
	v_mfma_f32_16x16x32_bf16 v[2:5], v[10:13], v[244:247], v[2:5]
	v_mfma_f32_16x16x32_bf16 v[32:35], v[14:17], v[240:243], v[28:31]
	v_mfma_f32_16x16x32_bf16 v[28:31], v[20:23], v[236:239], v[180:183]
	v_mfma_f32_16x16x32_bf16 v[16:19], v[14:17], v[248:251], v[2:5]
	v_mfma_f32_16x16x32_bf16 v[2:5], v[20:23], v[244:247], v[6:9]
	v_mfma_f32_16x16x32_bf16 v[28:31], v[24:27], v[240:243], v[28:31]
	v_mfma_f32_16x16x32_bf16 v[12:15], v[24:27], v[248:251], v[2:5]
	v_mfma_f32_16x16x32_bf16 v[2:5], v[216:219], v[36:39], v[184:187]
	v_mfma_f32_16x16x32_bf16 v[56:59], v[220:223], v[40:43], v[2:5]
	v_mfma_f32_16x16x32_bf16 v[2:5], v[224:227], v[36:39], v[188:191]
	v_mfma_f32_16x16x32_bf16 v[52:55], v[228:231], v[40:43], v[2:5]
	v_mfma_f32_16x16x32_bf16 v[2:5], v[216:219], v[146:149], v[192:195]
	v_mfma_f32_16x16x32_bf16 v[40:43], v[220:223], v[232:235], v[2:5]
	v_mfma_f32_16x16x32_bf16 v[2:5], v[224:227], v[146:149], v[196:199]
	v_mfma_f32_16x16x32_bf16 v[36:39], v[228:231], v[232:235], v[2:5]
	v_mfma_f32_16x16x32_bf16 v[2:5], v[216:219], v[236:239], v[200:203]
	v_mfma_f32_16x16x32_bf16 v[24:27], v[220:223], v[240:243], v[2:5]
	v_mfma_f32_16x16x32_bf16 v[2:5], v[224:227], v[236:239], v[204:207]
	v_mfma_f32_16x16x32_bf16 v[20:23], v[228:231], v[240:243], v[2:5]
	v_mfma_f32_16x16x32_bf16 v[2:5], v[216:219], v[244:247], v[208:211]
	v_mfma_f32_16x16x32_bf16 v[8:11], v[220:223], v[248:251], v[2:5]
	v_mfma_f32_16x16x32_bf16 v[2:5], v[224:227], v[244:247], v[212:215]
	v_mfma_f32_16x16x32_bf16 v[4:7], v[228:231], v[248:251], v[2:5]
	s_barrier
	s_setprio 0
	s_mov_b32 s22, 2
	s_branch .LBB0_1052

.LBB0_1053:
	ds_read_b128 v[146:149], v155
	ds_read_b128 v[160:163], v155 offset:1024
	ds_read_b128 v[164:167], v155 offset:2048
	ds_read_b128 v[168:171], v155 offset:3072
	ds_read_b128 v[172:175], v156
	ds_read_b128 v[176:179], v156 offset:1024
	ds_read_b128 v[180:183], v156 offset:2048
	ds_read_b128 v[184:187], v156 offset:3072
	s_add_u32 s12, s68, s30
	s_addc_u32 s13, s69, 0
	s_cmp_eq_u32 s30, s6
	s_cselect_b32 s23, s0, s13
	s_cselect_b32 s22, s1, s12
	s_cselect_b32 s53, s41, s67
	s_cselect_b32 s52, s64, s66
	s_add_i32 s71, s21, 0xc000
	v_lshl_add_u64 v[220:221], v[2:3], 0, s[30:31]
	s_mov_b32 m0, s71
	s_add_i32 s70, s21, 0xe000
	ds_read_b128 v[188:191], v157
	ds_read_b128 v[192:195], v157 offset:1024
	ds_read_b128 v[196:199], v157 offset:2048
	ds_read_b128 v[200:203], v157 offset:3072
	ds_read_b128 v[204:207], v157 offset:4096
	ds_read_b128 v[208:211], v157 offset:5120
	ds_read_b128 v[212:215], v157 offset:6144
	ds_read_b128 v[216:219], v157 offset:7168
	global_load_lds_dwordx4 v[220:221], off
	v_lshl_add_u64 v[220:221], v[150:151], 0, s[30:31]
	s_mov_b32 m0, s70
	s_nop 0
	global_load_lds_dwordx4 v[220:221], off
	s_waitcnt vmcnt(8)
	s_waitcnt lgkmcnt(0)
	s_setprio 1
	s_barrier
	v_mfma_f32_16x16x32_bf16 v[128:131], v[146:149], v[188:191], v[128:131]
	v_mfma_f32_16x16x32_bf16 v[124:127], v[164:167], v[188:191], v[124:127]
	v_mfma_f32_16x16x32_bf16 v[112:115], v[146:149], v[196:199], v[112:115]
	v_mfma_f32_16x16x32_bf16 v[108:111], v[164:167], v[196:199], v[108:111]
	v_mfma_f32_16x16x32_bf16 v[96:99], v[146:149], v[204:207], v[96:99]
	v_mfma_f32_16x16x32_bf16 v[92:95], v[164:167], v[204:207], v[92:95]
	v_mfma_f32_16x16x32_bf16 v[80:83], v[146:149], v[212:215], v[80:83]
	v_mfma_f32_16x16x32_bf16 v[76:79], v[164:167], v[212:215], v[76:79]
	v_mfma_f32_16x16x32_bf16 v[128:131], v[160:163], v[192:195], v[128:131]
	v_mfma_f32_16x16x32_bf16 v[124:127], v[168:171], v[192:195], v[124:127]
	v_mfma_f32_16x16x32_bf16 v[112:115], v[160:163], v[200:203], v[112:115]
	v_mfma_f32_16x16x32_bf16 v[108:111], v[168:171], v[200:203], v[108:111]
	v_mfma_f32_16x16x32_bf16 v[96:99], v[160:163], v[208:211], v[96:99]
	v_mfma_f32_16x16x32_bf16 v[92:95], v[168:171], v[208:211], v[92:95]
	v_mfma_f32_16x16x32_bf16 v[80:83], v[160:163], v[216:219], v[80:83]
	v_mfma_f32_16x16x32_bf16 v[76:79], v[168:171], v[216:219], v[76:79]
	v_mfma_f32_16x16x32_bf16 v[120:123], v[172:175], v[188:191], v[120:123]
	v_mfma_f32_16x16x32_bf16 v[116:119], v[180:183], v[188:191], v[116:119]
	v_mfma_f32_16x16x32_bf16 v[104:107], v[172:175], v[196:199], v[104:107]
	v_mfma_f32_16x16x32_bf16 v[100:103], v[180:183], v[196:199], v[100:103]
	v_mfma_f32_16x16x32_bf16 v[88:91], v[172:175], v[204:207], v[88:91]
	v_mfma_f32_16x16x32_bf16 v[84:87], v[180:183], v[204:207], v[84:87]
	v_mfma_f32_16x16x32_bf16 v[64:67], v[172:175], v[212:215], v[64:67]
	v_mfma_f32_16x16x32_bf16 v[60:63], v[180:183], v[212:215], v[60:63]
	v_mfma_f32_16x16x32_bf16 v[120:123], v[176:179], v[192:195], v[120:123]
	v_mfma_f32_16x16x32_bf16 v[116:119], v[184:187], v[192:195], v[116:119]
	v_mfma_f32_16x16x32_bf16 v[104:107], v[176:179], v[200:203], v[104:107]
	v_mfma_f32_16x16x32_bf16 v[100:103], v[184:187], v[200:203], v[100:103]
	v_mfma_f32_16x16x32_bf16 v[88:91], v[176:179], v[208:211], v[88:91]
	v_mfma_f32_16x16x32_bf16 v[84:87], v[184:187], v[208:211], v[84:87]
	v_mfma_f32_16x16x32_bf16 v[64:67], v[176:179], v[216:219], v[64:67]
	v_mfma_f32_16x16x32_bf16 v[60:63], v[184:187], v[216:219], v[60:63]
	s_barrier
	s_setprio 0
	s_add_i32 s12, s58, s20
	v_lshl_add_u64 v[220:221], s[52:53], 0, v[134:135]
	s_mov_b32 m0, s12
	ds_read_b128 v[188:191], v157 offset:16384
	ds_read_b128 v[192:195], v157 offset:17408
	ds_read_b128 v[196:199], v157 offset:18432
	ds_read_b128 v[200:203], v157 offset:19456
	ds_read_b128 v[204:207], v157 offset:20480
	ds_read_b128 v[208:211], v157 offset:21504
	ds_read_b128 v[212:215], v157 offset:22528
	ds_read_b128 v[216:219], v157 offset:23552
	global_load_lds_dwordx4 v[220:221], off
	s_add_i32 m0, s12, 0x2000
	s_add_u32 s12, s52, 0x4000
	v_lshl_add_u64 v[220:221], s[52:53], 0, v[138:139]
	s_addc_u32 s13, s53, 0
	s_add_i32 s14, s59, s20
	global_load_lds_dwordx4 v[220:221], off
	v_lshl_add_u64 v[220:221], s[12:13], 0, v[134:135]
	s_mov_b32 m0, s14
	v_lshl_add_u64 v[222:223], s[22:23], 0, v[136:137]
	global_load_lds_dwordx4 v[220:221], off
	v_lshl_add_u64 v[220:221], s[12:13], 0, v[138:139]
	s_add_i32 m0, s14, 0x2000
	s_nop 0
	global_load_lds_dwordx4 v[220:221], off
	v_lshl_add_u64 v[220:221], s[22:23], 0, v[132:133]
	s_mov_b32 m0, s21
	s_nop 0
	global_load_lds_dwordx4 v[220:221], off
	s_mov_b32 m0, s24
	s_nop 0
	global_load_lds_dwordx4 v[222:223], off
	s_waitcnt vmcnt(8)
	s_waitcnt lgkmcnt(0)
	s_setprio 1
	s_barrier
	v_mfma_f32_16x16x32_bf16 v[72:75], v[146:149], v[188:191], v[72:75]
	v_mfma_f32_16x16x32_bf16 v[68:71], v[164:167], v[188:191], v[68:71]
	v_mfma_f32_16x16x32_bf16 v[48:51], v[146:149], v[196:199], v[48:51]
	v_mfma_f32_16x16x32_bf16 v[44:47], v[164:167], v[196:199], v[44:47]
	v_mfma_f32_16x16x32_bf16 v[32:35], v[146:149], v[204:207], v[32:35]
	v_mfma_f32_16x16x32_bf16 v[28:31], v[164:167], v[204:207], v[28:31]
	v_mfma_f32_16x16x32_bf16 v[16:19], v[146:149], v[212:215], v[16:19]
	v_mfma_f32_16x16x32_bf16 v[12:15], v[164:167], v[212:215], v[12:15]
	v_mfma_f32_16x16x32_bf16 v[72:75], v[160:163], v[192:195], v[72:75]
	v_mfma_f32_16x16x32_bf16 v[68:71], v[168:171], v[192:195], v[68:71]
	v_mfma_f32_16x16x32_bf16 v[48:51], v[160:163], v[200:203], v[48:51]
	v_mfma_f32_16x16x32_bf16 v[44:47], v[168:171], v[200:203], v[44:47]
	v_mfma_f32_16x16x32_bf16 v[32:35], v[160:163], v[208:211], v[32:35]
	v_mfma_f32_16x16x32_bf16 v[28:31], v[168:171], v[208:211], v[28:31]
	v_mfma_f32_16x16x32_bf16 v[16:19], v[160:163], v[216:219], v[16:19]
	v_mfma_f32_16x16x32_bf16 v[12:15], v[168:171], v[216:219], v[12:15]
	v_mfma_f32_16x16x32_bf16 v[56:59], v[172:175], v[188:191], v[56:59]
	v_mfma_f32_16x16x32_bf16 v[52:55], v[180:183], v[188:191], v[52:55]
	v_mfma_f32_16x16x32_bf16 v[40:43], v[172:175], v[196:199], v[40:43]
	v_mfma_f32_16x16x32_bf16 v[36:39], v[180:183], v[196:199], v[36:39]
	v_mfma_f32_16x16x32_bf16 v[24:27], v[172:175], v[204:207], v[24:27]
	v_mfma_f32_16x16x32_bf16 v[20:23], v[180:183], v[204:207], v[20:23]
	v_mfma_f32_16x16x32_bf16 v[8:11], v[172:175], v[212:215], v[8:11]
	v_mfma_f32_16x16x32_bf16 v[4:7], v[180:183], v[212:215], v[4:7]
	v_mfma_f32_16x16x32_bf16 v[56:59], v[176:179], v[192:195], v[56:59]
	v_mfma_f32_16x16x32_bf16 v[52:55], v[184:187], v[192:195], v[52:55]
	v_mfma_f32_16x16x32_bf16 v[40:43], v[176:179], v[200:203], v[40:43]
	v_mfma_f32_16x16x32_bf16 v[36:39], v[184:187], v[200:203], v[36:39]
	v_mfma_f32_16x16x32_bf16 v[24:27], v[176:179], v[208:211], v[24:27]
	v_mfma_f32_16x16x32_bf16 v[20:23], v[184:187], v[208:211], v[20:23]
	v_mfma_f32_16x16x32_bf16 v[8:11], v[176:179], v[216:219], v[8:11]
	v_mfma_f32_16x16x32_bf16 v[4:7], v[184:187], v[216:219], v[4:7]
	s_barrier
	s_setprio 0
	s_add_i32 s14, 0, 0x18000
	v_add_u32_e32 v0, s14, v154
	s_add_i32 s72, 0, 0x1c000
	ds_read_b128 v[146:149], v0
	ds_read_b128 v[160:163], v0 offset:1024
	ds_read_b128 v[164:167], v0 offset:2048
	ds_read_b128 v[168:171], v0 offset:3072
	v_add_u32_e32 v0, s72, v154
	ds_read_b128 v[172:175], v0
	ds_read_b128 v[176:179], v0 offset:1024
	ds_read_b128 v[180:183], v0 offset:2048
	ds_read_b128 v[184:187], v0 offset:3072
	s_add_u32 s12, s22, 0x100000
	s_addc_u32 s13, s23, 0
	s_mov_b32 m0, s25
	v_lshl_add_u64 v[224:225], s[12:13], 0, v[132:133]
	ds_read_b128 v[188:191], v157 offset:32768
	ds_read_b128 v[192:195], v157 offset:33792
	ds_read_b128 v[196:199], v157 offset:34816
	ds_read_b128 v[200:203], v157 offset:35840
	ds_read_b128 v[204:207], v157 offset:36864
	ds_read_b128 v[208:211], v157 offset:37888
	ds_read_b128 v[212:215], v157 offset:38912
	ds_read_b128 v[216:219], v157 offset:39936
	global_load_lds_dwordx4 v[224:225], off
	v_lshl_add_u64 v[224:225], s[12:13], 0, v[136:137]
	s_mov_b32 m0, s33
	s_nop 0
	global_load_lds_dwordx4 v[224:225], off
	s_waitcnt vmcnt(8)
	s_waitcnt lgkmcnt(0)
	s_setprio 1
	s_barrier
	v_mfma_f32_16x16x32_bf16 v[128:131], v[146:149], v[188:191], v[128:131]
	v_mfma_f32_16x16x32_bf16 v[124:127], v[164:167], v[188:191], v[124:127]
	v_mfma_f32_16x16x32_bf16 v[112:115], v[146:149], v[196:199], v[112:115]
	v_mfma_f32_16x16x32_bf16 v[108:111], v[164:167], v[196:199], v[108:111]
	v_mfma_f32_16x16x32_bf16 v[96:99], v[146:149], v[204:207], v[96:99]
	v_mfma_f32_16x16x32_bf16 v[92:95], v[164:167], v[204:207], v[92:95]
	v_mfma_f32_16x16x32_bf16 v[80:83], v[146:149], v[212:215], v[80:83]
	v_mfma_f32_16x16x32_bf16 v[76:79], v[164:167], v[212:215], v[76:79]
	v_mfma_f32_16x16x32_bf16 v[128:131], v[160:163], v[192:195], v[128:131]
	v_mfma_f32_16x16x32_bf16 v[124:127], v[168:171], v[192:195], v[124:127]
	v_mfma_f32_16x16x32_bf16 v[112:115], v[160:163], v[200:203], v[112:115]
	v_mfma_f32_16x16x32_bf16 v[108:111], v[168:171], v[200:203], v[108:111]
	v_mfma_f32_16x16x32_bf16 v[96:99], v[160:163], v[208:211], v[96:99]
	v_mfma_f32_16x16x32_bf16 v[92:95], v[168:171], v[208:211], v[92:95]
	v_mfma_f32_16x16x32_bf16 v[80:83], v[160:163], v[216:219], v[80:83]
	v_mfma_f32_16x16x32_bf16 v[76:79], v[168:171], v[216:219], v[76:79]
	v_mfma_f32_16x16x32_bf16 v[120:123], v[172:175], v[188:191], v[120:123]
	v_mfma_f32_16x16x32_bf16 v[116:119], v[180:183], v[188:191], v[116:119]
	v_mfma_f32_16x16x32_bf16 v[104:107], v[172:175], v[196:199], v[104:107]
	v_mfma_f32_16x16x32_bf16 v[100:103], v[180:183], v[196:199], v[100:103]
	v_mfma_f32_16x16x32_bf16 v[88:91], v[172:175], v[204:207], v[88:91]
	v_mfma_f32_16x16x32_bf16 v[84:87], v[180:183], v[204:207], v[84:87]
	v_mfma_f32_16x16x32_bf16 v[64:67], v[172:175], v[212:215], v[64:67]
	v_mfma_f32_16x16x32_bf16 v[60:63], v[180:183], v[212:215], v[60:63]
	v_mfma_f32_16x16x32_bf16 v[120:123], v[176:179], v[192:195], v[120:123]
	v_mfma_f32_16x16x32_bf16 v[116:119], v[184:187], v[192:195], v[116:119]
	v_mfma_f32_16x16x32_bf16 v[104:107], v[176:179], v[200:203], v[104:107]
	v_mfma_f32_16x16x32_bf16 v[100:103], v[184:187], v[200:203], v[100:103]
	v_mfma_f32_16x16x32_bf16 v[88:91], v[176:179], v[208:211], v[88:91]
	v_mfma_f32_16x16x32_bf16 v[84:87], v[184:187], v[208:211], v[84:87]
	v_mfma_f32_16x16x32_bf16 v[64:67], v[176:179], v[216:219], v[64:67]
	v_mfma_f32_16x16x32_bf16 v[60:63], v[184:187], v[216:219], v[60:63]
	s_barrier
	s_setprio 0
	s_add_u32 s12, s52, 0x8000
	s_addc_u32 s13, s53, 0
	s_add_i32 s14, s14, s20
	v_lshl_add_u64 v[224:225], s[12:13], 0, v[134:135]
	s_mov_b32 m0, s14
	ds_read_b128 v[188:191], v157 offset:49152
	ds_read_b128 v[192:195], v157 offset:50176
	ds_read_b128 v[196:199], v157 offset:51200
	ds_read_b128 v[200:203], v157 offset:52224
	ds_read_b128 v[204:207], v157 offset:53248
	ds_read_b128 v[208:211], v157 offset:54272
	ds_read_b128 v[212:215], v157 offset:55296
	ds_read_b128 v[216:219], v157 offset:56320
	global_load_lds_dwordx4 v[224:225], off
	s_add_i32 m0, s14, 0x2000
	v_lshl_add_u64 v[224:225], s[12:13], 0, v[138:139]
	s_add_u32 s12, s52, 0xc000
	s_addc_u32 s13, s53, 0
	s_add_i32 s14, s72, s20
	global_load_lds_dwordx4 v[224:225], off
	v_lshl_add_u64 v[224:225], s[12:13], 0, v[134:135]
	s_mov_b32 m0, s14
	v_lshl_add_u64 v[220:221], v[220:221], 0, s[28:29]
	global_load_lds_dwordx4 v[224:225], off
	v_lshl_add_u64 v[224:225], s[12:13], 0, v[138:139]
	s_add_i32 m0, s14, 0x2000
	s_nop 0
	global_load_lds_dwordx4 v[224:225], off
	s_mov_b32 m0, s54
	s_nop 0
	global_load_lds_dwordx4 v[220:221], off
	v_lshl_add_u64 v[220:221], v[222:223], 0, s[28:29]
	s_mov_b32 m0, s55
	s_nop 0
	global_load_lds_dwordx4 v[220:221], off
	s_waitcnt vmcnt(8)
	s_waitcnt lgkmcnt(0)
	s_setprio 1
	s_barrier
	v_mfma_f32_16x16x32_bf16 v[72:75], v[146:149], v[188:191], v[72:75]
	v_mfma_f32_16x16x32_bf16 v[68:71], v[164:167], v[188:191], v[68:71]
	v_mfma_f32_16x16x32_bf16 v[48:51], v[146:149], v[196:199], v[48:51]
	v_mfma_f32_16x16x32_bf16 v[44:47], v[164:167], v[196:199], v[44:47]
	v_mfma_f32_16x16x32_bf16 v[32:35], v[146:149], v[204:207], v[32:35]
	v_mfma_f32_16x16x32_bf16 v[28:31], v[164:167], v[204:207], v[28:31]
	v_mfma_f32_16x16x32_bf16 v[16:19], v[146:149], v[212:215], v[16:19]
	v_mfma_f32_16x16x32_bf16 v[12:15], v[164:167], v[212:215], v[12:15]
	v_mfma_f32_16x16x32_bf16 v[72:75], v[160:163], v[192:195], v[72:75]
	v_mfma_f32_16x16x32_bf16 v[68:71], v[168:171], v[192:195], v[68:71]
	v_mfma_f32_16x16x32_bf16 v[48:51], v[160:163], v[200:203], v[48:51]
	v_mfma_f32_16x16x32_bf16 v[44:47], v[168:171], v[200:203], v[44:47]
	v_mfma_f32_16x16x32_bf16 v[32:35], v[160:163], v[208:211], v[32:35]
	v_mfma_f32_16x16x32_bf16 v[28:31], v[168:171], v[208:211], v[28:31]
	v_mfma_f32_16x16x32_bf16 v[16:19], v[160:163], v[216:219], v[16:19]
	v_mfma_f32_16x16x32_bf16 v[12:15], v[168:171], v[216:219], v[12:15]
	v_mfma_f32_16x16x32_bf16 v[56:59], v[172:175], v[188:191], v[56:59]
	v_mfma_f32_16x16x32_bf16 v[52:55], v[180:183], v[188:191], v[52:55]
	v_mfma_f32_16x16x32_bf16 v[40:43], v[172:175], v[196:199], v[40:43]
	v_mfma_f32_16x16x32_bf16 v[36:39], v[180:183], v[196:199], v[36:39]
	v_mfma_f32_16x16x32_bf16 v[24:27], v[172:175], v[204:207], v[24:27]
	v_mfma_f32_16x16x32_bf16 v[20:23], v[180:183], v[204:207], v[20:23]
	v_mfma_f32_16x16x32_bf16 v[8:11], v[172:175], v[212:215], v[8:11]
	v_mfma_f32_16x16x32_bf16 v[4:7], v[180:183], v[212:215], v[4:7]
	v_mfma_f32_16x16x32_bf16 v[56:59], v[176:179], v[192:195], v[56:59]
	v_mfma_f32_16x16x32_bf16 v[52:55], v[184:187], v[192:195], v[52:55]
	v_mfma_f32_16x16x32_bf16 v[40:43], v[176:179], v[200:203], v[40:43]
	v_mfma_f32_16x16x32_bf16 v[36:39], v[184:187], v[200:203], v[36:39]
	v_mfma_f32_16x16x32_bf16 v[24:27], v[176:179], v[208:211], v[24:27]
	v_mfma_f32_16x16x32_bf16 v[20:23], v[184:187], v[208:211], v[20:23]
	v_mfma_f32_16x16x32_bf16 v[8:11], v[176:179], v[216:219], v[8:11]
	v_mfma_f32_16x16x32_bf16 v[4:7], v[184:187], v[216:219], v[4:7]
	s_barrier
	s_setprio 0
	s_add_i32 s65, s65, 2
	s_add_u32 s66, s66, 0x10000
	s_addc_u32 s67, s67, 0
	s_add_u32 s68, s68, 0x100
	s_addc_u32 s69, s69, 0
	s_add_u32 s6, s6, 0xffffff00
	s_addc_u32 s7, s7, -1
	v_lshl_add_u64 v[2:3], v[2:3], 0, s[36:37]
	s_cmp_gt_u32 s65, 61
	v_lshl_add_u64 v[150:151], v[150:151], 0, s[36:37]
	s_cbranch_scc0 .LBB0_1053
	s_and_b64 vcc, exec, s[34:35]
	s_cbranch_vccnz .LBB0_1061
	s_and_b64 s[0:1], s[10:11], s[4:5]
	s_andn2_b64 vcc, exec, s[0:1]
	s_cbranch_vccz .LBB0_1062

.LBB0_1120:
	s_cmp_lt_i32 s86, 11
	s_cselect_b64 s[0:1], -1, 0
	s_and_b64 s[4:5], s[0:1], s[4:5]
	s_andn2_b64 vcc, exec, s[4:5]
	s_cbranch_vccnz .LBB0_1269
	s_load_dwordx2 s[0:1], s[84:85], 0x50
	s_load_dword s2, s[84:85], 0x2e0
	v_mbcnt_lo_u32_b32 v0, -1, 0
	v_mbcnt_hi_u32_b32 v0, -1, v0
	s_cmpk_gt_i32 s90, 0x1ff
	v_mbcnt_lo_u32_b32 v0, -1, 0
	v_mbcnt_hi_u32_b32 v0, -1, v0
	s_nop 0
	v_ashrrev_i32_e32 v1, 31, v0
	s_waitcnt lgkmcnt(0)
	v_lshl_add_u64 v[0:1], v[0:1], 2, s[0:1]
	global_load_dword v2, v[0:1], off offset:768
	global_load_dword v3, v[0:1], off offset:1024
	global_load_dword v4, v[0:1], off offset:1792
	global_load_dword v5, v[0:1], off offset:1280
	global_load_dword v6, v[0:1], off offset:256
	global_load_dword v7, v[0:1], off offset:512
	global_load_dword v8, v[0:1], off
	global_load_dword v9, v[0:1], off offset:1536
	v_mbcnt_lo_u32_b32 v0, -1, 0
	v_mbcnt_hi_u32_b32 v0, -1, v0
	v_and_b32_e32 v1, 64, v0
	v_xor_b32_e32 v10, 1, v0
	v_add_u32_e32 v1, 64, v1
	v_cmp_lt_i32_e32 vcc, v10, v1
	v_xor_b32_e32 v11, 2, v0
	v_xor_b32_e32 v12, 4, v0
	v_cndmask_b32_e32 v10, v0, v10, vcc
	v_lshlrev_b32_e32 v10, 2, v10
	v_cmp_lt_i32_e32 vcc, v11, v1
	v_xor_b32_e32 v13, 8, v0
	v_xor_b32_e32 v14, 16, v0
	v_xor_b32_e32 v15, 32, v0
	v_readlane_b32 s0, v254, 5
	v_readlane_b32 s1, v254, 6
	s_mov_b32 s1, 0
	v_writelane_b32 v254, s0, 5
	s_waitcnt vmcnt(0)
	v_mul_f32_e32 v4, v5, v4
	v_mul_f32_e32 v2, v6, v2
	v_cndmask_b32_e32 v6, v0, v11, vcc
	v_fmac_f32_e32 v2, v8, v7
	v_fmac_f32_e32 v4, v3, v9
	ds_bpermute_b32 v3, v10, v2
	ds_bpermute_b32 v5, v10, v4
	v_lshlrev_b32_e32 v6, 2, v6
	v_cmp_lt_i32_e32 vcc, v12, v1
	v_writelane_b32 v254, s1, 6
	s_waitcnt lgkmcnt(1)
	v_add_f32_e32 v2, v2, v3
	s_waitcnt lgkmcnt(0)
	v_add_f32_e32 v3, v4, v5
	ds_bpermute_b32 v4, v6, v2
	ds_bpermute_b32 v5, v6, v3
	v_cndmask_b32_e32 v6, v0, v12, vcc
	v_lshlrev_b32_e32 v6, 2, v6
	v_cmp_lt_i32_e32 vcc, v13, v1
	s_waitcnt lgkmcnt(1)
	v_add_f32_e32 v2, v2, v4
	s_waitcnt lgkmcnt(0)
	v_add_f32_e32 v3, v3, v5
	ds_bpermute_b32 v4, v6, v2
	ds_bpermute_b32 v5, v6, v3
	v_cndmask_b32_e32 v6, v0, v13, vcc
	v_lshlrev_b32_e32 v6, 2, v6
	v_cmp_lt_i32_e32 vcc, v14, v1
	s_waitcnt lgkmcnt(1)
	v_add_f32_e32 v2, v2, v4
	s_waitcnt lgkmcnt(0)
	v_add_f32_e32 v3, v3, v5
	ds_bpermute_b32 v4, v6, v2
	ds_bpermute_b32 v5, v6, v3
	v_cndmask_b32_e32 v6, v0, v14, vcc
	v_lshlrev_b32_e32 v6, 2, v6
	v_cmp_lt_i32_e32 vcc, v15, v1
	s_waitcnt lgkmcnt(1)
	v_add_f32_e32 v2, v2, v4
	s_waitcnt lgkmcnt(0)
	v_add_f32_e32 v3, v3, v5
	ds_bpermute_b32 v4, v6, v2
	ds_bpermute_b32 v5, v6, v3
	v_cndmask_b32_e32 v0, v0, v15, vcc
	v_lshlrev_b32_e32 v0, 2, v0
	s_waitcnt lgkmcnt(1)
	v_add_f32_e32 v1, v2, v4
	s_waitcnt lgkmcnt(0)
	v_add_f32_e32 v2, v3, v5
	ds_bpermute_b32 v3, v0, v1
	ds_bpermute_b32 v0, v0, v2
	s_waitcnt lgkmcnt(1)
	v_add_f32_e32 v1, v1, v3
	s_waitcnt lgkmcnt(0)
	v_add_f32_e32 v0, v2, v0
	v_mul_f32_e32 v1, 0x3fb8aa3b, v1
	v_mul_f32_e32 v0, 0x3fb8aa3b, v0
	v_exp_f32_e32 v1, v1
	v_exp_f32_e32 v0, v0
	s_nop 0
	v_sub_f32_e32 v0, v1, v0
	v_add_f32_e32 v0, s2, v0
	s_nop 0
	v_readfirstlane_b32 s2, v0
	s_cbranch_scc1 .LBB0_1269
	v_writelane_b32 v254, s4, 34
	s_add_u32 s0, s78, 0x3b400000
	v_mov_b32_e32 v217, 0
	v_writelane_b32 v254, s5, 35
	v_writelane_b32 v254, s82, 19
	s_mov_b32 s94, 0x4e800000
	s_mov_b32 s95, 0x7ffffff0
	v_writelane_b32 v254, s83, 20
	v_writelane_b32 v254, s80, 17
	s_mov_b64 s[30:31], 0x4b404000
	s_mov_b64 s[34:35], 0x4b404080
	v_writelane_b32 v254, s81, 18
	v_writelane_b32 v254, s0, 23
	s_addc_u32 s0, s79, 0
	s_add_u32 s33, s78, 0x4b400000
	v_writelane_b32 v254, s0, 24
	s_addc_u32 s0, s79, 0
	v_writelane_b32 v254, s0, 38
	s_add_u32 s0, s78, 0x5b400000
	v_writelane_b32 v254, s0, 39
	s_addc_u32 s0, s79, 0
	v_writelane_b32 v254, s0, 36
	s_add_u32 s0, s78, 0x53400000
	v_writelane_b32 v254, s0, 25
	s_addc_u32 s0, s79, 0
	s_ashr_i32 s91, s90, 31
	v_writelane_b32 v254, s0, 26
	s_lshl_b64 s[0:1], s[90:91], 18
	s_add_u32 s3, s78, s0
	v_readlane_b32 s6, v254, 5
	s_addc_u32 s4, s79, s1
	s_lshl_b32 s0, s6, 8
	s_add_i32 s23, s0, 0
	s_lshl_b32 s22, s6, 5
	s_add_i32 s23, s23, 0x18000
	s_bfe_u32 s0, s88, 0x20006
	s_cmp_lt_u32 s0, 2
	v_readlane_b32 s7, v254, 6
	s_cselect_b64 s[8:9], -1, 0
	s_lshl_b32 s24, s6, 10
	s_lshl_b32 s1, s6, 1
	s_and_b32 s25, s1, 0x7fffff8
	s_lshl_b32 s82, s0, 6
	s_add_i32 s83, s24, 0
	s_lshl_b64 s[0:1], s[6:7], 14
	s_add_u32 s0, s3, s0
	s_addc_u32 s1, s4, s1
	s_add_u32 s12, s0, 0x6b400000
	s_addc_u32 s13, s1, 0
	v_writelane_b32 v254, s8, 27
	s_add_u32 s26, s0, 0x6b420000
	s_mul_i32 s0, s6, 0x1e00
	v_writelane_b32 v254, s9, 28
	s_addc_u32 s27, s1, 0
	s_add_i32 s84, s83, s0
	s_lshl_b32 s0, s77, 2
	v_writelane_b32 v254, s0, 30
	s_lshl_b32 s0, s88, 3
	s_and_b32 s87, s0, 0xfffff800
	s_sub_i32 s0, s22, 64
	v_writelane_b32 v254, s0, 29
	s_lshl_b32 s0, s77, 5
	v_writelane_b32 v254, s0, 32
	s_mov_b32 s0, s90
	s_lshl_b32 s85, s90, 2
	s_lshl_b32 s89, s90, 5
	s_movk_i32 s88, 0x70
	s_add_i32 s92, 0, 0x10000
	s_mov_b64 s[36:37], 0x53404000
	s_mov_b64 s[38:39], 0x53405000
	s_mov_b64 s[40:41], 0x53406000
	s_mov_b64 s[42:43], 0x53407000
	s_mov_b64 s[44:45], 0x4b408000
	s_mov_b64 s[46:47], 0x4b408080
	s_mov_b64 s[48:49], 0x53408000
	s_mov_b64 s[50:51], 0x53409000
	s_mov_b64 s[52:53], 0x5340a000
	s_mov_b64 s[54:55], 0x5340b000
	s_mov_b64 s[56:57], 0x4b604000
	s_mov_b64 s[58:59], 0x4b604080
	s_mov_b64 s[60:61], 0x4b608000
	s_mov_b64 s[62:63], 0x4b608080
	v_mov_b32_e32 v224, 0x3727c5ac
	s_movk_i32 s6, 0x7fff
	v_mov_b32_e32 v225, 1
	v_mov_b32_e32 v226, 0xff800000
	v_writelane_b32 v254, s0, 21
	s_mov_b32 s7, s90
	s_nop 0
	v_writelane_b32 v254, s1, 22
	v_mbcnt_lo_u32_b32 v255, -1, 0
	v_mbcnt_hi_u32_b32 v255, -1, v255
	v_lshl_add_u32 v250, v255, 4, s24
	v_ashrrev_i32_e32 v251, 31, v250
	v_lshrrev_b32_e32 v251, 22, v251
	v_add_u32_e32 v251, v250, v251
	v_ashrrev_i32_e32 v251, 10, v251
	v_mul_i32_i24_e32 v252, 0x400, v251
	v_sub_u32_e32 v250, v250, v252
	v_lshrrev_b32_e32 v252, 4, v250
	v_bitop3_b32 v250, v252, v250, 32 bitop3:0x6c
	v_ashrrev_i32_e32 v252, 31, v250
	v_lshrrev_b32_e32 v252, 26, v252
	v_add_u32_e32 v252, v250, v252
	v_and_b32_e32 v253, 0xc0, v252
	v_sub_u32_e32 v250, v250, v253
	v_lshlrev_b32_e32 v253, 11, v251
	v_lshlrev_b32_e32 v252, 2, v252
	v_and_b32_e32 v253, 0xfffff000, v253
	v_and_b32_e32 v252, 0xffffff00, v252
	v_ashrrev_i16_sdwa v250, v225, sext(v250) dst_sel:DWORD dst_unused:UNUSED_PAD src0_sel:DWORD src1_sel:BYTE_0
	v_add_u32_e32 v252, v253, v252
	v_lshlrev_b32_e32 v251, 6, v251
	v_bfe_i32 v250, v250, 0, 16
	v_and_or_b32 v251, v251, 64, v252
	v_lshl_add_u32 v229, v250, 1, v251
	v_and_b32_e32 v252, 1, v255
	v_lshlrev_b32_e32 v250, 7, v255
	v_and_b32_e32 v250, 0x700, v250
	v_add_lshl_u32 v251, v255, s82, 1
	v_add_u32_e32 v250, s87, v250
	v_and_b32_e32 v251, 0xe0, v251
	v_lshlrev_b32_e32 v252, 4, v252
	v_add3_u32 v252, v250, v251, v252
	v_mov_b32_e32 v250, v229
	v_mov_b32_e32 v251, 0
	v_mov_b32_e32 v253, 0
	s_branch .LBB0_1124

.LBB0_1139:
	s_or_b32 s0, s18, 1
	s_cmp_ge_u32 s0, s16
	s_cbranch_scc1 .LBB0_1141
	s_add_u32 s0, s8, s76
	s_addc_u32 s1, s9, s77
	v_lshl_add_u64 v[192:193], s[0:1], 0, v[250:251]
	v_lshl_add_u64 v[194:195], v[192:193], 0, s[30:31]
	s_add_i32 m0, s83, 0x14000
	v_lshl_add_u64 v[192:193], v[192:193], 0, s[34:35]
	global_load_lds_dwordx4 v[194:195], off
	s_add_i32 m0, s83, 0x16000
	s_nop 0
	global_load_lds_dwordx4 v[192:193], off
	s_add_u32 s0, s86, s76
	s_addc_u32 s1, s90, s77
	v_lshl_add_u64 v[192:193], s[0:1], 0, v[252:253]
	v_lshl_add_u64 v[194:195], v[192:193], 0, s[36:37]
	s_add_i32 m0, s83, 0x8000
	s_nop 0
	global_load_lds_dwordx4 v[194:195], off
	v_lshl_add_u64 v[194:195], v[192:193], 0, s[38:39]
	s_add_i32 m0, s83, 0xa000
	s_nop 0
	global_load_lds_dwordx4 v[194:195], off
	v_lshl_add_u64 v[194:195], v[192:193], 0, s[40:41]
	s_add_i32 m0, s83, 0xc000
	v_lshl_add_u64 v[192:193], v[192:193], 0, s[42:43]
	global_load_lds_dwordx4 v[194:195], off
	s_add_i32 m0, s83, 0xe000
	s_nop 0
	global_load_lds_dwordx4 v[192:193], off

.LBB0_1148:
	ds_read_b128 v[202:205], v227 offset:0x7000
	ds_read_b128 v[206:209], v227 offset:0x7800
	s_waitcnt lgkmcnt(4)
	ds_read_b128 v[220:223], v227 offset:0x7400
	v_mfma_f32_16x16x32_bf16 v[210:213], v[192:195], v[0:3], v[176:179]
	ds_read_b128 v[230:233], v227 offset:0x7c00
	s_waitcnt lgkmcnt(4)
	v_mfma_f32_16x16x32_bf16 v[192:195], v[192:195], v[16:19], v[180:183]
	v_mfma_f32_16x16x32_bf16 v[176:179], v[188:191], v[0:3], v[176:179]
	v_mfma_f32_16x16x32_bf16 v[180:183], v[188:191], v[16:19], v[180:183]
	v_mfma_f32_16x16x32_bf16 v[188:191], v[196:199], v[4:7], v[210:213]
	s_waitcnt lgkmcnt(2)
	v_mfma_f32_16x16x32_bf16 v[176:179], v[184:187], v[4:7], v[176:179]
	v_mfma_f32_16x16x32_bf16 v[180:183], v[184:187], v[20:23], v[180:183]
	v_mfma_f32_16x16x32_bf16 v[192:195], v[196:199], v[20:23], v[192:195]
	v_mfma_f32_16x16x32_bf16 v[184:187], v[202:205], v[8:11], v[188:191]
	s_waitcnt lgkmcnt(0)
	v_mfma_f32_16x16x32_bf16 v[176:179], v[206:209], v[8:11], v[176:179]
	v_mfma_f32_16x16x32_bf16 v[192:195], v[202:205], v[24:27], v[192:195]
	v_mfma_f32_16x16x32_bf16 v[196:199], v[206:209], v[24:27], v[180:183]
	v_mfma_f32_16x16x32_bf16 v[188:191], v[220:223], v[12:15], v[184:187]
	v_mfma_f32_16x16x32_bf16 v[180:183], v[220:223], v[28:31], v[192:195]
	v_mfma_f32_16x16x32_bf16 v[184:187], v[230:233], v[12:15], v[176:179]
	v_mfma_f32_16x16x32_bf16 v[176:179], v[230:233], v[28:31], v[196:199]
	s_add_i32 s18, s18, 2
	s_cmp_ge_u32 s18, s16
	s_cselect_b64 s[4:5], -1, 0
	s_and_b64 vcc, exec, s[4:5]
	s_cbranch_vccnz .LBB0_1150
	s_add_u32 s0, s8, s76
	s_addc_u32 s1, s9, s77
	v_lshl_add_u64 v[192:193], s[0:1], 0, v[250:251]
	v_lshl_add_u64 v[194:195], v[192:193], 0, s[44:45]
	s_add_i32 m0, s83, 0x10000
	v_lshl_add_u64 v[192:193], v[192:193], 0, s[46:47]
	global_load_lds_dwordx4 v[194:195], off
	s_add_i32 m0, s83, 0x12000
	s_nop 0
	global_load_lds_dwordx4 v[192:193], off
	s_add_u32 s0, s86, s76
	s_addc_u32 s1, s90, s77
	v_lshl_add_u64 v[192:193], s[0:1], 0, v[252:253]
	v_lshl_add_u64 v[194:195], v[192:193], 0, s[48:49]
	s_mov_b32 m0, s83
	s_nop 0
	global_load_lds_dwordx4 v[194:195], off
	v_lshl_add_u64 v[194:195], v[192:193], 0, s[50:51]
	s_mov_b32 m0, s15
	s_nop 0
	global_load_lds_dwordx4 v[194:195], off
	v_lshl_add_u64 v[194:195], v[192:193], 0, s[52:53]
	s_mov_b32 m0, s20
	v_lshl_add_u64 v[192:193], v[192:193], 0, s[54:55]
	global_load_lds_dwordx4 v[194:195], off
	s_mov_b32 m0, s21
	s_nop 0
	global_load_lds_dwordx4 v[192:193], off

.LBB0_1175:
	s_or_b32 s0, s10, 1
	s_cmp_ge_u32 s0, s28
	s_cbranch_scc1 .LBB0_1177
	s_add_u32 s0, s8, s74
	s_addc_u32 s1, s9, s75
	v_lshl_add_u64 v[192:193], s[0:1], 0, v[250:251]
	v_lshl_add_u64 v[194:195], v[192:193], 0, s[30:31]
	s_add_i32 m0, s83, 0x14000
	v_lshl_add_u64 v[192:193], v[192:193], 0, s[34:35]
	global_load_lds_dwordx4 v[194:195], off
	s_add_i32 m0, s83, 0x16000
	s_nop 0
	global_load_lds_dwordx4 v[192:193], off
	s_add_u32 s0, s86, s74
	s_addc_u32 s1, s90, s75
	v_lshl_add_u64 v[192:193], s[0:1], 0, v[252:253]
	v_lshl_add_u64 v[194:195], v[192:193], 0, s[36:37]
	s_add_i32 m0, s83, 0x8000
	s_nop 0
	global_load_lds_dwordx4 v[194:195], off
	v_lshl_add_u64 v[194:195], v[192:193], 0, s[38:39]
	s_add_i32 m0, s83, 0xa000
	s_nop 0
	global_load_lds_dwordx4 v[194:195], off
	v_lshl_add_u64 v[194:195], v[192:193], 0, s[40:41]
	s_add_i32 m0, s83, 0xc000
	v_lshl_add_u64 v[192:193], v[192:193], 0, s[42:43]
	global_load_lds_dwordx4 v[194:195], off
	s_add_i32 m0, s83, 0xe000
	s_nop 0
	global_load_lds_dwordx4 v[192:193], off

.LBB0_1184:
	ds_read_b128 v[202:205], v227 offset:0x7000
	ds_read_b128 v[206:209], v227 offset:0x7800
	s_waitcnt lgkmcnt(4)
	ds_read_b128 v[220:223], v227 offset:0x7400
	v_mfma_f32_16x16x32_bf16 v[210:213], v[192:195], v[0:3], v[176:179]
	ds_read_b128 v[230:233], v227 offset:0x7c00
	s_waitcnt lgkmcnt(4)
	v_mfma_f32_16x16x32_bf16 v[192:195], v[192:195], v[16:19], v[180:183]
	v_mfma_f32_16x16x32_bf16 v[176:179], v[188:191], v[0:3], v[176:179]
	v_mfma_f32_16x16x32_bf16 v[180:183], v[188:191], v[16:19], v[180:183]
	v_mfma_f32_16x16x32_bf16 v[188:191], v[196:199], v[4:7], v[210:213]
	s_waitcnt lgkmcnt(2)
	v_mfma_f32_16x16x32_bf16 v[176:179], v[184:187], v[4:7], v[176:179]
	v_mfma_f32_16x16x32_bf16 v[180:183], v[184:187], v[20:23], v[180:183]
	v_mfma_f32_16x16x32_bf16 v[192:195], v[196:199], v[20:23], v[192:195]
	v_mfma_f32_16x16x32_bf16 v[184:187], v[202:205], v[8:11], v[188:191]
	s_waitcnt lgkmcnt(0)
	v_mfma_f32_16x16x32_bf16 v[176:179], v[206:209], v[8:11], v[176:179]
	v_mfma_f32_16x16x32_bf16 v[192:195], v[202:205], v[24:27], v[192:195]
	v_mfma_f32_16x16x32_bf16 v[196:199], v[206:209], v[24:27], v[180:183]
	v_mfma_f32_16x16x32_bf16 v[188:191], v[220:223], v[12:15], v[184:187]
	v_mfma_f32_16x16x32_bf16 v[180:183], v[220:223], v[28:31], v[192:195]
	v_mfma_f32_16x16x32_bf16 v[184:187], v[230:233], v[12:15], v[176:179]
	v_mfma_f32_16x16x32_bf16 v[176:179], v[230:233], v[28:31], v[196:199]
	s_add_i32 s10, s10, 2
	s_cmp_ge_u32 s10, s28
	s_cselect_b64 s[4:5], -1, 0
	s_and_b64 vcc, exec, s[4:5]
	s_cbranch_vccnz .LBB0_1186
	s_add_u32 s0, s8, s74
	s_addc_u32 s1, s9, s75
	v_lshl_add_u64 v[192:193], s[0:1], 0, v[250:251]
	v_lshl_add_u64 v[194:195], v[192:193], 0, s[44:45]
	s_add_i32 m0, s83, 0x10000
	v_lshl_add_u64 v[192:193], v[192:193], 0, s[46:47]
	global_load_lds_dwordx4 v[194:195], off
	s_add_i32 m0, s83, 0x12000
	s_nop 0
	global_load_lds_dwordx4 v[192:193], off
	s_add_u32 s0, s86, s74
	s_addc_u32 s1, s90, s75
	v_lshl_add_u64 v[192:193], s[0:1], 0, v[252:253]
	v_lshl_add_u64 v[194:195], v[192:193], 0, s[48:49]
	s_mov_b32 m0, s83
	s_nop 0
	global_load_lds_dwordx4 v[194:195], off
	v_lshl_add_u64 v[194:195], v[192:193], 0, s[50:51]
	s_mov_b32 m0, s15
	s_nop 0
	global_load_lds_dwordx4 v[194:195], off
	v_lshl_add_u64 v[194:195], v[192:193], 0, s[52:53]
	s_mov_b32 m0, s20
	v_lshl_add_u64 v[192:193], v[192:193], 0, s[54:55]
	global_load_lds_dwordx4 v[194:195], off
	s_mov_b32 m0, s21
	s_nop 0
	global_load_lds_dwordx4 v[192:193], off

.LBB0_1211:
	s_or_b32 s0, s11, 1
	s_cmp_ge_u32 s0, s16
	s_cbranch_scc1 .LBB0_1213
	s_add_u32 s0, s8, s74
	s_addc_u32 s1, s9, s75
	v_lshl_add_u64 v[192:193], s[0:1], 0, v[250:251]
	v_lshl_add_u64 v[194:195], v[192:193], 0, s[56:57]
	s_add_i32 m0, s83, 0x14000
	v_lshl_add_u64 v[192:193], v[192:193], 0, s[58:59]
	global_load_lds_dwordx4 v[194:195], off
	s_add_i32 m0, s83, 0x16000
	s_nop 0
	global_load_lds_dwordx4 v[192:193], off
	s_add_u32 s0, s86, s74
	s_addc_u32 s1, s90, s75
	v_lshl_add_u64 v[192:193], s[0:1], 0, v[252:253]
	v_lshl_add_u64 v[194:195], v[192:193], 0, s[36:37]
	s_add_i32 m0, s83, 0x8000
	s_nop 0
	global_load_lds_dwordx4 v[194:195], off
	v_lshl_add_u64 v[194:195], v[192:193], 0, s[38:39]
	s_add_i32 m0, s83, 0xa000
	s_nop 0
	global_load_lds_dwordx4 v[194:195], off
	v_lshl_add_u64 v[194:195], v[192:193], 0, s[40:41]
	s_add_i32 m0, s83, 0xc000
	v_lshl_add_u64 v[192:193], v[192:193], 0, s[42:43]
	global_load_lds_dwordx4 v[194:195], off
	s_add_i32 m0, s83, 0xe000
	s_nop 0
	global_load_lds_dwordx4 v[192:193], off

.LBB0_1220:
	ds_read_b128 v[202:205], v227 offset:0x7000
	ds_read_b128 v[206:209], v227 offset:0x7800
	s_waitcnt lgkmcnt(4)
	ds_read_b128 v[220:223], v227 offset:0x7400
	v_mfma_f32_16x16x32_bf16 v[210:213], v[192:195], v[0:3], v[176:179]
	ds_read_b128 v[230:233], v227 offset:0x7c00
	s_waitcnt lgkmcnt(4)
	v_mfma_f32_16x16x32_bf16 v[192:195], v[192:195], v[16:19], v[180:183]
	v_mfma_f32_16x16x32_bf16 v[176:179], v[188:191], v[0:3], v[176:179]
	v_mfma_f32_16x16x32_bf16 v[180:183], v[188:191], v[16:19], v[180:183]
	v_mfma_f32_16x16x32_bf16 v[188:191], v[196:199], v[4:7], v[210:213]
	s_waitcnt lgkmcnt(2)
	v_mfma_f32_16x16x32_bf16 v[176:179], v[184:187], v[4:7], v[176:179]
	v_mfma_f32_16x16x32_bf16 v[180:183], v[184:187], v[20:23], v[180:183]
	v_mfma_f32_16x16x32_bf16 v[192:195], v[196:199], v[20:23], v[192:195]
	v_mfma_f32_16x16x32_bf16 v[184:187], v[202:205], v[8:11], v[188:191]
	s_waitcnt lgkmcnt(0)
	v_mfma_f32_16x16x32_bf16 v[176:179], v[206:209], v[8:11], v[176:179]
	v_mfma_f32_16x16x32_bf16 v[192:195], v[202:205], v[24:27], v[192:195]
	v_mfma_f32_16x16x32_bf16 v[196:199], v[206:209], v[24:27], v[180:183]
	v_mfma_f32_16x16x32_bf16 v[188:191], v[220:223], v[12:15], v[184:187]
	v_mfma_f32_16x16x32_bf16 v[180:183], v[220:223], v[28:31], v[192:195]
	v_mfma_f32_16x16x32_bf16 v[184:187], v[230:233], v[12:15], v[176:179]
	v_mfma_f32_16x16x32_bf16 v[176:179], v[230:233], v[28:31], v[196:199]
	s_add_i32 s11, s11, 2
	s_cmp_ge_u32 s11, s16
	s_cselect_b64 s[4:5], -1, 0
	s_and_b64 vcc, exec, s[4:5]
	s_cbranch_vccnz .LBB0_1222
	s_add_u32 s0, s8, s74
	s_addc_u32 s1, s9, s75
	v_lshl_add_u64 v[192:193], s[0:1], 0, v[250:251]
	v_lshl_add_u64 v[194:195], v[192:193], 0, s[60:61]
	s_add_i32 m0, s83, 0x10000
	v_lshl_add_u64 v[192:193], v[192:193], 0, s[62:63]
	global_load_lds_dwordx4 v[194:195], off
	s_add_i32 m0, s83, 0x12000
	s_nop 0
	global_load_lds_dwordx4 v[192:193], off
	s_add_u32 s0, s86, s74
	s_addc_u32 s1, s90, s75
	v_lshl_add_u64 v[192:193], s[0:1], 0, v[252:253]
	v_lshl_add_u64 v[194:195], v[192:193], 0, s[48:49]
	s_mov_b32 m0, s83
	s_nop 0
	global_load_lds_dwordx4 v[194:195], off
	v_lshl_add_u64 v[194:195], v[192:193], 0, s[50:51]
	s_mov_b32 m0, s15
	s_nop 0
	global_load_lds_dwordx4 v[194:195], off
	v_lshl_add_u64 v[194:195], v[192:193], 0, s[52:53]
	s_mov_b32 m0, s20
	v_lshl_add_u64 v[192:193], v[192:193], 0, s[54:55]
	global_load_lds_dwordx4 v[194:195], off
	s_mov_b32 m0, s21
	s_nop 0
	global_load_lds_dwordx4 v[192:193], off

.LBB0_1247:
	s_or_b32 s0, s10, 1
	s_cmp_ge_u32 s0, s28
	s_cbranch_scc1 .LBB0_1249
	s_add_u32 s0, s8, s64
	s_addc_u32 s1, s9, s65
	v_lshl_add_u64 v[192:193], s[0:1], 0, v[250:251]
	v_lshl_add_u64 v[194:195], v[192:193], 0, s[56:57]
	s_add_i32 m0, s83, 0x14000
	v_lshl_add_u64 v[192:193], v[192:193], 0, s[58:59]
	global_load_lds_dwordx4 v[194:195], off
	s_add_i32 m0, s83, 0x16000
	s_nop 0
	global_load_lds_dwordx4 v[192:193], off
	s_add_u32 s0, s86, s64
	s_addc_u32 s1, s90, s65
	v_lshl_add_u64 v[192:193], s[0:1], 0, v[252:253]
	v_lshl_add_u64 v[194:195], v[192:193], 0, s[36:37]
	s_add_i32 m0, s83, 0x8000
	s_nop 0
	global_load_lds_dwordx4 v[194:195], off
	v_lshl_add_u64 v[194:195], v[192:193], 0, s[38:39]
	s_add_i32 m0, s83, 0xa000
	s_nop 0
	global_load_lds_dwordx4 v[194:195], off
	v_lshl_add_u64 v[194:195], v[192:193], 0, s[40:41]
	s_add_i32 m0, s83, 0xc000
	v_lshl_add_u64 v[192:193], v[192:193], 0, s[42:43]
	global_load_lds_dwordx4 v[194:195], off
	s_add_i32 m0, s83, 0xe000
	s_nop 0
	global_load_lds_dwordx4 v[192:193], off

.LBB0_1256:
	ds_read_b128 v[202:205], v227 offset:0x7000
	ds_read_b128 v[206:209], v227 offset:0x7800
	s_waitcnt lgkmcnt(4)
	ds_read_b128 v[220:223], v227 offset:0x7400
	v_mfma_f32_16x16x32_bf16 v[210:213], v[192:195], v[0:3], v[176:179]
	ds_read_b128 v[230:233], v227 offset:0x7c00
	s_waitcnt lgkmcnt(4)
	v_mfma_f32_16x16x32_bf16 v[192:195], v[192:195], v[16:19], v[180:183]
	v_mfma_f32_16x16x32_bf16 v[176:179], v[188:191], v[0:3], v[176:179]
	v_mfma_f32_16x16x32_bf16 v[180:183], v[188:191], v[16:19], v[180:183]
	v_mfma_f32_16x16x32_bf16 v[188:191], v[196:199], v[4:7], v[210:213]
	s_waitcnt lgkmcnt(2)
	v_mfma_f32_16x16x32_bf16 v[176:179], v[184:187], v[4:7], v[176:179]
	v_mfma_f32_16x16x32_bf16 v[180:183], v[184:187], v[20:23], v[180:183]
	v_mfma_f32_16x16x32_bf16 v[192:195], v[196:199], v[20:23], v[192:195]
	v_mfma_f32_16x16x32_bf16 v[184:187], v[202:205], v[8:11], v[188:191]
	s_waitcnt lgkmcnt(0)
	v_mfma_f32_16x16x32_bf16 v[176:179], v[206:209], v[8:11], v[176:179]
	v_mfma_f32_16x16x32_bf16 v[192:195], v[202:205], v[24:27], v[192:195]
	v_mfma_f32_16x16x32_bf16 v[196:199], v[206:209], v[24:27], v[180:183]
	v_mfma_f32_16x16x32_bf16 v[188:191], v[220:223], v[12:15], v[184:187]
	v_mfma_f32_16x16x32_bf16 v[180:183], v[220:223], v[28:31], v[192:195]
	v_mfma_f32_16x16x32_bf16 v[184:187], v[230:233], v[12:15], v[176:179]
	v_mfma_f32_16x16x32_bf16 v[176:179], v[230:233], v[28:31], v[196:199]
	s_add_i32 s10, s10, 2
	s_cmp_ge_u32 s10, s28
	s_cselect_b64 s[4:5], -1, 0
	s_and_b64 vcc, exec, s[4:5]
	s_cbranch_vccnz .LBB0_1258
	s_add_u32 s0, s8, s64
	s_addc_u32 s1, s9, s65
	v_lshl_add_u64 v[192:193], s[0:1], 0, v[250:251]
	v_lshl_add_u64 v[194:195], v[192:193], 0, s[60:61]
	s_add_i32 m0, s83, 0x10000
	v_lshl_add_u64 v[192:193], v[192:193], 0, s[62:63]
	global_load_lds_dwordx4 v[194:195], off
	s_add_i32 m0, s83, 0x12000
	s_nop 0
	global_load_lds_dwordx4 v[192:193], off
	s_add_u32 s0, s86, s64
	s_addc_u32 s1, s90, s65
	v_lshl_add_u64 v[192:193], s[0:1], 0, v[252:253]
	v_lshl_add_u64 v[194:195], v[192:193], 0, s[48:49]
	s_mov_b32 m0, s83
	s_nop 0
	global_load_lds_dwordx4 v[194:195], off
	v_lshl_add_u64 v[194:195], v[192:193], 0, s[50:51]
	s_mov_b32 m0, s15
	s_nop 0
	global_load_lds_dwordx4 v[194:195], off
	v_lshl_add_u64 v[194:195], v[192:193], 0, s[52:53]
	s_mov_b32 m0, s20
	v_lshl_add_u64 v[192:193], v[192:193], 0, s[54:55]
	global_load_lds_dwordx4 v[194:195], off
	s_mov_b32 m0, s21
	s_nop 0
	global_load_lds_dwordx4 v[192:193], off

.LBB0_1729:
	ds_read_b128 v[2:5], v153
	ds_read_b128 v[6:9], v153 offset:1024
	ds_read_b128 v[10:13], v153 offset:2048
	ds_read_b128 v[14:17], v153 offset:3072
	ds_read_b128 v[18:21], v154
	ds_read_b128 v[22:25], v154 offset:1024
	ds_read_b128 v[26:29], v154 offset:2048
	ds_read_b128 v[30:33], v154 offset:3072
	s_add_u32 s0, s44, 0x10000
	s_addc_u32 s1, s45, 0
	ds_read_b128 v[34:37], v155
	ds_read_b128 v[38:41], v155 offset:1024
	ds_read_b128 v[42:45], v155 offset:2048
	ds_read_b128 v[46:49], v155 offset:3072
	ds_read_b128 v[50:53], v155 offset:4096
	ds_read_b128 v[54:57], v155 offset:5120
	ds_read_b128 v[58:61], v155 offset:6144
	ds_read_b128 v[62:65], v155 offset:7168
	s_waitcnt vmcnt(24)
	s_waitcnt lgkmcnt(0)
	s_setprio 1
	s_barrier
	v_mfma_f32_16x16x32_bf16 v[66:69], v[2:5], v[34:37], 0
	v_mfma_f32_16x16x32_bf16 v[70:73], v[10:13], v[34:37], 0
	v_mfma_f32_16x16x32_bf16 v[74:77], v[2:5], v[42:45], 0
	v_mfma_f32_16x16x32_bf16 v[78:81], v[10:13], v[42:45], 0
	v_mfma_f32_16x16x32_bf16 v[82:85], v[2:5], v[50:53], 0
	v_mfma_f32_16x16x32_bf16 v[86:89], v[10:13], v[50:53], 0
	v_mfma_f32_16x16x32_bf16 v[90:93], v[2:5], v[58:61], 0
	v_mfma_f32_16x16x32_bf16 v[94:97], v[10:13], v[58:61], 0
	v_mfma_f32_16x16x32_bf16 v[66:69], v[6:9], v[38:41], v[66:69]
	v_mfma_f32_16x16x32_bf16 v[70:73], v[14:17], v[38:41], v[70:73]
	v_mfma_f32_16x16x32_bf16 v[74:77], v[6:9], v[46:49], v[74:77]
	v_mfma_f32_16x16x32_bf16 v[78:81], v[14:17], v[46:49], v[78:81]
	v_mfma_f32_16x16x32_bf16 v[82:85], v[6:9], v[54:57], v[82:85]
	v_mfma_f32_16x16x32_bf16 v[86:89], v[14:17], v[54:57], v[86:89]
	v_mfma_f32_16x16x32_bf16 v[90:93], v[6:9], v[62:65], v[90:93]
	v_mfma_f32_16x16x32_bf16 v[104:107], v[14:17], v[62:65], v[94:97]
	v_mfma_f32_16x16x32_bf16 v[94:97], v[18:21], v[34:37], 0
	v_mfma_f32_16x16x32_bf16 v[34:37], v[26:29], v[34:37], 0
	v_mfma_f32_16x16x32_bf16 v[108:111], v[22:25], v[38:41], v[94:97]
	v_mfma_f32_16x16x32_bf16 v[34:37], v[30:33], v[38:41], v[34:37]
	v_mfma_f32_16x16x32_bf16 v[38:41], v[18:21], v[42:45], 0
	v_mfma_f32_16x16x32_bf16 v[42:45], v[26:29], v[42:45], 0
	v_mfma_f32_16x16x32_bf16 v[38:41], v[22:25], v[46:49], v[38:41]
	v_mfma_f32_16x16x32_bf16 v[42:45], v[30:33], v[46:49], v[42:45]
	v_mfma_f32_16x16x32_bf16 v[46:49], v[18:21], v[50:53], 0
	v_mfma_f32_16x16x32_bf16 v[50:53], v[26:29], v[50:53], 0
	v_mfma_f32_16x16x32_bf16 v[46:49], v[22:25], v[54:57], v[46:49]
	v_mfma_f32_16x16x32_bf16 v[50:53], v[30:33], v[54:57], v[50:53]
	v_mfma_f32_16x16x32_bf16 v[54:57], v[18:21], v[58:61], 0
	v_mfma_f32_16x16x32_bf16 v[58:61], v[26:29], v[58:61], 0
	v_mfma_f32_16x16x32_bf16 v[54:57], v[22:25], v[62:65], v[54:57]
	v_mfma_f32_16x16x32_bf16 v[58:61], v[30:33], v[62:65], v[58:61]
	s_barrier
	s_setprio 0
	s_add_i32 s12, s52, s17
	v_lshl_add_u64 v[102:103], s[0:1], 0, v[134:135]
	s_mov_b32 m0, s12
	ds_read_b128 v[62:65], v155 offset:16384
	ds_read_b128 v[94:97], v155 offset:17408
	ds_read_b128 v[98:101], v155 offset:18432
	ds_read_b128 v[112:115], v155 offset:19456
	ds_read_b128 v[116:119], v155 offset:20480
	ds_read_b128 v[120:123], v155 offset:21504
	ds_read_b128 v[124:127], v155 offset:22528
	ds_read_b128 v[128:131], v155 offset:23552
	global_load_lds_dwordx4 v[102:103], off
	s_add_i32 m0, s12, 0x2000
	v_lshl_add_u64 v[102:103], s[0:1], 0, v[138:139]
	s_add_u32 s0, s44, 0x14000
	s_addc_u32 s1, s45, 0
	s_add_i32 s12, s53, s17
	global_load_lds_dwordx4 v[102:103], off
	v_lshl_add_u64 v[102:103], s[0:1], 0, v[134:135]
	s_mov_b32 m0, s12
	v_lshl_add_u64 v[148:149], s[46:47], 0, v[132:133]
	global_load_lds_dwordx4 v[102:103], off
	v_lshl_add_u64 v[102:103], s[0:1], 0, v[138:139]
	s_add_i32 m0, s12, 0x2000
	v_lshl_add_u64 v[144:145], s[46:47], 0, v[136:137]
	global_load_lds_dwordx4 v[102:103], off
	v_lshl_add_u64 v[102:103], v[148:149], 0, s[38:39]
	s_mov_b32 m0, s18
	s_nop 0
	global_load_lds_dwordx4 v[102:103], off
	v_lshl_add_u64 v[102:103], v[144:145], 0, s[38:39]
	s_mov_b32 m0, s19
	s_nop 0
	global_load_lds_dwordx4 v[102:103], off
	s_waitcnt vmcnt(24)
	s_waitcnt lgkmcnt(0)
	s_setprio 1
	s_barrier
	v_mfma_f32_16x16x32_bf16 v[158:161], v[2:5], v[62:65], 0
	v_mfma_f32_16x16x32_bf16 v[166:169], v[2:5], v[98:101], 0
	v_mfma_f32_16x16x32_bf16 v[174:177], v[2:5], v[116:119], 0
	v_mfma_f32_16x16x32_bf16 v[2:5], v[2:5], v[124:127], 0
	v_mfma_f32_16x16x32_bf16 v[158:161], v[6:9], v[94:97], v[158:161]
	v_mfma_f32_16x16x32_bf16 v[166:169], v[6:9], v[112:115], v[166:169]
	v_mfma_f32_16x16x32_bf16 v[174:177], v[6:9], v[120:123], v[174:177]
	v_mfma_f32_16x16x32_bf16 v[2:5], v[6:9], v[128:131], v[2:5]
	v_mfma_f32_16x16x32_bf16 v[6:9], v[10:13], v[124:127], 0
	v_mfma_f32_16x16x32_bf16 v[162:165], v[10:13], v[62:65], 0
	v_mfma_f32_16x16x32_bf16 v[170:173], v[10:13], v[98:101], 0
	v_mfma_f32_16x16x32_bf16 v[178:181], v[10:13], v[116:119], 0
	v_mfma_f32_16x16x32_bf16 v[6:9], v[14:17], v[128:131], v[6:9]
	v_mfma_f32_16x16x32_bf16 v[162:165], v[14:17], v[94:97], v[162:165]
	v_mfma_f32_16x16x32_bf16 v[170:173], v[14:17], v[112:115], v[170:173]
	v_mfma_f32_16x16x32_bf16 v[178:181], v[14:17], v[120:123], v[178:181]
	v_mfma_f32_16x16x32_bf16 v[14:17], v[26:29], v[62:65], 0
	v_mfma_f32_16x16x32_bf16 v[182:185], v[30:33], v[94:97], v[14:17]
	v_mfma_f32_16x16x32_bf16 v[14:17], v[18:21], v[98:101], 0
	v_mfma_f32_16x16x32_bf16 v[186:189], v[22:25], v[112:115], v[14:17]
	v_mfma_f32_16x16x32_bf16 v[14:17], v[26:29], v[98:101], 0
	v_mfma_f32_16x16x32_bf16 v[190:193], v[30:33], v[112:115], v[14:17]
	v_mfma_f32_16x16x32_bf16 v[14:17], v[18:21], v[116:119], 0
	v_mfma_f32_16x16x32_bf16 v[194:197], v[22:25], v[120:123], v[14:17]
	v_mfma_f32_16x16x32_bf16 v[14:17], v[26:29], v[116:119], 0
	v_mfma_f32_16x16x32_bf16 v[10:13], v[18:21], v[62:65], 0
	v_mfma_f32_16x16x32_bf16 v[198:201], v[30:33], v[120:123], v[14:17]
	v_mfma_f32_16x16x32_bf16 v[14:17], v[18:21], v[124:127], 0
	v_mfma_f32_16x16x32_bf16 v[10:13], v[22:25], v[94:97], v[10:13]
	v_mfma_f32_16x16x32_bf16 v[202:205], v[22:25], v[128:131], v[14:17]
	v_mfma_f32_16x16x32_bf16 v[14:17], v[26:29], v[124:127], 0
	v_mfma_f32_16x16x32_bf16 v[206:209], v[30:33], v[128:131], v[14:17]
	s_barrier
	s_setprio 0
	s_add_i32 s12, 0, 0x18000
	v_add_u32_e32 v1, s12, v151
	s_add_i32 s13, 0, 0x1c000
	s_nop 1
	ds_read_b128 v[14:17], v1
	ds_read_b128 v[24:27], v1 offset:1024
	ds_read_b128 v[28:31], v1 offset:2048
	ds_read_b128 v[210:213], v1 offset:3072
	v_add_u32_e32 v1, s13, v151
	ds_read_b128 v[214:217], v1
	ds_read_b128 v[218:221], v1 offset:1024
	ds_read_b128 v[222:225], v1 offset:2048
	ds_read_b128 v[226:229], v1 offset:3072
	s_add_u32 s0, s46, 0x2b0100
	s_addc_u32 s1, s47, 0
	s_mov_b32 m0, s20
	v_lshl_add_u64 v[22:23], s[0:1], 0, v[132:133]
	ds_read_b128 v[18:21], v155 offset:32768
	ds_read_b128 v[120:123], v155 offset:33792
	ds_read_b128 v[230:233], v155 offset:34816
	ds_read_b128 v[234:237], v155 offset:35840
	ds_read_b128 v[238:241], v155 offset:36864
	ds_read_b128 v[242:245], v155 offset:37888
	ds_read_b128 v[246:249], v155 offset:38912
	ds_read_b128 v[250:253], v155 offset:39936
	global_load_lds_dwordx4 v[22:23], off
	v_lshl_add_u64 v[22:23], s[0:1], 0, v[136:137]
	s_mov_b32 m0, s21
	s_nop 0
	global_load_lds_dwordx4 v[22:23], off
	s_waitcnt vmcnt(24)
	s_waitcnt lgkmcnt(0)
	s_setprio 1
	s_barrier
	v_mfma_f32_16x16x32_bf16 v[62:65], v[14:17], v[18:21], v[66:69]
	v_mfma_f32_16x16x32_bf16 v[128:131], v[24:27], v[120:123], v[62:65]
	v_mfma_f32_16x16x32_bf16 v[62:65], v[28:31], v[18:21], v[70:73]
	v_mfma_f32_16x16x32_bf16 v[116:119], v[210:213], v[120:123], v[62:65]
	v_mfma_f32_16x16x32_bf16 v[62:65], v[14:17], v[230:233], v[74:77]
	v_mfma_f32_16x16x32_bf16 v[112:115], v[24:27], v[234:237], v[62:65]
	v_mfma_f32_16x16x32_bf16 v[62:65], v[28:31], v[230:233], v[78:81]
	v_mfma_f32_16x16x32_bf16 v[100:103], v[210:213], v[234:237], v[62:65]
	v_mfma_f32_16x16x32_bf16 v[62:65], v[14:17], v[238:241], v[82:85]
	v_mfma_f32_16x16x32_bf16 v[96:99], v[24:27], v[242:245], v[62:65]
	v_mfma_f32_16x16x32_bf16 v[62:65], v[28:31], v[238:241], v[86:89]
	v_mfma_f32_16x16x32_bf16 v[84:87], v[210:213], v[242:245], v[62:65]
	v_mfma_f32_16x16x32_bf16 v[62:65], v[14:17], v[246:249], v[90:93]
	v_mfma_f32_16x16x32_bf16 v[80:83], v[24:27], v[250:253], v[62:65]
	v_mfma_f32_16x16x32_bf16 v[62:65], v[28:31], v[246:249], v[104:107]
	v_mfma_f32_16x16x32_bf16 v[64:67], v[210:213], v[250:253], v[62:65]
	v_mfma_f32_16x16x32_bf16 v[68:71], v[214:217], v[18:21], v[108:111]
	v_mfma_f32_16x16x32_bf16 v[18:21], v[222:225], v[18:21], v[34:37]
	v_mfma_f32_16x16x32_bf16 v[124:127], v[218:221], v[120:123], v[68:71]
	v_mfma_f32_16x16x32_bf16 v[120:123], v[226:229], v[120:123], v[18:21]
	v_mfma_f32_16x16x32_bf16 v[18:21], v[214:217], v[230:233], v[38:41]
	v_mfma_f32_16x16x32_bf16 v[108:111], v[218:221], v[234:237], v[18:21]
	v_mfma_f32_16x16x32_bf16 v[18:21], v[222:225], v[230:233], v[42:45]
	v_mfma_f32_16x16x32_bf16 v[104:107], v[226:229], v[234:237], v[18:21]
	v_mfma_f32_16x16x32_bf16 v[18:21], v[214:217], v[238:241], v[46:49]
	v_mfma_f32_16x16x32_bf16 v[92:95], v[218:221], v[242:245], v[18:21]
	v_mfma_f32_16x16x32_bf16 v[18:21], v[222:225], v[238:241], v[50:53]
	v_mfma_f32_16x16x32_bf16 v[88:91], v[226:229], v[242:245], v[18:21]
	v_mfma_f32_16x16x32_bf16 v[18:21], v[214:217], v[246:249], v[54:57]
	v_mfma_f32_16x16x32_bf16 v[72:75], v[218:221], v[250:253], v[18:21]
	v_mfma_f32_16x16x32_bf16 v[18:21], v[222:225], v[246:249], v[58:61]
	v_mfma_f32_16x16x32_bf16 v[68:71], v[226:229], v[250:253], v[18:21]
	s_barrier
	s_setprio 0
	s_add_u32 s0, s44, 0x18000
	s_addc_u32 s1, s45, 0
	s_add_i32 s12, s12, s17
	s_nop 1
	v_lshl_add_u64 v[18:19], s[0:1], 0, v[134:135]
	s_mov_b32 m0, s12
	ds_read_b128 v[40:43], v155 offset:49152
	ds_read_b128 v[44:47], v155 offset:50176
	ds_read_b128 v[230:233], v155 offset:51200
	ds_read_b128 v[234:237], v155 offset:52224
	ds_read_b128 v[238:241], v155 offset:53248
	ds_read_b128 v[242:245], v155 offset:54272
	ds_read_b128 v[246:249], v155 offset:55296
	ds_read_b128 v[250:253], v155 offset:56320
	global_load_lds_dwordx4 v[18:19], off
	s_add_i32 m0, s12, 0x2000
	v_lshl_add_u64 v[18:19], s[0:1], 0, v[138:139]
	s_add_u32 s0, s44, 0x1c000
	s_addc_u32 s1, s45, 0
	s_add_i32 s12, s13, s17
	global_load_lds_dwordx4 v[18:19], off
	v_lshl_add_u64 v[18:19], s[0:1], 0, v[134:135]
	s_mov_b32 m0, s12
	s_nop 0
	global_load_lds_dwordx4 v[18:19], off
	v_lshl_add_u64 v[18:19], s[0:1], 0, v[138:139]
	s_add_i32 m0, s12, 0x2000
	s_nop 0
	global_load_lds_dwordx4 v[18:19], off
	v_lshl_add_u64 v[18:19], v[148:149], 0, s[40:41]
	s_mov_b32 m0, s48
	s_nop 0
	global_load_lds_dwordx4 v[18:19], off
	v_lshl_add_u64 v[18:19], v[144:145], 0, s[40:41]
	s_mov_b32 m0, s49
	s_nop 0
	global_load_lds_dwordx4 v[18:19], off
	s_waitcnt vmcnt(8)
	s_waitcnt lgkmcnt(0)
	s_setprio 1
	s_barrier
	v_mfma_f32_16x16x32_bf16 v[18:21], v[14:17], v[40:43], v[158:161]
	v_mfma_f32_16x16x32_bf16 v[76:79], v[24:27], v[44:47], v[18:21]
	v_mfma_f32_16x16x32_bf16 v[18:21], v[28:31], v[40:43], v[162:165]
	v_mfma_f32_16x16x32_bf16 v[52:55], v[210:213], v[44:47], v[18:21]
	v_mfma_f32_16x16x32_bf16 v[18:21], v[14:17], v[230:233], v[166:169]
	v_mfma_f32_16x16x32_bf16 v[48:51], v[24:27], v[234:237], v[18:21]
	v_mfma_f32_16x16x32_bf16 v[18:21], v[28:31], v[230:233], v[170:173]
	v_mfma_f32_16x16x32_bf16 v[36:39], v[210:213], v[234:237], v[18:21]
	v_mfma_f32_16x16x32_bf16 v[18:21], v[14:17], v[238:241], v[174:177]
	v_mfma_f32_16x16x32_bf16 v[32:35], v[24:27], v[242:245], v[18:21]
	v_mfma_f32_16x16x32_bf16 v[18:21], v[28:31], v[238:241], v[178:181]
	v_mfma_f32_16x16x32_bf16 v[2:5], v[14:17], v[246:249], v[2:5]
	v_mfma_f32_16x16x32_bf16 v[20:23], v[210:213], v[242:245], v[18:21]
	v_mfma_f32_16x16x32_bf16 v[16:19], v[24:27], v[250:253], v[2:5]
	v_mfma_f32_16x16x32_bf16 v[2:5], v[28:31], v[246:249], v[6:9]
	v_mfma_f32_16x16x32_bf16 v[4:7], v[210:213], v[250:253], v[2:5]
	v_mfma_f32_16x16x32_bf16 v[8:11], v[214:217], v[40:43], v[10:13]
	v_mfma_f32_16x16x32_bf16 v[60:63], v[218:221], v[44:47], v[8:11]
	v_mfma_f32_16x16x32_bf16 v[8:11], v[222:225], v[40:43], v[182:185]
	v_mfma_f32_16x16x32_bf16 v[56:59], v[226:229], v[44:47], v[8:11]
	v_mfma_f32_16x16x32_bf16 v[8:11], v[214:217], v[230:233], v[186:189]
	v_mfma_f32_16x16x32_bf16 v[44:47], v[218:221], v[234:237], v[8:11]
	v_mfma_f32_16x16x32_bf16 v[8:11], v[222:225], v[230:233], v[190:193]
	v_mfma_f32_16x16x32_bf16 v[40:43], v[226:229], v[234:237], v[8:11]
	v_mfma_f32_16x16x32_bf16 v[8:11], v[214:217], v[238:241], v[194:197]
	v_mfma_f32_16x16x32_bf16 v[28:31], v[218:221], v[242:245], v[8:11]
	v_mfma_f32_16x16x32_bf16 v[8:11], v[222:225], v[238:241], v[198:201]
	v_mfma_f32_16x16x32_bf16 v[24:27], v[226:229], v[242:245], v[8:11]
	v_mfma_f32_16x16x32_bf16 v[8:11], v[214:217], v[246:249], v[202:205]
	v_mfma_f32_16x16x32_bf16 v[12:15], v[218:221], v[250:253], v[8:11]
	v_mfma_f32_16x16x32_bf16 v[8:11], v[222:225], v[246:249], v[206:209]
	v_mfma_f32_16x16x32_bf16 v[8:11], v[226:229], v[250:253], v[8:11]
	s_barrier
	s_setprio 0
	s_mov_b32 s22, 2
	s_branch .LBB0_1733

.LBB0_1734:
	ds_read_b128 v[158:161], v153
	ds_read_b128 v[162:165], v153 offset:1024
	ds_read_b128 v[166:169], v153 offset:2048
	ds_read_b128 v[170:173], v153 offset:3072
	ds_read_b128 v[174:177], v154
	ds_read_b128 v[178:181], v154 offset:1024
	ds_read_b128 v[182:185], v154 offset:2048
	ds_read_b128 v[186:189], v154 offset:3072
	s_add_u32 s12, s60, s24
	s_addc_u32 s13, s61, 0
	s_cmp_eq_u32 s24, s44
	s_cselect_b32 s23, s9, s13
	s_cselect_b32 s22, s8, s12
	s_cselect_b32 s47, s43, s59
	s_cselect_b32 s46, s42, s1
	s_add_i32 s63, s18, 0xc000
	v_lshl_add_u64 v[144:145], v[2:3], 0, s[24:25]
	s_mov_b32 m0, s63
	s_add_i32 s62, s18, 0xe000
	ds_read_b128 v[190:193], v155
	ds_read_b128 v[194:197], v155 offset:1024
	ds_read_b128 v[198:201], v155 offset:2048
	ds_read_b128 v[202:205], v155 offset:3072
	ds_read_b128 v[206:209], v155 offset:4096
	ds_read_b128 v[210:213], v155 offset:5120
	ds_read_b128 v[214:217], v155 offset:6144
	ds_read_b128 v[218:221], v155 offset:7168
	global_load_lds_dwordx4 v[144:145], off
	v_lshl_add_u64 v[144:145], v[148:149], 0, s[24:25]
	s_mov_b32 m0, s62
	s_nop 0
	global_load_lds_dwordx4 v[144:145], off
	s_waitcnt vmcnt(8)
	s_waitcnt lgkmcnt(0)
	s_setprio 1
	s_barrier
	v_mfma_f32_16x16x32_bf16 v[128:131], v[158:161], v[190:193], v[128:131]
	v_mfma_f32_16x16x32_bf16 v[116:119], v[166:169], v[190:193], v[116:119]
	v_mfma_f32_16x16x32_bf16 v[112:115], v[158:161], v[198:201], v[112:115]
	v_mfma_f32_16x16x32_bf16 v[100:103], v[166:169], v[198:201], v[100:103]
	v_mfma_f32_16x16x32_bf16 v[96:99], v[158:161], v[206:209], v[96:99]
	v_mfma_f32_16x16x32_bf16 v[84:87], v[166:169], v[206:209], v[84:87]
	v_mfma_f32_16x16x32_bf16 v[80:83], v[158:161], v[214:217], v[80:83]
	v_mfma_f32_16x16x32_bf16 v[64:67], v[166:169], v[214:217], v[64:67]
	v_mfma_f32_16x16x32_bf16 v[128:131], v[162:165], v[194:197], v[128:131]
	v_mfma_f32_16x16x32_bf16 v[116:119], v[170:173], v[194:197], v[116:119]
	v_mfma_f32_16x16x32_bf16 v[112:115], v[162:165], v[202:205], v[112:115]
	v_mfma_f32_16x16x32_bf16 v[100:103], v[170:173], v[202:205], v[100:103]
	v_mfma_f32_16x16x32_bf16 v[96:99], v[162:165], v[210:213], v[96:99]
	v_mfma_f32_16x16x32_bf16 v[84:87], v[170:173], v[210:213], v[84:87]
	v_mfma_f32_16x16x32_bf16 v[80:83], v[162:165], v[218:221], v[80:83]
	v_mfma_f32_16x16x32_bf16 v[64:67], v[170:173], v[218:221], v[64:67]
	v_mfma_f32_16x16x32_bf16 v[124:127], v[174:177], v[190:193], v[124:127]
	v_mfma_f32_16x16x32_bf16 v[120:123], v[182:185], v[190:193], v[120:123]
	v_mfma_f32_16x16x32_bf16 v[108:111], v[174:177], v[198:201], v[108:111]
	v_mfma_f32_16x16x32_bf16 v[104:107], v[182:185], v[198:201], v[104:107]
	v_mfma_f32_16x16x32_bf16 v[92:95], v[174:177], v[206:209], v[92:95]
	v_mfma_f32_16x16x32_bf16 v[88:91], v[182:185], v[206:209], v[88:91]
	v_mfma_f32_16x16x32_bf16 v[72:75], v[174:177], v[214:217], v[72:75]
	v_mfma_f32_16x16x32_bf16 v[68:71], v[182:185], v[214:217], v[68:71]
	v_mfma_f32_16x16x32_bf16 v[124:127], v[178:181], v[194:197], v[124:127]
	v_mfma_f32_16x16x32_bf16 v[120:123], v[186:189], v[194:197], v[120:123]
	v_mfma_f32_16x16x32_bf16 v[108:111], v[178:181], v[202:205], v[108:111]
	v_mfma_f32_16x16x32_bf16 v[104:107], v[186:189], v[202:205], v[104:107]
	v_mfma_f32_16x16x32_bf16 v[92:95], v[178:181], v[210:213], v[92:95]
	v_mfma_f32_16x16x32_bf16 v[88:91], v[186:189], v[210:213], v[88:91]
	v_mfma_f32_16x16x32_bf16 v[72:75], v[178:181], v[218:221], v[72:75]
	v_mfma_f32_16x16x32_bf16 v[68:71], v[186:189], v[218:221], v[68:71]
	s_barrier
	s_setprio 0
	s_add_i32 s12, s52, s17
	v_lshl_add_u64 v[144:145], s[46:47], 0, v[134:135]
	s_mov_b32 m0, s12
	ds_read_b128 v[190:193], v155 offset:16384
	ds_read_b128 v[194:197], v155 offset:17408
	ds_read_b128 v[198:201], v155 offset:18432
	ds_read_b128 v[202:205], v155 offset:19456
	ds_read_b128 v[206:209], v155 offset:20480
	ds_read_b128 v[210:213], v155 offset:21504
	ds_read_b128 v[214:217], v155 offset:22528
	ds_read_b128 v[218:221], v155 offset:23552
	global_load_lds_dwordx4 v[144:145], off
	s_add_i32 m0, s12, 0x2000
	s_add_u32 s12, s46, 0x4000
	v_lshl_add_u64 v[144:145], s[46:47], 0, v[138:139]
	s_addc_u32 s13, s47, 0
	s_add_i32 s14, s53, s17
	global_load_lds_dwordx4 v[144:145], off
	v_lshl_add_u64 v[144:145], s[12:13], 0, v[134:135]
	s_mov_b32 m0, s14
	v_lshl_add_u64 v[222:223], s[22:23], 0, v[136:137]
	global_load_lds_dwordx4 v[144:145], off
	v_lshl_add_u64 v[144:145], s[12:13], 0, v[138:139]
	s_add_i32 m0, s14, 0x2000
	s_nop 0
	global_load_lds_dwordx4 v[144:145], off
	v_lshl_add_u64 v[144:145], s[22:23], 0, v[132:133]
	s_mov_b32 m0, s18
	s_nop 0
	global_load_lds_dwordx4 v[144:145], off
	s_mov_b32 m0, s19
	s_nop 0
	global_load_lds_dwordx4 v[222:223], off
	s_waitcnt vmcnt(8)
	s_waitcnt lgkmcnt(0)
	s_setprio 1
	s_barrier
	v_mfma_f32_16x16x32_bf16 v[76:79], v[158:161], v[190:193], v[76:79]
	v_mfma_f32_16x16x32_bf16 v[52:55], v[166:169], v[190:193], v[52:55]
	v_mfma_f32_16x16x32_bf16 v[48:51], v[158:161], v[198:201], v[48:51]
	v_mfma_f32_16x16x32_bf16 v[36:39], v[166:169], v[198:201], v[36:39]
	v_mfma_f32_16x16x32_bf16 v[32:35], v[158:161], v[206:209], v[32:35]
	v_mfma_f32_16x16x32_bf16 v[20:23], v[166:169], v[206:209], v[20:23]
	v_mfma_f32_16x16x32_bf16 v[16:19], v[158:161], v[214:217], v[16:19]
	v_mfma_f32_16x16x32_bf16 v[4:7], v[166:169], v[214:217], v[4:7]
	v_mfma_f32_16x16x32_bf16 v[76:79], v[162:165], v[194:197], v[76:79]
	v_mfma_f32_16x16x32_bf16 v[52:55], v[170:173], v[194:197], v[52:55]
	v_mfma_f32_16x16x32_bf16 v[48:51], v[162:165], v[202:205], v[48:51]
	v_mfma_f32_16x16x32_bf16 v[36:39], v[170:173], v[202:205], v[36:39]
	v_mfma_f32_16x16x32_bf16 v[32:35], v[162:165], v[210:213], v[32:35]
	v_mfma_f32_16x16x32_bf16 v[20:23], v[170:173], v[210:213], v[20:23]
	v_mfma_f32_16x16x32_bf16 v[16:19], v[162:165], v[218:221], v[16:19]
	v_mfma_f32_16x16x32_bf16 v[4:7], v[170:173], v[218:221], v[4:7]
	v_mfma_f32_16x16x32_bf16 v[60:63], v[174:177], v[190:193], v[60:63]
	v_mfma_f32_16x16x32_bf16 v[56:59], v[182:185], v[190:193], v[56:59]
	v_mfma_f32_16x16x32_bf16 v[44:47], v[174:177], v[198:201], v[44:47]
	v_mfma_f32_16x16x32_bf16 v[40:43], v[182:185], v[198:201], v[40:43]
	v_mfma_f32_16x16x32_bf16 v[28:31], v[174:177], v[206:209], v[28:31]
	v_mfma_f32_16x16x32_bf16 v[24:27], v[182:185], v[206:209], v[24:27]
	v_mfma_f32_16x16x32_bf16 v[12:15], v[174:177], v[214:217], v[12:15]
	v_mfma_f32_16x16x32_bf16 v[8:11], v[182:185], v[214:217], v[8:11]
	v_mfma_f32_16x16x32_bf16 v[60:63], v[178:181], v[194:197], v[60:63]
	v_mfma_f32_16x16x32_bf16 v[56:59], v[186:189], v[194:197], v[56:59]
	v_mfma_f32_16x16x32_bf16 v[44:47], v[178:181], v[202:205], v[44:47]
	v_mfma_f32_16x16x32_bf16 v[40:43], v[186:189], v[202:205], v[40:43]
	v_mfma_f32_16x16x32_bf16 v[28:31], v[178:181], v[210:213], v[28:31]
	v_mfma_f32_16x16x32_bf16 v[24:27], v[186:189], v[210:213], v[24:27]
	v_mfma_f32_16x16x32_bf16 v[12:15], v[178:181], v[218:221], v[12:15]
	v_mfma_f32_16x16x32_bf16 v[8:11], v[186:189], v[218:221], v[8:11]
	s_barrier
	s_setprio 0
	s_add_i32 s14, 0, 0x18000
	v_add_u32_e32 v1, s14, v151
	s_add_i32 s64, 0, 0x1c000
	ds_read_b128 v[158:161], v1
	ds_read_b128 v[162:165], v1 offset:1024
	ds_read_b128 v[166:169], v1 offset:2048
	ds_read_b128 v[170:173], v1 offset:3072
	v_add_u32_e32 v1, s64, v151
	ds_read_b128 v[174:177], v1
	ds_read_b128 v[178:181], v1 offset:1024
	ds_read_b128 v[182:185], v1 offset:2048
	ds_read_b128 v[186:189], v1 offset:3072
	s_add_u32 s12, s22, 0x2b0000
	s_addc_u32 s13, s23, 0
	s_mov_b32 m0, s20
	v_lshl_add_u64 v[224:225], s[12:13], 0, v[132:133]
	ds_read_b128 v[190:193], v155 offset:32768
	ds_read_b128 v[194:197], v155 offset:33792
	ds_read_b128 v[198:201], v155 offset:34816
	ds_read_b128 v[202:205], v155 offset:35840
	ds_read_b128 v[206:209], v155 offset:36864
	ds_read_b128 v[210:213], v155 offset:37888
	ds_read_b128 v[214:217], v155 offset:38912
	ds_read_b128 v[218:221], v155 offset:39936
	global_load_lds_dwordx4 v[224:225], off
	v_lshl_add_u64 v[224:225], s[12:13], 0, v[136:137]
	s_mov_b32 m0, s21
	s_nop 0
	global_load_lds_dwordx4 v[224:225], off
	s_waitcnt vmcnt(8)
	s_waitcnt lgkmcnt(0)
	s_setprio 1
	s_barrier
	v_mfma_f32_16x16x32_bf16 v[128:131], v[158:161], v[190:193], v[128:131]
	v_mfma_f32_16x16x32_bf16 v[116:119], v[166:169], v[190:193], v[116:119]
	v_mfma_f32_16x16x32_bf16 v[112:115], v[158:161], v[198:201], v[112:115]
	v_mfma_f32_16x16x32_bf16 v[100:103], v[166:169], v[198:201], v[100:103]
	v_mfma_f32_16x16x32_bf16 v[96:99], v[158:161], v[206:209], v[96:99]
	v_mfma_f32_16x16x32_bf16 v[84:87], v[166:169], v[206:209], v[84:87]
	v_mfma_f32_16x16x32_bf16 v[80:83], v[158:161], v[214:217], v[80:83]
	v_mfma_f32_16x16x32_bf16 v[64:67], v[166:169], v[214:217], v[64:67]
	v_mfma_f32_16x16x32_bf16 v[128:131], v[162:165], v[194:197], v[128:131]
	v_mfma_f32_16x16x32_bf16 v[116:119], v[170:173], v[194:197], v[116:119]
	v_mfma_f32_16x16x32_bf16 v[112:115], v[162:165], v[202:205], v[112:115]
	v_mfma_f32_16x16x32_bf16 v[100:103], v[170:173], v[202:205], v[100:103]
	v_mfma_f32_16x16x32_bf16 v[96:99], v[162:165], v[210:213], v[96:99]
	v_mfma_f32_16x16x32_bf16 v[84:87], v[170:173], v[210:213], v[84:87]
	v_mfma_f32_16x16x32_bf16 v[80:83], v[162:165], v[218:221], v[80:83]
	v_mfma_f32_16x16x32_bf16 v[64:67], v[170:173], v[218:221], v[64:67]
	v_mfma_f32_16x16x32_bf16 v[124:127], v[174:177], v[190:193], v[124:127]
	v_mfma_f32_16x16x32_bf16 v[120:123], v[182:185], v[190:193], v[120:123]
	v_mfma_f32_16x16x32_bf16 v[108:111], v[174:177], v[198:201], v[108:111]
	v_mfma_f32_16x16x32_bf16 v[104:107], v[182:185], v[198:201], v[104:107]
	v_mfma_f32_16x16x32_bf16 v[92:95], v[174:177], v[206:209], v[92:95]
	v_mfma_f32_16x16x32_bf16 v[88:91], v[182:185], v[206:209], v[88:91]
	v_mfma_f32_16x16x32_bf16 v[72:75], v[174:177], v[214:217], v[72:75]
	v_mfma_f32_16x16x32_bf16 v[68:71], v[182:185], v[214:217], v[68:71]
	v_mfma_f32_16x16x32_bf16 v[124:127], v[178:181], v[194:197], v[124:127]
	v_mfma_f32_16x16x32_bf16 v[120:123], v[186:189], v[194:197], v[120:123]
	v_mfma_f32_16x16x32_bf16 v[108:111], v[178:181], v[202:205], v[108:111]
	v_mfma_f32_16x16x32_bf16 v[104:107], v[186:189], v[202:205], v[104:107]
	v_mfma_f32_16x16x32_bf16 v[92:95], v[178:181], v[210:213], v[92:95]
	v_mfma_f32_16x16x32_bf16 v[88:91], v[186:189], v[210:213], v[88:91]
	v_mfma_f32_16x16x32_bf16 v[72:75], v[178:181], v[218:221], v[72:75]
	v_mfma_f32_16x16x32_bf16 v[68:71], v[186:189], v[218:221], v[68:71]
	s_barrier
	s_setprio 0
	s_add_u32 s12, s46, 0x8000
	s_addc_u32 s13, s47, 0
	s_add_i32 s14, s14, s17
	v_lshl_add_u64 v[224:225], s[12:13], 0, v[134:135]
	s_mov_b32 m0, s14
	ds_read_b128 v[190:193], v155 offset:49152
	ds_read_b128 v[194:197], v155 offset:50176
	ds_read_b128 v[198:201], v155 offset:51200
	ds_read_b128 v[202:205], v155 offset:52224
	ds_read_b128 v[206:209], v155 offset:53248
	ds_read_b128 v[210:213], v155 offset:54272
	ds_read_b128 v[214:217], v155 offset:55296
	ds_read_b128 v[218:221], v155 offset:56320
	global_load_lds_dwordx4 v[224:225], off
	s_add_i32 m0, s14, 0x2000
	v_lshl_add_u64 v[224:225], s[12:13], 0, v[138:139]
	s_add_u32 s12, s46, 0xc000
	s_addc_u32 s13, s47, 0
	s_add_i32 s14, s64, s17
	global_load_lds_dwordx4 v[224:225], off
	v_lshl_add_u64 v[224:225], s[12:13], 0, v[134:135]
	s_mov_b32 m0, s14
	v_lshl_add_u64 v[144:145], v[144:145], 0, s[34:35]
	global_load_lds_dwordx4 v[224:225], off
	v_lshl_add_u64 v[224:225], s[12:13], 0, v[138:139]
	s_add_i32 m0, s14, 0x2000
	s_nop 0
	global_load_lds_dwordx4 v[224:225], off
	s_mov_b32 m0, s48
	s_nop 0
	global_load_lds_dwordx4 v[144:145], off
	v_lshl_add_u64 v[144:145], v[222:223], 0, s[34:35]
	s_mov_b32 m0, s49
	s_nop 0
	global_load_lds_dwordx4 v[144:145], off
	s_waitcnt vmcnt(8)
	s_waitcnt lgkmcnt(0)
	s_setprio 1
	s_barrier
	v_mfma_f32_16x16x32_bf16 v[76:79], v[158:161], v[190:193], v[76:79]
	v_mfma_f32_16x16x32_bf16 v[52:55], v[166:169], v[190:193], v[52:55]
	v_mfma_f32_16x16x32_bf16 v[48:51], v[158:161], v[198:201], v[48:51]
	v_mfma_f32_16x16x32_bf16 v[36:39], v[166:169], v[198:201], v[36:39]
	v_mfma_f32_16x16x32_bf16 v[32:35], v[158:161], v[206:209], v[32:35]
	v_mfma_f32_16x16x32_bf16 v[20:23], v[166:169], v[206:209], v[20:23]
	v_mfma_f32_16x16x32_bf16 v[16:19], v[158:161], v[214:217], v[16:19]
	v_mfma_f32_16x16x32_bf16 v[4:7], v[166:169], v[214:217], v[4:7]
	v_mfma_f32_16x16x32_bf16 v[76:79], v[162:165], v[194:197], v[76:79]
	v_mfma_f32_16x16x32_bf16 v[52:55], v[170:173], v[194:197], v[52:55]
	v_mfma_f32_16x16x32_bf16 v[48:51], v[162:165], v[202:205], v[48:51]
	v_mfma_f32_16x16x32_bf16 v[36:39], v[170:173], v[202:205], v[36:39]
	v_mfma_f32_16x16x32_bf16 v[32:35], v[162:165], v[210:213], v[32:35]
	v_mfma_f32_16x16x32_bf16 v[20:23], v[170:173], v[210:213], v[20:23]
	v_mfma_f32_16x16x32_bf16 v[16:19], v[162:165], v[218:221], v[16:19]
	v_mfma_f32_16x16x32_bf16 v[4:7], v[170:173], v[218:221], v[4:7]
	v_mfma_f32_16x16x32_bf16 v[60:63], v[174:177], v[190:193], v[60:63]
	v_mfma_f32_16x16x32_bf16 v[56:59], v[182:185], v[190:193], v[56:59]
	v_mfma_f32_16x16x32_bf16 v[44:47], v[174:177], v[198:201], v[44:47]
	v_mfma_f32_16x16x32_bf16 v[40:43], v[182:185], v[198:201], v[40:43]
	v_mfma_f32_16x16x32_bf16 v[28:31], v[174:177], v[206:209], v[28:31]
	v_mfma_f32_16x16x32_bf16 v[24:27], v[182:185], v[206:209], v[24:27]
	v_mfma_f32_16x16x32_bf16 v[12:15], v[174:177], v[214:217], v[12:15]
	v_mfma_f32_16x16x32_bf16 v[8:11], v[182:185], v[214:217], v[8:11]
	v_mfma_f32_16x16x32_bf16 v[60:63], v[178:181], v[194:197], v[60:63]
	v_mfma_f32_16x16x32_bf16 v[56:59], v[186:189], v[194:197], v[56:59]
	v_mfma_f32_16x16x32_bf16 v[44:47], v[178:181], v[202:205], v[44:47]
	v_mfma_f32_16x16x32_bf16 v[40:43], v[186:189], v[202:205], v[40:43]
	v_mfma_f32_16x16x32_bf16 v[28:31], v[178:181], v[210:213], v[28:31]
	v_mfma_f32_16x16x32_bf16 v[24:27], v[186:189], v[210:213], v[24:27]
	v_mfma_f32_16x16x32_bf16 v[12:15], v[178:181], v[218:221], v[12:15]
	v_mfma_f32_16x16x32_bf16 v[8:11], v[186:189], v[218:221], v[8:11]
	s_barrier
	s_setprio 0
	s_add_i32 s0, s0, 2
	s_add_u32 s1, s1, 0x10000
	s_addc_u32 s59, s59, 0
	s_add_u32 s60, s60, 0x100
	s_addc_u32 s61, s61, 0
	s_add_u32 s44, s44, 0xffffff00
	s_addc_u32 s45, s45, -1
	v_lshl_add_u64 v[2:3], v[2:3], 0, s[38:39]
	s_cmpk_gt_u32 s0, 0xa9
	v_lshl_add_u64 v[148:149], v[148:149], 0, s[38:39]
	s_cbranch_scc0 .LBB0_1734
	s_and_b64 vcc, exec, s[36:37]
	s_cbranch_vccz .LBB0_1737
	s_barrier

	.amdhsa_kernel _Z6mk_fwd4Args
		.amdhsa_group_segment_fixed_size 0
		.amdhsa_private_segment_fixed_size 0
		.amdhsa_kernarg_size 1000
		.amdhsa_user_sgpr_count 2
		.amdhsa_user_sgpr_dispatch_ptr 0
		.amdhsa_user_sgpr_queue_ptr 0
		.amdhsa_user_sgpr_kernarg_segment_ptr 1
		.amdhsa_user_sgpr_dispatch_id 0
		.amdhsa_user_sgpr_kernarg_preload_length 0
		.amdhsa_user_sgpr_kernarg_preload_offset 0
		.amdhsa_user_sgpr_private_segment_size 0
		.amdhsa_uses_dynamic_stack 0
		.amdhsa_enable_private_segment 0
		.amdhsa_system_sgpr_workgroup_id_x 1
		.amdhsa_system_sgpr_workgroup_id_y 0
		.amdhsa_system_sgpr_workgroup_id_z 0
		.amdhsa_system_sgpr_workgroup_info 0
		.amdhsa_system_vgpr_workitem_id 0
		.amdhsa_next_free_vgpr 256
		.amdhsa_next_free_sgpr 98
		.amdhsa_accum_offset 256
		.amdhsa_reserve_vcc 1
		.amdhsa_float_round_mode_32 0
		.amdhsa_float_round_mode_16_64 0
		.amdhsa_float_denorm_mode_32 3
		.amdhsa_float_denorm_mode_16_64 3
		.amdhsa_dx10_clamp 1
		.amdhsa_ieee_mode 1
		.amdhsa_fp16_overflow 0
		.amdhsa_tg_split 0
		.amdhsa_exception_fp_ieee_invalid_op 0
		.amdhsa_exception_fp_denorm_src 0
		.amdhsa_exception_fp_ieee_div_zero 0
		.amdhsa_exception_fp_ieee_overflow 0
		.amdhsa_exception_fp_ieee_underflow 0
		.amdhsa_exception_fp_ieee_inexact 0
		.amdhsa_exception_int_div_zero 0
	.end_amdhsa_kernel

amdhsa.kernels:
  - .agpr_count:     0
    .args:
      - .offset:         0
        .size:           744
        .value_kind:     by_value
      - .offset:         744
        .size:           4
        .value_kind:     hidden_block_count_x
      - .offset:         748
        .size:           4
        .value_kind:     hidden_block_count_y
      - .offset:         752
        .size:           4
        .value_kind:     hidden_block_count_z
      - .offset:         756
        .size:           2
        .value_kind:     hidden_group_size_x
      - .offset:         758
        .size:           2
        .value_kind:     hidden_group_size_y
      - .offset:         760
        .size:           2
        .value_kind:     hidden_group_size_z
      - .offset:         762
        .size:           2
        .value_kind:     hidden_remainder_x
      - .offset:         764
        .size:           2
        .value_kind:     hidden_remainder_y
      - .offset:         766
        .size:           2
        .value_kind:     hidden_remainder_z
      - .offset:         784
        .size:           8
        .value_kind:     hidden_global_offset_x
      - .offset:         792
        .size:           8
        .value_kind:     hidden_global_offset_y
      - .offset:         800
        .size:           8
        .value_kind:     hidden_global_offset_z
      - .offset:         808
        .size:           2
        .value_kind:     hidden_grid_dims
      - .offset:         864
        .size:           4
        .value_kind:     hidden_dynamic_lds_size
    .group_segment_fixed_size: 0
    .kernarg_segment_align: 8
    .kernarg_segment_size: 1000
    .language:       OpenCL C
    .language_version:
      - 2
      - 0
    .max_flat_workgroup_size: 512
    .name:           _Z6mk_fwd4Args
    .private_segment_fixed_size: 0
    .sgpr_count:     104
    .sgpr_spill_count: 63
    .symbol:         _Z6mk_fwd4Args.kd
    .uniform_work_group_size: 1
    .uses_dynamic_stack: false
    .vgpr_count:     256
    .vgpr_spill_count: 0
    .wavefront_size: 64
